# code placement: phases E1/E2 and G shifted by 12 bytes (4 mod 8), F kept at baseline phase; otherwise same as previous (seam rebalance, attention v2 K-stride 224, GLU pipelining)
# baseline (speedup 1.0000x reference)
; #define GSYNC() xcd_barrier(xbar)
; __global__ void __launch_bounds__(512, 2) fwd_kernel(KArgs a) {
;     ...
;             }
;             }
;             GSYNC();
.Lmy_pad_LBB01065:
	s_branch .Lmy_shLBB01065
	s_nop 0
	s_nop 0

; __device__ __forceinline__ unsigned cvt_pk_bf16(float lo, float hi) { unsigned r; asm volatile("v_cvt_pk_bf16_f32 %0, %1, %2" : "=v"(r) : "v"(lo), "v"(hi)); return r; }
; __device__ __forceinline__ float gelu_tanh(float x) { const float u = 0.7978845608028654f * (x + 0.044715f * x * x * x); return x * sigm(2.f * u); }
; #define UNPK8(VV_, XX_) float XX_[8] = {bflo((VV_).x), bfhi((VV_).x), bflo((VV_).y), bfhi((VV_).y), bflo((VV_).z), bfhi((VV_).z), bflo((VV_).w), bfhi((VV_).w)}
; __device__ __forceinline__ void glu_task(int t, int l, const float* s5d, const bf16_t* P, const bf16_t* YB, const bf16_t* WGLU, bf16_t* Z1, int fr, int fq) {
;     const int cb0 = (t & 3) * 4; const size_t row0 = (size_t)((t >> 2) * 32 + fr);
;     bf16x8 bfr[2][8];
; #pragma unroll
;     for (int tb = 0; tb < 2; ++tb) { const size_t row = row0 + tb * 16;
; #pragma unroll
;         for (int ks = 0; ks < 8; ++ks) { const int k0 = ks * 32 + fq * 8; const u32x4 yw = ld8(YB + row * 256 + k0), uw = ld8(P + row * INP + OFF_S5 + k0);
;             const f32x4 d0 = *(const f32x4*)(s5d + l * 256 + k0), d1 = *(const f32x4*)(s5d + l * 256 + k0 + 4); UNPK8(yw, y); UNPK8(uw, u); u32x4 o;
;             o.x = cvt_pk_bf16(gelu_tanh(y[0] + d0[0] * u[0]), gelu_tanh(y[1] + d0[1] * u[1])); o.y = cvt_pk_bf16(gelu_tanh(y[2] + d0[2] * u[2]), gelu_tanh(y[3] + d0[3] * u[3]));
;             o.z = cvt_pk_bf16(gelu_tanh(y[4] + d1[0] * u[4]), gelu_tanh(y[5] + d1[1] * u[5])); o.w = cvt_pk_bf16(gelu_tanh(y[6] + d1[2] * u[6]), gelu_tanh(y[7] + d1[3] * u[7]));
;             bfr[tb][ks] = asfrag(o); } }
.LBB0_1282:
	s_lshl_b32 s5, s20, 3
	s_andn2_b32 s5, s5, 31
	v_or_b32_e32 v2, s5, v174
	v_ashrrev_i32_e32 v3, 31, v2
	v_lshlrev_b64 v[114:115], 9, v[2:3]
	v_lshl_add_u64 v[70:71], s[38:39], 0, v[114:115]
	v_mov_b64_e32 v[4:5], s[36:37]
	v_mad_i64_i32 v[72:73], s[6:7], v2, s84, v[4:5]
	v_lshl_add_u64 v[34:35], v[70:71], 0, v[0:1]
	v_lshl_add_u64 v[36:37], v[72:73], 0, v[0:1]
	ds_read_b128 v[14:17], v246 offset:16
	ds_read_b128 v[18:21], v246
	v_or_b32_e32 v138, 0x2000, v114
	v_mov_b32_e32 v139, v115
	v_lshl_add_u64 v[74:75], s[38:39], 0, v[138:139]
	s_mov_b64 s[6:7], 0x22000
	v_lshl_add_u64 v[76:77], v[72:73], 0, s[6:7]
	v_lshl_add_u64 v[66:67], v[74:75], 0, v[0:1]
	v_lshl_add_u64 v[68:69], v[76:77], 0, v[0:1]
	s_lshl_b32 s1, s20, 6
	s_and_b32 s5, s1, 0xc0
	v_or_b32_e32 v178, s5, v175
	v_lshlrev_b32_e32 v158, 1, v178
	v_mov_b32_e32 v159, v1
	v_lshl_add_u64 v[70:71], v[70:71], 0, v[158:159]
	v_lshl_add_u64 v[72:73], v[72:73], 0, v[158:159]
	v_lshlrev_b32_e32 v178, 2, v178
	s_add_i32 s1, s20, s60
	global_load_dwordx4 v[98:101], v[34:35], off
	global_load_dwordx4 v[102:105], v[36:37], off offset:320
	global_load_dwordx4 v[106:109], v[34:35], off offset:64
	global_load_dwordx4 v[110:113], v[36:37], off offset:384
	global_load_dwordx4 v[118:121], v[34:35], off offset:128
	global_load_dwordx4 v[122:125], v[36:37], off offset:448
	global_load_dwordx4 v[126:129], v[34:35], off offset:192
	global_load_dwordx4 v[130:133], v[36:37], off offset:512
	global_load_dwordx4 v[140:143], v[34:35], off offset:256
	global_load_dwordx4 v[144:147], v[36:37], off offset:576
	global_load_dwordx4 v[160:163], v[34:35], off offset:320
	global_load_dwordx4 v[164:167], v[36:37], off offset:640
	global_load_dwordx4 v[180:183], v[34:35], off offset:384
	global_load_dwordx4 v[184:187], v[36:37], off offset:704
	global_load_dwordx4 v[214:217], v[34:35], off offset:448
	global_load_dwordx4 v[218:221], v[36:37], off offset:768
	global_load_dwordx4 v[222:225], v[66:67], off
	global_load_dwordx4 v[226:229], v[68:69], off offset:320
	global_load_dwordx4 v[230:233], v[66:67], off offset:64
	global_load_dwordx4 v[234:237], v[68:69], off offset:384
	global_load_dwordx4 v[238:241], v[66:67], off offset:128
	global_load_dwordx4 v[242:245], v[68:69], off offset:448
	global_load_dwordx4 v[168:171], v[66:67], off offset:192
	global_load_dwordx4 v[188:191], v[68:69], off offset:512
	s_waitcnt vmcnt(22) lgkmcnt(0)
	v_mov_b32_e32 v2, v98
	v_mov_b32_e32 v3, v99
	v_mov_b32_e32 v4, v100
	v_mov_b32_e32 v5, v101
	v_mov_b32_e32 v6, v102
	v_mov_b32_e32 v7, v103
	v_mov_b32_e32 v8, v104
	v_mov_b32_e32 v9, v105
	global_load_dwordx4 v[98:101], v[66:67], off offset:256
	global_load_dwordx4 v[102:105], v[68:69], off offset:576
	v_lshlrev_b32_e32 v26, 16, v6
	v_lshlrev_b32_e32 v22, 16, v2
	v_and_b32_e32 v2, 0xffff0000, v2
	v_and_b32_e32 v6, 0xffff0000, v6
	v_fmac_f32_e32 v2, v19, v6
	v_mul_f32_e32 v6, 0x3d372713, v2
	v_mul_f32_e32 v6, v2, v6
	v_fma_f32 v6, v2, v6, v2
	v_mul_f32_e32 v6, 0x3f4c422a, v6
	v_add_f32_e32 v6, v6, v6
	v_mul_f32_e32 v6, 0xbfb8aa3b, v6
	v_exp_f32_e32 v6, v6
	v_lshlrev_b32_e32 v23, 16, v3
	v_and_b32_e32 v3, 0xffff0000, v3
	v_lshlrev_b32_e32 v27, 16, v7
	v_add_f32_e32 v6, 1.0, v6
	v_rcp_f32_e32 v6, v6
	v_and_b32_e32 v7, 0xffff0000, v7
	v_fmac_f32_e32 v23, v20, v27
	v_fmac_f32_e32 v3, v21, v7
	v_fmac_f32_e32 v22, v18, v26
	v_mul_f32_e32 v2, v2, v6
	v_mul_f32_e32 v6, 0x3d372713, v23
	v_mul_f32_e32 v7, 0x3d372713, v3
	v_mul_f32_e32 v18, 0x3d372713, v22
	v_mul_f32_e32 v6, v23, v6
	v_mul_f32_e32 v7, v3, v7
	v_mul_f32_e32 v18, v22, v18
	v_fma_f32 v6, v23, v6, v23
	v_fma_f32 v7, v3, v7, v3
	v_fma_f32 v18, v22, v18, v22
	v_mul_f32_e32 v6, 0x3f4c422a, v6
	v_mul_f32_e32 v7, 0x3f4c422a, v7
	v_mul_f32_e32 v18, 0x3f4c422a, v18
	v_add_f32_e32 v6, v6, v6
	v_add_f32_e32 v7, v7, v7
	v_add_f32_e32 v18, v18, v18
	v_mul_f32_e32 v6, 0xbfb8aa3b, v6
	v_mul_f32_e32 v7, 0xbfb8aa3b, v7
	v_mul_f32_e32 v18, 0xbfb8aa3b, v18
	v_exp_f32_e32 v6, v6
	v_exp_f32_e32 v7, v7
	v_exp_f32_e32 v18, v18
	v_lshlrev_b32_e32 v24, 16, v4
	v_add_f32_e32 v6, 1.0, v6
	v_add_f32_e32 v7, 1.0, v7
	v_add_f32_e32 v18, 1.0, v18
	v_rcp_f32_e32 v6, v6
	v_rcp_f32_e32 v7, v7
	v_rcp_f32_e32 v18, v18
	v_and_b32_e32 v4, 0xffff0000, v4
	v_lshlrev_b32_e32 v28, 16, v8
	v_and_b32_e32 v8, 0xffff0000, v8
	v_mul_f32_e32 v6, v23, v6
	v_mul_f32_e32 v3, v3, v7
	v_fmac_f32_e32 v24, v14, v28
	v_fmac_f32_e32 v4, v15, v8
	v_mul_f32_e32 v18, v22, v18
	v_cvt_pk_bf16_f32 v2, v18, v2
	v_cvt_pk_bf16_f32 v3, v6, v3
	v_mul_f32_e32 v6, 0x3d372713, v24
	v_mul_f32_e32 v7, 0x3d372713, v4
	v_mul_f32_e32 v6, v24, v6
	v_mul_f32_e32 v7, v4, v7
	v_fma_f32 v6, v24, v6, v24
	v_fma_f32 v7, v4, v7, v4
	v_mul_f32_e32 v6, 0x3f4c422a, v6
	v_mul_f32_e32 v7, 0x3f4c422a, v7
	v_add_f32_e32 v6, v6, v6
	v_add_f32_e32 v7, v7, v7
	v_mul_f32_e32 v6, 0xbfb8aa3b, v6
	v_mul_f32_e32 v7, 0xbfb8aa3b, v7
	v_exp_f32_e32 v6, v6
	v_exp_f32_e32 v7, v7
	v_lshlrev_b32_e32 v25, 16, v5
	v_and_b32_e32 v5, 0xffff0000, v5
	v_add_f32_e32 v6, 1.0, v6
	v_add_f32_e32 v7, 1.0, v7
	v_rcp_f32_e32 v6, v6
	v_rcp_f32_e32 v7, v7
	v_lshlrev_b32_e32 v29, 16, v9
	v_and_b32_e32 v9, 0xffff0000, v9
	v_mul_f32_e32 v6, v24, v6
	v_mul_f32_e32 v4, v4, v7
	v_fmac_f32_e32 v25, v16, v29
	v_fmac_f32_e32 v5, v17, v9
	v_cvt_pk_bf16_f32 v4, v6, v4
	v_mul_f32_e32 v6, 0x3d372713, v25
	v_mul_f32_e32 v7, 0x3d372713, v5
	v_mul_f32_e32 v6, v25, v6
	v_mul_f32_e32 v7, v5, v7
	v_fma_f32 v6, v25, v6, v25
	v_fma_f32 v7, v5, v7, v5
	v_mul_f32_e32 v6, 0x3f4c422a, v6
	v_mul_f32_e32 v7, 0x3f4c422a, v7
	v_add_f32_e32 v6, v6, v6
	v_add_f32_e32 v7, v7, v7
	v_mul_f32_e32 v6, 0xbfb8aa3b, v6
	v_mul_f32_e32 v7, 0xbfb8aa3b, v7
	v_exp_f32_e32 v6, v6
	v_exp_f32_e32 v7, v7
	v_add_f32_e32 v6, 1.0, v6
	v_add_f32_e32 v7, 1.0, v7
	v_rcp_f32_e32 v6, v6
	v_rcp_f32_e32 v7, v7
	v_mul_f32_e32 v6, v25, v6
	v_mul_f32_e32 v5, v5, v7
	v_cvt_pk_bf16_f32 v5, v6, v5
	ds_read_b128 v[18:21], v246 offset:144
	ds_read_b128 v[22:25], v246 offset:128
	s_waitcnt vmcnt(22) lgkmcnt(0)
; __device__ __forceinline__ unsigned cvt_pk_bf16(float lo, float hi) { unsigned r; asm volatile("v_cvt_pk_bf16_f32 %0, %1, %2" : "=v"(r) : "v"(lo), "v"(hi)); return r; }
; __device__ __forceinline__ float gelu_tanh(float x) { const float u = 0.7978845608028654f * (x + 0.044715f * x * x * x); return x * sigm(2.f * u); }
; #define UNPK8(VV_, XX_) float XX_[8] = {bflo((VV_).x), bfhi((VV_).x), bflo((VV_).y), bfhi((VV_).y), bflo((VV_).z), bfhi((VV_).z), bflo((VV_).w), bfhi((VV_).w)}
; __device__ __forceinline__ void glu_task(int t, int l, const float* s5d, const bf16_t* P, const bf16_t* YB, const bf16_t* WGLU, bf16_t* Z1, int fr, int fq) {
;     ...
;     for (int tb = 0; tb < 2; ++tb) { const size_t row = row0 + tb * 16;
; #pragma unroll
;         for (int ks = 0; ks < 8; ++ks) { const int k0 = ks * 32 + fq * 8; const u32x4 yw = ld8(YB + row * 256 + k0), uw = ld8(P + row * INP + OFF_S5 + k0);
;             const f32x4 d0 = *(const f32x4*)(s5d + l * 256 + k0), d1 = *(const f32x4*)(s5d + l * 256 + k0 + 4); UNPK8(yw, y); UNPK8(uw, u); u32x4 o;
;             o.x = cvt_pk_bf16(gelu_tanh(y[0] + d0[0] * u[0]), gelu_tanh(y[1] + d0[1] * u[1])); o.y = cvt_pk_bf16(gelu_tanh(y[2] + d0[2] * u[2]), gelu_tanh(y[3] + d0[3] * u[3]));
;             o.z = cvt_pk_bf16(gelu_tanh(y[4] + d1[0] * u[4]), gelu_tanh(y[5] + d1[1] * u[5])); o.w = cvt_pk_bf16(gelu_tanh(y[6] + d1[2] * u[6]), gelu_tanh(y[7] + d1[3] * u[7]));
;             bfr[tb][ks] = asfrag(o); } }
	v_mov_b32_e32 v6, v106
	v_mov_b32_e32 v7, v107
	v_mov_b32_e32 v8, v108
	v_mov_b32_e32 v9, v109
	v_mov_b32_e32 v14, v110
	v_mov_b32_e32 v15, v111
	v_mov_b32_e32 v16, v112
	v_mov_b32_e32 v17, v113
	global_load_dwordx4 v[106:109], v[66:67], off offset:320
	global_load_dwordx4 v[110:113], v[68:69], off offset:640
	v_lshlrev_b32_e32 v26, 16, v6
	v_and_b32_e32 v6, 0xffff0000, v6
	v_lshlrev_b32_e32 v30, 16, v14
	v_and_b32_e32 v14, 0xffff0000, v14
	v_fmac_f32_e32 v6, v23, v14
	v_mul_f32_e32 v14, 0x3d372713, v6
	v_mul_f32_e32 v14, v6, v14
	v_fma_f32 v14, v6, v14, v6
	v_mul_f32_e32 v14, 0x3f4c422a, v14
	v_add_f32_e32 v14, v14, v14
	v_mul_f32_e32 v14, 0xbfb8aa3b, v14
	v_exp_f32_e32 v14, v14
	v_lshlrev_b32_e32 v27, 16, v7
	v_and_b32_e32 v7, 0xffff0000, v7
	v_lshlrev_b32_e32 v31, 16, v15
	v_add_f32_e32 v14, 1.0, v14
	v_rcp_f32_e32 v14, v14
	v_and_b32_e32 v15, 0xffff0000, v15
	v_fmac_f32_e32 v27, v24, v31
	v_fmac_f32_e32 v7, v25, v15
	v_fmac_f32_e32 v26, v22, v30
	v_mul_f32_e32 v6, v6, v14
	v_mul_f32_e32 v14, 0x3d372713, v27
	v_mul_f32_e32 v15, 0x3d372713, v7
	v_mul_f32_e32 v22, 0x3d372713, v26
	v_mul_f32_e32 v14, v27, v14
	v_mul_f32_e32 v15, v7, v15
	v_mul_f32_e32 v22, v26, v22
	v_fma_f32 v14, v27, v14, v27
	v_fma_f32 v15, v7, v15, v7
	v_fma_f32 v22, v26, v22, v26
	v_mul_f32_e32 v14, 0x3f4c422a, v14
	v_mul_f32_e32 v15, 0x3f4c422a, v15
	v_mul_f32_e32 v22, 0x3f4c422a, v22
	v_add_f32_e32 v14, v14, v14
	v_add_f32_e32 v15, v15, v15
	v_add_f32_e32 v22, v22, v22
	v_mul_f32_e32 v14, 0xbfb8aa3b, v14
	v_mul_f32_e32 v15, 0xbfb8aa3b, v15
	v_mul_f32_e32 v22, 0xbfb8aa3b, v22
	v_exp_f32_e32 v14, v14
	v_exp_f32_e32 v15, v15
	v_exp_f32_e32 v22, v22
	v_lshlrev_b32_e32 v28, 16, v8
	v_add_f32_e32 v14, 1.0, v14
	v_add_f32_e32 v15, 1.0, v15
	v_add_f32_e32 v22, 1.0, v22
	v_rcp_f32_e32 v14, v14
	v_rcp_f32_e32 v15, v15
	v_rcp_f32_e32 v22, v22
	v_and_b32_e32 v8, 0xffff0000, v8
	v_lshlrev_b32_e32 v32, 16, v16
	v_and_b32_e32 v16, 0xffff0000, v16
	v_mul_f32_e32 v14, v27, v14
	v_mul_f32_e32 v7, v7, v15
	v_fmac_f32_e32 v28, v18, v32
	v_fmac_f32_e32 v8, v19, v16
	v_mul_f32_e32 v22, v26, v22
	v_cvt_pk_bf16_f32 v6, v22, v6
	v_cvt_pk_bf16_f32 v7, v14, v7
	v_mul_f32_e32 v14, 0x3d372713, v28
	v_mul_f32_e32 v15, 0x3d372713, v8
	v_mul_f32_e32 v14, v28, v14
	v_mul_f32_e32 v15, v8, v15
	v_fma_f32 v14, v28, v14, v28
	v_fma_f32 v15, v8, v15, v8
	v_mul_f32_e32 v14, 0x3f4c422a, v14
	v_mul_f32_e32 v15, 0x3f4c422a, v15
	v_add_f32_e32 v14, v14, v14
	v_add_f32_e32 v15, v15, v15
	v_mul_f32_e32 v14, 0xbfb8aa3b, v14
	v_mul_f32_e32 v15, 0xbfb8aa3b, v15
	v_exp_f32_e32 v14, v14
	v_exp_f32_e32 v15, v15
	v_lshlrev_b32_e32 v29, 16, v9
	v_and_b32_e32 v9, 0xffff0000, v9
	v_add_f32_e32 v14, 1.0, v14
	v_add_f32_e32 v15, 1.0, v15
	v_rcp_f32_e32 v14, v14
	v_rcp_f32_e32 v15, v15
	v_lshlrev_b32_e32 v33, 16, v17
	v_and_b32_e32 v17, 0xffff0000, v17
	v_mul_f32_e32 v14, v28, v14
	v_mul_f32_e32 v8, v8, v15
	v_fmac_f32_e32 v29, v20, v33
	v_fmac_f32_e32 v9, v21, v17
	v_cvt_pk_bf16_f32 v8, v14, v8
	v_mul_f32_e32 v14, 0x3d372713, v29
	v_mul_f32_e32 v15, 0x3d372713, v9
	v_mul_f32_e32 v14, v29, v14
	v_mul_f32_e32 v15, v9, v15
	v_fma_f32 v14, v29, v14, v29
	v_fma_f32 v15, v9, v15, v9
	v_mul_f32_e32 v14, 0x3f4c422a, v14
	v_mul_f32_e32 v15, 0x3f4c422a, v15
	v_add_f32_e32 v14, v14, v14
	v_add_f32_e32 v15, v15, v15
	v_mul_f32_e32 v14, 0xbfb8aa3b, v14
	v_mul_f32_e32 v15, 0xbfb8aa3b, v15
	v_exp_f32_e32 v14, v14
	v_exp_f32_e32 v15, v15
	v_add_f32_e32 v14, 1.0, v14
	v_add_f32_e32 v15, 1.0, v15
	v_rcp_f32_e32 v14, v14
	v_rcp_f32_e32 v15, v15
	v_mul_f32_e32 v14, v29, v14
	v_mul_f32_e32 v9, v9, v15
	v_cvt_pk_bf16_f32 v9, v14, v9
	ds_read_b128 v[22:25], v246 offset:272
	ds_read_b128 v[26:29], v246 offset:256
	s_waitcnt vmcnt(22) lgkmcnt(0)
	v_mov_b32_e32 v14, v118
	v_mov_b32_e32 v15, v119
	v_mov_b32_e32 v16, v120
	v_mov_b32_e32 v17, v121
	v_mov_b32_e32 v18, v122
	v_mov_b32_e32 v19, v123
	v_mov_b32_e32 v20, v124
	v_mov_b32_e32 v21, v125
	global_load_dwordx4 v[118:121], v[66:67], off offset:384
	global_load_dwordx4 v[122:125], v[68:69], off offset:704
	v_lshlrev_b32_e32 v30, 16, v14
	v_and_b32_e32 v14, 0xffff0000, v14
	v_lshlrev_b32_e32 v38, 16, v18
	v_and_b32_e32 v18, 0xffff0000, v18
	v_fmac_f32_e32 v14, v27, v18
	v_mul_f32_e32 v18, 0x3d372713, v14
	v_mul_f32_e32 v18, v14, v18
	v_fma_f32 v18, v14, v18, v14
	v_mul_f32_e32 v18, 0x3f4c422a, v18
	v_add_f32_e32 v18, v18, v18
	v_mul_f32_e32 v18, 0xbfb8aa3b, v18
	v_exp_f32_e32 v18, v18
	v_lshlrev_b32_e32 v31, 16, v15
	v_and_b32_e32 v15, 0xffff0000, v15
	v_lshlrev_b32_e32 v39, 16, v19
	v_add_f32_e32 v18, 1.0, v18
	v_rcp_f32_e32 v18, v18
	v_and_b32_e32 v19, 0xffff0000, v19
	v_fmac_f32_e32 v31, v28, v39
	v_fmac_f32_e32 v15, v29, v19
	v_fmac_f32_e32 v30, v26, v38
	v_mul_f32_e32 v14, v14, v18
	v_mul_f32_e32 v18, 0x3d372713, v31
	v_mul_f32_e32 v19, 0x3d372713, v15
	v_mul_f32_e32 v26, 0x3d372713, v30
	v_mul_f32_e32 v18, v31, v18
	v_mul_f32_e32 v19, v15, v19
	v_mul_f32_e32 v26, v30, v26
	v_fma_f32 v18, v31, v18, v31
	v_fma_f32 v19, v15, v19, v15
	v_fma_f32 v26, v30, v26, v30
	v_mul_f32_e32 v18, 0x3f4c422a, v18
	v_mul_f32_e32 v19, 0x3f4c422a, v19
	v_mul_f32_e32 v26, 0x3f4c422a, v26
	v_add_f32_e32 v18, v18, v18
	v_add_f32_e32 v19, v19, v19
	v_add_f32_e32 v26, v26, v26
	v_mul_f32_e32 v18, 0xbfb8aa3b, v18
	v_mul_f32_e32 v19, 0xbfb8aa3b, v19
	v_mul_f32_e32 v26, 0xbfb8aa3b, v26
	v_exp_f32_e32 v18, v18
	v_exp_f32_e32 v19, v19
	v_exp_f32_e32 v26, v26
	v_lshlrev_b32_e32 v32, 16, v16
	v_add_f32_e32 v18, 1.0, v18
	v_add_f32_e32 v19, 1.0, v19
	v_add_f32_e32 v26, 1.0, v26
	v_rcp_f32_e32 v18, v18
	v_rcp_f32_e32 v19, v19
	v_rcp_f32_e32 v26, v26
	v_and_b32_e32 v16, 0xffff0000, v16
	v_lshlrev_b32_e32 v40, 16, v20
; __device__ __forceinline__ unsigned cvt_pk_bf16(float lo, float hi) { unsigned r; asm volatile("v_cvt_pk_bf16_f32 %0, %1, %2" : "=v"(r) : "v"(lo), "v"(hi)); return r; }
; __device__ __forceinline__ float gelu_tanh(float x) { const float u = 0.7978845608028654f * (x + 0.044715f * x * x * x); return x * sigm(2.f * u); }
; #define UNPK8(VV_, XX_) float XX_[8] = {bflo((VV_).x), bfhi((VV_).x), bflo((VV_).y), bfhi((VV_).y), bflo((VV_).z), bfhi((VV_).z), bflo((VV_).w), bfhi((VV_).w)}
; __device__ __forceinline__ void glu_task(int t, int l, const float* s5d, const bf16_t* P, const bf16_t* YB, const bf16_t* WGLU, bf16_t* Z1, int fr, int fq) {
;     ...
;     for (int tb = 0; tb < 2; ++tb) { const size_t row = row0 + tb * 16;
; #pragma unroll
;         for (int ks = 0; ks < 8; ++ks) { const int k0 = ks * 32 + fq * 8; const u32x4 yw = ld8(YB + row * 256 + k0), uw = ld8(P + row * INP + OFF_S5 + k0);
;             const f32x4 d0 = *(const f32x4*)(s5d + l * 256 + k0), d1 = *(const f32x4*)(s5d + l * 256 + k0 + 4); UNPK8(yw, y); UNPK8(uw, u); u32x4 o;
;             o.x = cvt_pk_bf16(gelu_tanh(y[0] + d0[0] * u[0]), gelu_tanh(y[1] + d0[1] * u[1])); o.y = cvt_pk_bf16(gelu_tanh(y[2] + d0[2] * u[2]), gelu_tanh(y[3] + d0[3] * u[3]));
;             o.z = cvt_pk_bf16(gelu_tanh(y[4] + d1[0] * u[4]), gelu_tanh(y[5] + d1[1] * u[5])); o.w = cvt_pk_bf16(gelu_tanh(y[6] + d1[2] * u[6]), gelu_tanh(y[7] + d1[3] * u[7]));
;             bfr[tb][ks] = asfrag(o); } }
	v_and_b32_e32 v20, 0xffff0000, v20
	v_mul_f32_e32 v18, v31, v18
	v_mul_f32_e32 v15, v15, v19
	v_fmac_f32_e32 v32, v22, v40
	v_fmac_f32_e32 v16, v23, v20
	v_mul_f32_e32 v26, v30, v26
	v_cvt_pk_bf16_f32 v14, v26, v14
	v_cvt_pk_bf16_f32 v15, v18, v15
	v_mul_f32_e32 v18, 0x3d372713, v32
	v_mul_f32_e32 v19, 0x3d372713, v16
	v_mul_f32_e32 v18, v32, v18
	v_mul_f32_e32 v19, v16, v19
	v_fma_f32 v18, v32, v18, v32
	v_fma_f32 v19, v16, v19, v16
	v_mul_f32_e32 v18, 0x3f4c422a, v18
	v_mul_f32_e32 v19, 0x3f4c422a, v19
	v_add_f32_e32 v18, v18, v18
	v_add_f32_e32 v19, v19, v19
	v_mul_f32_e32 v18, 0xbfb8aa3b, v18
	v_mul_f32_e32 v19, 0xbfb8aa3b, v19
	v_exp_f32_e32 v18, v18
	v_exp_f32_e32 v19, v19
	v_lshlrev_b32_e32 v33, 16, v17
	v_and_b32_e32 v17, 0xffff0000, v17
	v_add_f32_e32 v18, 1.0, v18
	v_add_f32_e32 v19, 1.0, v19
	v_rcp_f32_e32 v18, v18
	v_rcp_f32_e32 v19, v19
	v_lshlrev_b32_e32 v41, 16, v21
	v_and_b32_e32 v21, 0xffff0000, v21
	v_mul_f32_e32 v18, v32, v18
	v_mul_f32_e32 v16, v16, v19
	v_fmac_f32_e32 v33, v24, v41
	v_fmac_f32_e32 v17, v25, v21
	v_cvt_pk_bf16_f32 v16, v18, v16
	v_mul_f32_e32 v18, 0x3d372713, v33
	v_mul_f32_e32 v19, 0x3d372713, v17
	v_mul_f32_e32 v18, v33, v18
	v_mul_f32_e32 v19, v17, v19
	v_fma_f32 v18, v33, v18, v33
	v_fma_f32 v19, v17, v19, v17
	v_mul_f32_e32 v18, 0x3f4c422a, v18
	v_mul_f32_e32 v19, 0x3f4c422a, v19
	v_add_f32_e32 v18, v18, v18
	v_add_f32_e32 v19, v19, v19
	v_mul_f32_e32 v18, 0xbfb8aa3b, v18
	v_mul_f32_e32 v19, 0xbfb8aa3b, v19
	v_exp_f32_e32 v18, v18
	v_exp_f32_e32 v19, v19
	v_add_f32_e32 v18, 1.0, v18
	v_add_f32_e32 v19, 1.0, v19
	v_rcp_f32_e32 v18, v18
	v_rcp_f32_e32 v19, v19
	v_mul_f32_e32 v18, v33, v18
	v_mul_f32_e32 v17, v17, v19
	v_cvt_pk_bf16_f32 v17, v18, v17
	ds_read_b128 v[26:29], v246 offset:400
	ds_read_b128 v[30:33], v246 offset:384
	s_waitcnt vmcnt(22) lgkmcnt(0)
	v_mov_b32_e32 v18, v126
	v_mov_b32_e32 v19, v127
	v_mov_b32_e32 v20, v128
	v_mov_b32_e32 v21, v129
	v_mov_b32_e32 v22, v130
	v_mov_b32_e32 v23, v131
	v_mov_b32_e32 v24, v132
	v_mov_b32_e32 v25, v133
	global_load_dwordx4 v[126:129], v[66:67], off offset:448
	global_load_dwordx4 v[130:133], v[68:69], off offset:768
	v_lshlrev_b32_e32 v38, 16, v18
	v_and_b32_e32 v18, 0xffff0000, v18
	v_lshlrev_b32_e32 v42, 16, v22
	v_and_b32_e32 v22, 0xffff0000, v22
	v_fmac_f32_e32 v18, v31, v22
	v_mul_f32_e32 v22, 0x3d372713, v18
	v_mul_f32_e32 v22, v18, v22
	v_fma_f32 v22, v18, v22, v18
	v_mul_f32_e32 v22, 0x3f4c422a, v22
	v_add_f32_e32 v22, v22, v22
	v_mul_f32_e32 v22, 0xbfb8aa3b, v22
	v_exp_f32_e32 v22, v22
	v_lshlrev_b32_e32 v39, 16, v19
	v_and_b32_e32 v19, 0xffff0000, v19
	v_lshlrev_b32_e32 v43, 16, v23
	v_add_f32_e32 v22, 1.0, v22
	v_rcp_f32_e32 v22, v22
	v_and_b32_e32 v23, 0xffff0000, v23
	v_fmac_f32_e32 v39, v32, v43
	v_fmac_f32_e32 v19, v33, v23
	v_fmac_f32_e32 v38, v30, v42
	v_mul_f32_e32 v18, v18, v22
	v_mul_f32_e32 v22, 0x3d372713, v39
	v_mul_f32_e32 v23, 0x3d372713, v19
	v_mul_f32_e32 v30, 0x3d372713, v38
	v_mul_f32_e32 v22, v39, v22
	v_mul_f32_e32 v23, v19, v23
	v_mul_f32_e32 v30, v38, v30
	v_fma_f32 v22, v39, v22, v39
	v_fma_f32 v23, v19, v23, v19
	v_fma_f32 v30, v38, v30, v38
	v_mul_f32_e32 v22, 0x3f4c422a, v22
	v_mul_f32_e32 v23, 0x3f4c422a, v23
	v_mul_f32_e32 v30, 0x3f4c422a, v30
	v_add_f32_e32 v22, v22, v22
	v_add_f32_e32 v23, v23, v23
	v_add_f32_e32 v30, v30, v30
	v_mul_f32_e32 v22, 0xbfb8aa3b, v22
	v_mul_f32_e32 v23, 0xbfb8aa3b, v23
	v_mul_f32_e32 v30, 0xbfb8aa3b, v30
	v_exp_f32_e32 v22, v22
	v_exp_f32_e32 v23, v23
	v_exp_f32_e32 v30, v30
	v_lshlrev_b32_e32 v40, 16, v20
	v_add_f32_e32 v22, 1.0, v22
	v_add_f32_e32 v23, 1.0, v23
	v_add_f32_e32 v30, 1.0, v30
	v_rcp_f32_e32 v22, v22
	v_rcp_f32_e32 v23, v23
	v_rcp_f32_e32 v30, v30
	v_and_b32_e32 v20, 0xffff0000, v20
	v_lshlrev_b32_e32 v44, 16, v24
	v_and_b32_e32 v24, 0xffff0000, v24
	v_mul_f32_e32 v22, v39, v22
	v_mul_f32_e32 v19, v19, v23
	v_fmac_f32_e32 v40, v26, v44
	v_fmac_f32_e32 v20, v27, v24
	v_mul_f32_e32 v30, v38, v30
	v_cvt_pk_bf16_f32 v18, v30, v18
	v_cvt_pk_bf16_f32 v19, v22, v19
	v_mul_f32_e32 v22, 0x3d372713, v40
	v_mul_f32_e32 v23, 0x3d372713, v20
	v_mul_f32_e32 v22, v40, v22
	v_mul_f32_e32 v23, v20, v23
	v_fma_f32 v22, v40, v22, v40
	v_fma_f32 v23, v20, v23, v20
	v_mul_f32_e32 v22, 0x3f4c422a, v22
	v_mul_f32_e32 v23, 0x3f4c422a, v23
	v_add_f32_e32 v22, v22, v22
	v_add_f32_e32 v23, v23, v23
	v_mul_f32_e32 v22, 0xbfb8aa3b, v22
	v_mul_f32_e32 v23, 0xbfb8aa3b, v23
	v_exp_f32_e32 v22, v22
	v_exp_f32_e32 v23, v23
	v_lshlrev_b32_e32 v41, 16, v21
	v_and_b32_e32 v21, 0xffff0000, v21
	v_add_f32_e32 v22, 1.0, v22
	v_add_f32_e32 v23, 1.0, v23
	v_rcp_f32_e32 v22, v22
	v_rcp_f32_e32 v23, v23
	v_lshlrev_b32_e32 v45, 16, v25
	v_and_b32_e32 v25, 0xffff0000, v25
	v_mul_f32_e32 v22, v40, v22
	v_mul_f32_e32 v20, v20, v23
	v_fmac_f32_e32 v41, v28, v45
	v_fmac_f32_e32 v21, v29, v25
	v_cvt_pk_bf16_f32 v20, v22, v20
	v_mul_f32_e32 v22, 0x3d372713, v41
	v_mul_f32_e32 v23, 0x3d372713, v21
	v_mul_f32_e32 v22, v41, v22
	v_mul_f32_e32 v23, v21, v23
	v_fma_f32 v22, v41, v22, v41
	v_fma_f32 v23, v21, v23, v21
	v_mul_f32_e32 v22, 0x3f4c422a, v22
	v_mul_f32_e32 v23, 0x3f4c422a, v23
	v_add_f32_e32 v22, v22, v22
	v_add_f32_e32 v23, v23, v23
	v_mul_f32_e32 v22, 0xbfb8aa3b, v22
	v_mul_f32_e32 v23, 0xbfb8aa3b, v23
	v_exp_f32_e32 v22, v22
	v_exp_f32_e32 v23, v23
	v_add_f32_e32 v22, 1.0, v22
	v_add_f32_e32 v23, 1.0, v23
	v_rcp_f32_e32 v22, v22
	v_rcp_f32_e32 v23, v23
	v_mul_f32_e32 v22, v41, v22
	v_mul_f32_e32 v21, v21, v23
	v_cvt_pk_bf16_f32 v21, v22, v21
	ds_read_b128 v[30:33], v246 offset:528
	ds_read_b128 v[38:41], v246 offset:512
	s_waitcnt vmcnt(22) lgkmcnt(0)
; __device__ __forceinline__ unsigned cvt_pk_bf16(float lo, float hi) { unsigned r; asm volatile("v_cvt_pk_bf16_f32 %0, %1, %2" : "=v"(r) : "v"(lo), "v"(hi)); return r; }
; __device__ __forceinline__ float gelu_tanh(float x) { const float u = 0.7978845608028654f * (x + 0.044715f * x * x * x); return x * sigm(2.f * u); }
; #define UNPK8(VV_, XX_) float XX_[8] = {bflo((VV_).x), bfhi((VV_).x), bflo((VV_).y), bfhi((VV_).y), bflo((VV_).z), bfhi((VV_).z), bflo((VV_).w), bfhi((VV_).w)}
; __device__ __forceinline__ void glu_task(int t, int l, const float* s5d, const bf16_t* P, const bf16_t* YB, const bf16_t* WGLU, bf16_t* Z1, int fr, int fq) {
;     ...
;     for (int tb = 0; tb < 2; ++tb) { const size_t row = row0 + tb * 16;
; #pragma unroll
;         for (int ks = 0; ks < 8; ++ks) { const int k0 = ks * 32 + fq * 8; const u32x4 yw = ld8(YB + row * 256 + k0), uw = ld8(P + row * INP + OFF_S5 + k0);
;             const f32x4 d0 = *(const f32x4*)(s5d + l * 256 + k0), d1 = *(const f32x4*)(s5d + l * 256 + k0 + 4); UNPK8(yw, y); UNPK8(uw, u); u32x4 o;
;             o.x = cvt_pk_bf16(gelu_tanh(y[0] + d0[0] * u[0]), gelu_tanh(y[1] + d0[1] * u[1])); o.y = cvt_pk_bf16(gelu_tanh(y[2] + d0[2] * u[2]), gelu_tanh(y[3] + d0[3] * u[3]));
;             o.z = cvt_pk_bf16(gelu_tanh(y[4] + d1[0] * u[4]), gelu_tanh(y[5] + d1[1] * u[5])); o.w = cvt_pk_bf16(gelu_tanh(y[6] + d1[2] * u[6]), gelu_tanh(y[7] + d1[3] * u[7]));
;             bfr[tb][ks] = asfrag(o); } }
	v_mov_b32_e32 v22, v140
	v_mov_b32_e32 v23, v141
	v_mov_b32_e32 v24, v142
	v_mov_b32_e32 v25, v143
	v_mov_b32_e32 v26, v144
	v_mov_b32_e32 v27, v145
	v_mov_b32_e32 v28, v146
	v_mov_b32_e32 v29, v147
	v_lshlrev_b32_e32 v42, 16, v22
	v_and_b32_e32 v22, 0xffff0000, v22
	v_lshlrev_b32_e32 v46, 16, v26
	v_and_b32_e32 v26, 0xffff0000, v26
	v_fmac_f32_e32 v22, v39, v26
	v_mul_f32_e32 v26, 0x3d372713, v22
	v_mul_f32_e32 v26, v22, v26
	v_fma_f32 v26, v22, v26, v22
	v_mul_f32_e32 v26, 0x3f4c422a, v26
	v_add_f32_e32 v26, v26, v26
	v_mul_f32_e32 v26, 0xbfb8aa3b, v26
	v_exp_f32_e32 v26, v26
	v_lshlrev_b32_e32 v43, 16, v23
	v_and_b32_e32 v23, 0xffff0000, v23
	v_lshlrev_b32_e32 v47, 16, v27
	v_add_f32_e32 v26, 1.0, v26
	v_rcp_f32_e32 v26, v26
	v_and_b32_e32 v27, 0xffff0000, v27
	v_fmac_f32_e32 v43, v40, v47
	v_fmac_f32_e32 v23, v41, v27
	v_fmac_f32_e32 v42, v38, v46
	v_mul_f32_e32 v22, v22, v26
	v_mul_f32_e32 v26, 0x3d372713, v43
	v_mul_f32_e32 v27, 0x3d372713, v23
	v_mul_f32_e32 v38, 0x3d372713, v42
	v_mul_f32_e32 v26, v43, v26
	v_mul_f32_e32 v27, v23, v27
	v_mul_f32_e32 v38, v42, v38
	v_fma_f32 v26, v43, v26, v43
	v_fma_f32 v27, v23, v27, v23
	v_fma_f32 v38, v42, v38, v42
	v_mul_f32_e32 v26, 0x3f4c422a, v26
	v_mul_f32_e32 v27, 0x3f4c422a, v27
	v_mul_f32_e32 v38, 0x3f4c422a, v38
	v_add_f32_e32 v26, v26, v26
	v_add_f32_e32 v27, v27, v27
	v_add_f32_e32 v38, v38, v38
	v_mul_f32_e32 v26, 0xbfb8aa3b, v26
	v_mul_f32_e32 v27, 0xbfb8aa3b, v27
	v_mul_f32_e32 v38, 0xbfb8aa3b, v38
	v_exp_f32_e32 v26, v26
	v_exp_f32_e32 v27, v27
	v_exp_f32_e32 v38, v38
	v_lshlrev_b32_e32 v44, 16, v24
	v_add_f32_e32 v26, 1.0, v26
	v_add_f32_e32 v27, 1.0, v27
	v_add_f32_e32 v38, 1.0, v38
	v_rcp_f32_e32 v26, v26
	v_rcp_f32_e32 v27, v27
	v_rcp_f32_e32 v38, v38
	v_and_b32_e32 v24, 0xffff0000, v24
	v_lshlrev_b32_e32 v48, 16, v28
	v_and_b32_e32 v28, 0xffff0000, v28
	v_mul_f32_e32 v26, v43, v26
	v_mul_f32_e32 v23, v23, v27
	v_fmac_f32_e32 v44, v30, v48
	v_fmac_f32_e32 v24, v31, v28
	v_mul_f32_e32 v38, v42, v38
	v_cvt_pk_bf16_f32 v22, v38, v22
	v_cvt_pk_bf16_f32 v23, v26, v23
	v_mul_f32_e32 v26, 0x3d372713, v44
	v_mul_f32_e32 v27, 0x3d372713, v24
	v_mul_f32_e32 v26, v44, v26
	v_mul_f32_e32 v27, v24, v27
	v_fma_f32 v26, v44, v26, v44
	v_fma_f32 v27, v24, v27, v24
	v_mul_f32_e32 v26, 0x3f4c422a, v26
	v_mul_f32_e32 v27, 0x3f4c422a, v27
	v_add_f32_e32 v26, v26, v26
	v_add_f32_e32 v27, v27, v27
	v_mul_f32_e32 v26, 0xbfb8aa3b, v26
	v_mul_f32_e32 v27, 0xbfb8aa3b, v27
	v_exp_f32_e32 v26, v26
	v_exp_f32_e32 v27, v27
	v_lshlrev_b32_e32 v45, 16, v25
	v_and_b32_e32 v25, 0xffff0000, v25
	v_add_f32_e32 v26, 1.0, v26
	v_add_f32_e32 v27, 1.0, v27
	v_rcp_f32_e32 v26, v26
	v_rcp_f32_e32 v27, v27
	v_lshlrev_b32_e32 v49, 16, v29
	v_and_b32_e32 v29, 0xffff0000, v29
	v_mul_f32_e32 v26, v44, v26
	v_mul_f32_e32 v24, v24, v27
	v_fmac_f32_e32 v45, v32, v49
	v_fmac_f32_e32 v25, v33, v29
	v_cvt_pk_bf16_f32 v24, v26, v24
	v_mul_f32_e32 v26, 0x3d372713, v45
	v_mul_f32_e32 v27, 0x3d372713, v25
	v_mul_f32_e32 v26, v45, v26
	v_mul_f32_e32 v27, v25, v27
	v_fma_f32 v26, v45, v26, v45
	v_fma_f32 v27, v25, v27, v25
	v_mul_f32_e32 v26, 0x3f4c422a, v26
	v_mul_f32_e32 v27, 0x3f4c422a, v27
	v_add_f32_e32 v26, v26, v26
	v_add_f32_e32 v27, v27, v27
	v_mul_f32_e32 v26, 0xbfb8aa3b, v26
	v_mul_f32_e32 v27, 0xbfb8aa3b, v27
	v_exp_f32_e32 v26, v26
	v_exp_f32_e32 v27, v27
	v_add_f32_e32 v26, 1.0, v26
	v_add_f32_e32 v27, 1.0, v27
	v_rcp_f32_e32 v26, v26
	v_rcp_f32_e32 v27, v27
	v_mul_f32_e32 v26, v45, v26
	v_mul_f32_e32 v25, v25, v27
	v_cvt_pk_bf16_f32 v25, v26, v25
	ds_read_b128 v[38:41], v246 offset:656
	ds_read_b128 v[42:45], v246 offset:640
	s_waitcnt vmcnt(20) lgkmcnt(0)
	v_mov_b32_e32 v26, v160
	v_mov_b32_e32 v27, v161
	v_mov_b32_e32 v28, v162
	v_mov_b32_e32 v29, v163
	v_mov_b32_e32 v30, v164
	v_mov_b32_e32 v31, v165
	v_mov_b32_e32 v32, v166
	v_mov_b32_e32 v33, v167
	v_lshlrev_b32_e32 v46, 16, v26
	v_and_b32_e32 v26, 0xffff0000, v26
	v_lshlrev_b32_e32 v50, 16, v30
	v_and_b32_e32 v30, 0xffff0000, v30
	v_fmac_f32_e32 v26, v43, v30
	v_mul_f32_e32 v30, 0x3d372713, v26
	v_mul_f32_e32 v30, v26, v30
	v_fma_f32 v30, v26, v30, v26
	v_mul_f32_e32 v30, 0x3f4c422a, v30
	v_add_f32_e32 v30, v30, v30
	v_mul_f32_e32 v30, 0xbfb8aa3b, v30
	v_exp_f32_e32 v30, v30
	v_lshlrev_b32_e32 v47, 16, v27
	v_and_b32_e32 v27, 0xffff0000, v27
	v_lshlrev_b32_e32 v51, 16, v31
	v_add_f32_e32 v30, 1.0, v30
	v_rcp_f32_e32 v30, v30
	v_and_b32_e32 v31, 0xffff0000, v31
	v_fmac_f32_e32 v47, v44, v51
	v_fmac_f32_e32 v27, v45, v31
	v_fmac_f32_e32 v46, v42, v50
	v_mul_f32_e32 v26, v26, v30
	v_mul_f32_e32 v30, 0x3d372713, v47
	v_mul_f32_e32 v31, 0x3d372713, v27
	v_mul_f32_e32 v42, 0x3d372713, v46
	v_mul_f32_e32 v30, v47, v30
	v_mul_f32_e32 v31, v27, v31
	v_mul_f32_e32 v42, v46, v42
	v_fma_f32 v30, v47, v30, v47
	v_fma_f32 v31, v27, v31, v27
	v_fma_f32 v42, v46, v42, v46
	v_mul_f32_e32 v30, 0x3f4c422a, v30
	v_mul_f32_e32 v31, 0x3f4c422a, v31
	v_mul_f32_e32 v42, 0x3f4c422a, v42
	v_add_f32_e32 v30, v30, v30
	v_add_f32_e32 v31, v31, v31
	v_add_f32_e32 v42, v42, v42
	v_mul_f32_e32 v30, 0xbfb8aa3b, v30
	v_mul_f32_e32 v31, 0xbfb8aa3b, v31
	v_mul_f32_e32 v42, 0xbfb8aa3b, v42
	v_exp_f32_e32 v30, v30
	v_exp_f32_e32 v31, v31
	v_exp_f32_e32 v42, v42
	v_lshlrev_b32_e32 v48, 16, v28
	v_add_f32_e32 v30, 1.0, v30
	v_add_f32_e32 v31, 1.0, v31
	v_add_f32_e32 v42, 1.0, v42
	v_rcp_f32_e32 v30, v30
	v_rcp_f32_e32 v31, v31
	v_rcp_f32_e32 v42, v42
	v_and_b32_e32 v28, 0xffff0000, v28
	v_lshlrev_b32_e32 v52, 16, v32
	v_and_b32_e32 v32, 0xffff0000, v32
	v_mul_f32_e32 v30, v47, v30
	v_mul_f32_e32 v27, v27, v31
	v_fmac_f32_e32 v48, v38, v52
	v_fmac_f32_e32 v28, v39, v32
	v_mul_f32_e32 v42, v46, v42
; __device__ __forceinline__ unsigned cvt_pk_bf16(float lo, float hi) { unsigned r; asm volatile("v_cvt_pk_bf16_f32 %0, %1, %2" : "=v"(r) : "v"(lo), "v"(hi)); return r; }
; __device__ __forceinline__ float gelu_tanh(float x) { const float u = 0.7978845608028654f * (x + 0.044715f * x * x * x); return x * sigm(2.f * u); }
; #define UNPK8(VV_, XX_) float XX_[8] = {bflo((VV_).x), bfhi((VV_).x), bflo((VV_).y), bfhi((VV_).y), bflo((VV_).z), bfhi((VV_).z), bflo((VV_).w), bfhi((VV_).w)}
; __device__ __forceinline__ void glu_task(int t, int l, const float* s5d, const bf16_t* P, const bf16_t* YB, const bf16_t* WGLU, bf16_t* Z1, int fr, int fq) {
;     ...
;     for (int tb = 0; tb < 2; ++tb) { const size_t row = row0 + tb * 16;
; #pragma unroll
;         for (int ks = 0; ks < 8; ++ks) { const int k0 = ks * 32 + fq * 8; const u32x4 yw = ld8(YB + row * 256 + k0), uw = ld8(P + row * INP + OFF_S5 + k0);
;             const f32x4 d0 = *(const f32x4*)(s5d + l * 256 + k0), d1 = *(const f32x4*)(s5d + l * 256 + k0 + 4); UNPK8(yw, y); UNPK8(uw, u); u32x4 o;
;             o.x = cvt_pk_bf16(gelu_tanh(y[0] + d0[0] * u[0]), gelu_tanh(y[1] + d0[1] * u[1])); o.y = cvt_pk_bf16(gelu_tanh(y[2] + d0[2] * u[2]), gelu_tanh(y[3] + d0[3] * u[3]));
;             o.z = cvt_pk_bf16(gelu_tanh(y[4] + d1[0] * u[4]), gelu_tanh(y[5] + d1[1] * u[5])); o.w = cvt_pk_bf16(gelu_tanh(y[6] + d1[2] * u[6]), gelu_tanh(y[7] + d1[3] * u[7]));
;             bfr[tb][ks] = asfrag(o); } }
	v_cvt_pk_bf16_f32 v26, v42, v26
	v_cvt_pk_bf16_f32 v27, v30, v27
	v_mul_f32_e32 v30, 0x3d372713, v48
	v_mul_f32_e32 v31, 0x3d372713, v28
	v_mul_f32_e32 v30, v48, v30
	v_mul_f32_e32 v31, v28, v31
	v_fma_f32 v30, v48, v30, v48
	v_fma_f32 v31, v28, v31, v28
	v_mul_f32_e32 v30, 0x3f4c422a, v30
	v_mul_f32_e32 v31, 0x3f4c422a, v31
	v_add_f32_e32 v30, v30, v30
	v_add_f32_e32 v31, v31, v31
	v_mul_f32_e32 v30, 0xbfb8aa3b, v30
	v_mul_f32_e32 v31, 0xbfb8aa3b, v31
	v_exp_f32_e32 v30, v30
	v_exp_f32_e32 v31, v31
	v_lshlrev_b32_e32 v49, 16, v29
	v_and_b32_e32 v29, 0xffff0000, v29
	v_add_f32_e32 v30, 1.0, v30
	v_add_f32_e32 v31, 1.0, v31
	v_rcp_f32_e32 v30, v30
	v_rcp_f32_e32 v31, v31
	v_lshlrev_b32_e32 v53, 16, v33
	v_and_b32_e32 v33, 0xffff0000, v33
	v_mul_f32_e32 v30, v48, v30
	v_mul_f32_e32 v28, v28, v31
	v_fmac_f32_e32 v49, v40, v53
	v_fmac_f32_e32 v29, v41, v33
	v_cvt_pk_bf16_f32 v28, v30, v28
	v_mul_f32_e32 v30, 0x3d372713, v49
	v_mul_f32_e32 v31, 0x3d372713, v29
	v_mul_f32_e32 v30, v49, v30
	v_mul_f32_e32 v31, v29, v31
	v_fma_f32 v30, v49, v30, v49
	v_fma_f32 v31, v29, v31, v29
	v_mul_f32_e32 v30, 0x3f4c422a, v30
	v_mul_f32_e32 v31, 0x3f4c422a, v31
	v_add_f32_e32 v30, v30, v30
	v_add_f32_e32 v31, v31, v31
	v_mul_f32_e32 v30, 0xbfb8aa3b, v30
	v_mul_f32_e32 v31, 0xbfb8aa3b, v31
	v_exp_f32_e32 v30, v30
	v_exp_f32_e32 v31, v31
	v_add_f32_e32 v30, 1.0, v30
	v_add_f32_e32 v31, 1.0, v31
	v_rcp_f32_e32 v30, v30
	v_rcp_f32_e32 v31, v31
	v_mul_f32_e32 v30, v49, v30
	v_mul_f32_e32 v29, v29, v31
	v_cvt_pk_bf16_f32 v29, v30, v29
	ds_read_b128 v[42:45], v246 offset:784
	ds_read_b128 v[46:49], v246 offset:768
	s_waitcnt vmcnt(18) lgkmcnt(0)
	v_mov_b32_e32 v30, v180
	v_mov_b32_e32 v31, v181
	v_mov_b32_e32 v32, v182
	v_mov_b32_e32 v33, v183
	v_mov_b32_e32 v38, v184
	v_mov_b32_e32 v39, v185
	v_mov_b32_e32 v40, v186
	v_mov_b32_e32 v41, v187
	v_lshlrev_b32_e32 v50, 16, v30
	v_and_b32_e32 v30, 0xffff0000, v30
	v_lshlrev_b32_e32 v54, 16, v38
	v_and_b32_e32 v38, 0xffff0000, v38
	v_fmac_f32_e32 v30, v47, v38
	v_mul_f32_e32 v38, 0x3d372713, v30
	v_mul_f32_e32 v38, v30, v38
	v_fma_f32 v38, v30, v38, v30
	v_mul_f32_e32 v38, 0x3f4c422a, v38
	v_add_f32_e32 v38, v38, v38
	v_mul_f32_e32 v38, 0xbfb8aa3b, v38
	v_exp_f32_e32 v38, v38
	v_lshlrev_b32_e32 v51, 16, v31
	v_and_b32_e32 v31, 0xffff0000, v31
	v_lshlrev_b32_e32 v55, 16, v39
	v_add_f32_e32 v38, 1.0, v38
	v_rcp_f32_e32 v38, v38
	v_and_b32_e32 v39, 0xffff0000, v39
	v_fmac_f32_e32 v51, v48, v55
	v_fmac_f32_e32 v31, v49, v39
	v_fmac_f32_e32 v50, v46, v54
	v_mul_f32_e32 v30, v30, v38
	v_mul_f32_e32 v38, 0x3d372713, v51
	v_mul_f32_e32 v39, 0x3d372713, v31
	v_mul_f32_e32 v46, 0x3d372713, v50
	v_mul_f32_e32 v38, v51, v38
	v_mul_f32_e32 v39, v31, v39
	v_mul_f32_e32 v46, v50, v46
	v_fma_f32 v38, v51, v38, v51
	v_fma_f32 v39, v31, v39, v31
	v_fma_f32 v46, v50, v46, v50
	v_mul_f32_e32 v38, 0x3f4c422a, v38
	v_mul_f32_e32 v39, 0x3f4c422a, v39
	v_mul_f32_e32 v46, 0x3f4c422a, v46
	v_add_f32_e32 v38, v38, v38
	v_add_f32_e32 v39, v39, v39
	v_add_f32_e32 v46, v46, v46
	v_mul_f32_e32 v38, 0xbfb8aa3b, v38
	v_mul_f32_e32 v39, 0xbfb8aa3b, v39
	v_mul_f32_e32 v46, 0xbfb8aa3b, v46
	v_exp_f32_e32 v38, v38
	v_exp_f32_e32 v39, v39
	v_exp_f32_e32 v46, v46
	v_lshlrev_b32_e32 v52, 16, v32
	v_add_f32_e32 v38, 1.0, v38
	v_add_f32_e32 v39, 1.0, v39
	v_add_f32_e32 v46, 1.0, v46
	v_rcp_f32_e32 v38, v38
	v_rcp_f32_e32 v39, v39
	v_rcp_f32_e32 v46, v46
	v_and_b32_e32 v32, 0xffff0000, v32
	v_lshlrev_b32_e32 v56, 16, v40
	v_and_b32_e32 v40, 0xffff0000, v40
	v_mul_f32_e32 v38, v51, v38
	v_mul_f32_e32 v31, v31, v39
	v_fmac_f32_e32 v52, v42, v56
	v_fmac_f32_e32 v32, v43, v40
	v_mul_f32_e32 v46, v50, v46
	v_cvt_pk_bf16_f32 v30, v46, v30
	v_cvt_pk_bf16_f32 v31, v38, v31
	v_mul_f32_e32 v38, 0x3d372713, v52
	v_mul_f32_e32 v39, 0x3d372713, v32
	v_mul_f32_e32 v38, v52, v38
	v_mul_f32_e32 v39, v32, v39
	v_fma_f32 v38, v52, v38, v52
	v_fma_f32 v39, v32, v39, v32
	v_mul_f32_e32 v38, 0x3f4c422a, v38
	v_mul_f32_e32 v39, 0x3f4c422a, v39
	v_add_f32_e32 v38, v38, v38
	v_add_f32_e32 v39, v39, v39
	v_mul_f32_e32 v38, 0xbfb8aa3b, v38
	v_mul_f32_e32 v39, 0xbfb8aa3b, v39
	v_exp_f32_e32 v38, v38
	v_exp_f32_e32 v39, v39
	v_lshlrev_b32_e32 v53, 16, v33
	v_and_b32_e32 v33, 0xffff0000, v33
	v_add_f32_e32 v38, 1.0, v38
	v_add_f32_e32 v39, 1.0, v39
	v_rcp_f32_e32 v38, v38
	v_rcp_f32_e32 v39, v39
	v_lshlrev_b32_e32 v57, 16, v41
	v_and_b32_e32 v41, 0xffff0000, v41
	v_mul_f32_e32 v38, v52, v38
	v_mul_f32_e32 v32, v32, v39
	v_fmac_f32_e32 v53, v44, v57
	v_fmac_f32_e32 v33, v45, v41
	v_cvt_pk_bf16_f32 v32, v38, v32
	v_mul_f32_e32 v38, 0x3d372713, v53
	v_mul_f32_e32 v39, 0x3d372713, v33
	v_mul_f32_e32 v38, v53, v38
	v_mul_f32_e32 v39, v33, v39
	v_fma_f32 v38, v53, v38, v53
	v_fma_f32 v39, v33, v39, v33
	v_mul_f32_e32 v38, 0x3f4c422a, v38
	v_mul_f32_e32 v39, 0x3f4c422a, v39
	v_add_f32_e32 v38, v38, v38
	v_add_f32_e32 v39, v39, v39
	v_mul_f32_e32 v38, 0xbfb8aa3b, v38
	v_mul_f32_e32 v39, 0xbfb8aa3b, v39
	v_exp_f32_e32 v38, v38
	v_exp_f32_e32 v39, v39
	v_add_f32_e32 v38, 1.0, v38
	v_add_f32_e32 v39, 1.0, v39
	v_rcp_f32_e32 v38, v38
	v_rcp_f32_e32 v39, v39
	v_mul_f32_e32 v38, v53, v38
	v_mul_f32_e32 v33, v33, v39
	v_cvt_pk_bf16_f32 v33, v38, v33
	s_nop 0
	s_nop 0
	ds_read_b128 v[42:45], v246 offset:912
	ds_read_b128 v[46:49], v246 offset:896
	s_waitcnt vmcnt(16) lgkmcnt(0)
; __device__ __forceinline__ unsigned cvt_pk_bf16(float lo, float hi) { unsigned r; asm volatile("v_cvt_pk_bf16_f32 %0, %1, %2" : "=v"(r) : "v"(lo), "v"(hi)); return r; }
; __device__ __forceinline__ float gelu_tanh(float x) { const float u = 0.7978845608028654f * (x + 0.044715f * x * x * x); return x * sigm(2.f * u); }
; #define UNPK8(VV_, XX_) float XX_[8] = {bflo((VV_).x), bfhi((VV_).x), bflo((VV_).y), bfhi((VV_).y), bflo((VV_).z), bfhi((VV_).z), bflo((VV_).w), bfhi((VV_).w)}
; __device__ __forceinline__ void glu_task(int t, int l, const float* s5d, const bf16_t* P, const bf16_t* YB, const bf16_t* WGLU, bf16_t* Z1, int fr, int fq) {
;     ...
;     for (int tb = 0; tb < 2; ++tb) { const size_t row = row0 + tb * 16;
; #pragma unroll
;         for (int ks = 0; ks < 8; ++ks) { const int k0 = ks * 32 + fq * 8; const u32x4 yw = ld8(YB + row * 256 + k0), uw = ld8(P + row * INP + OFF_S5 + k0);
;             const f32x4 d0 = *(const f32x4*)(s5d + l * 256 + k0), d1 = *(const f32x4*)(s5d + l * 256 + k0 + 4); UNPK8(yw, y); UNPK8(uw, u); u32x4 o;
;             o.x = cvt_pk_bf16(gelu_tanh(y[0] + d0[0] * u[0]), gelu_tanh(y[1] + d0[1] * u[1])); o.y = cvt_pk_bf16(gelu_tanh(y[2] + d0[2] * u[2]), gelu_tanh(y[3] + d0[3] * u[3]));
;             o.z = cvt_pk_bf16(gelu_tanh(y[4] + d1[0] * u[4]), gelu_tanh(y[5] + d1[1] * u[5])); o.w = cvt_pk_bf16(gelu_tanh(y[6] + d1[2] * u[6]), gelu_tanh(y[7] + d1[3] * u[7]));
;             bfr[tb][ks] = asfrag(o); } }
	v_mov_b32_e32 v38, v214
	v_mov_b32_e32 v39, v215
	v_mov_b32_e32 v40, v216
	v_mov_b32_e32 v41, v217
	v_mov_b32_e32 v34, v218
	v_mov_b32_e32 v35, v219
	v_mov_b32_e32 v36, v220
	v_mov_b32_e32 v37, v221
	v_lshlrev_b32_e32 v50, 16, v38
	v_and_b32_e32 v38, 0xffff0000, v38
	v_lshlrev_b32_e32 v54, 16, v34
	v_and_b32_e32 v34, 0xffff0000, v34
	v_fmac_f32_e32 v38, v47, v34
	v_mul_f32_e32 v34, 0x3d372713, v38
	v_mul_f32_e32 v34, v38, v34
	v_fma_f32 v34, v38, v34, v38
	v_mul_f32_e32 v34, 0x3f4c422a, v34
	v_add_f32_e32 v34, v34, v34
	v_mul_f32_e32 v34, 0xbfb8aa3b, v34
	v_exp_f32_e32 v34, v34
	v_lshlrev_b32_e32 v51, 16, v39
	v_and_b32_e32 v39, 0xffff0000, v39
	v_lshlrev_b32_e32 v55, 16, v35
	v_add_f32_e32 v34, 1.0, v34
	v_rcp_f32_e32 v34, v34
	v_and_b32_e32 v35, 0xffff0000, v35
	v_fmac_f32_e32 v51, v48, v55
	v_fmac_f32_e32 v39, v49, v35
	v_fmac_f32_e32 v50, v46, v54
	v_mul_f32_e32 v34, v38, v34
	v_mul_f32_e32 v38, 0x3d372713, v51
	v_mul_f32_e32 v35, 0x3d372713, v39
	v_mul_f32_e32 v46, 0x3d372713, v50
	v_mul_f32_e32 v38, v51, v38
	v_mul_f32_e32 v35, v39, v35
	v_mul_f32_e32 v46, v50, v46
	v_fma_f32 v38, v51, v38, v51
	v_fma_f32 v35, v39, v35, v39
	v_fma_f32 v46, v50, v46, v50
	v_mul_f32_e32 v38, 0x3f4c422a, v38
	v_mul_f32_e32 v35, 0x3f4c422a, v35
	v_mul_f32_e32 v46, 0x3f4c422a, v46
	v_add_f32_e32 v38, v38, v38
	v_add_f32_e32 v35, v35, v35
	v_add_f32_e32 v46, v46, v46
	v_mul_f32_e32 v38, 0xbfb8aa3b, v38
	v_mul_f32_e32 v35, 0xbfb8aa3b, v35
	v_mul_f32_e32 v46, 0xbfb8aa3b, v46
	v_exp_f32_e32 v38, v38
	v_exp_f32_e32 v35, v35
	v_exp_f32_e32 v46, v46
	v_lshlrev_b32_e32 v52, 16, v40
	v_add_f32_e32 v38, 1.0, v38
	v_add_f32_e32 v35, 1.0, v35
	v_add_f32_e32 v46, 1.0, v46
	v_rcp_f32_e32 v38, v38
	v_rcp_f32_e32 v35, v35
	v_rcp_f32_e32 v46, v46
	v_and_b32_e32 v40, 0xffff0000, v40
	v_lshlrev_b32_e32 v56, 16, v36
	v_and_b32_e32 v36, 0xffff0000, v36
	v_mul_f32_e32 v38, v51, v38
	v_mul_f32_e32 v35, v39, v35
	v_fmac_f32_e32 v52, v42, v56
	v_fmac_f32_e32 v40, v43, v36
	v_mul_f32_e32 v46, v50, v46
	v_cvt_pk_bf16_f32 v34, v46, v34
	v_cvt_pk_bf16_f32 v35, v38, v35
	v_mul_f32_e32 v38, 0x3d372713, v52
	v_mul_f32_e32 v36, 0x3d372713, v40
	v_mul_f32_e32 v38, v52, v38
	v_mul_f32_e32 v36, v40, v36
	v_fma_f32 v38, v52, v38, v52
	v_fma_f32 v36, v40, v36, v40
	v_mul_f32_e32 v38, 0x3f4c422a, v38
	v_mul_f32_e32 v36, 0x3f4c422a, v36
	v_add_f32_e32 v38, v38, v38
	v_add_f32_e32 v36, v36, v36
	v_mul_f32_e32 v38, 0xbfb8aa3b, v38
	v_mul_f32_e32 v36, 0xbfb8aa3b, v36
	v_exp_f32_e32 v38, v38
	v_exp_f32_e32 v36, v36
	v_lshlrev_b32_e32 v53, 16, v41
	v_and_b32_e32 v41, 0xffff0000, v41
	v_add_f32_e32 v38, 1.0, v38
	v_add_f32_e32 v36, 1.0, v36
	v_rcp_f32_e32 v38, v38
	v_rcp_f32_e32 v36, v36
	v_lshlrev_b32_e32 v57, 16, v37
	v_and_b32_e32 v37, 0xffff0000, v37
	v_mul_f32_e32 v38, v52, v38
	v_mul_f32_e32 v36, v40, v36
	v_fmac_f32_e32 v53, v44, v57
	v_fmac_f32_e32 v41, v45, v37
	v_cvt_pk_bf16_f32 v36, v38, v36
	v_mul_f32_e32 v38, 0x3d372713, v53
	v_mul_f32_e32 v37, 0x3d372713, v41
	v_mul_f32_e32 v38, v53, v38
	v_mul_f32_e32 v37, v41, v37
	v_fma_f32 v38, v53, v38, v53
	v_fma_f32 v37, v41, v37, v41
	v_mul_f32_e32 v38, 0x3f4c422a, v38
	v_mul_f32_e32 v37, 0x3f4c422a, v37
	v_add_f32_e32 v38, v38, v38
	v_add_f32_e32 v37, v37, v37
	v_mul_f32_e32 v38, 0xbfb8aa3b, v38
	v_mul_f32_e32 v37, 0xbfb8aa3b, v37
	v_exp_f32_e32 v38, v38
	v_exp_f32_e32 v37, v37
	v_add_f32_e32 v38, 1.0, v38
	v_add_f32_e32 v37, 1.0, v37
	v_rcp_f32_e32 v38, v38
	v_rcp_f32_e32 v37, v37
	v_mul_f32_e32 v38, v53, v38
	v_mul_f32_e32 v37, v41, v37
	v_cvt_pk_bf16_f32 v37, v38, v37
	ds_read_b128 v[46:49], v246 offset:16
	ds_read_b128 v[50:53], v246
	s_waitcnt vmcnt(14) lgkmcnt(0)
	v_mov_b32_e32 v38, v222
	v_mov_b32_e32 v39, v223
	v_mov_b32_e32 v40, v224
	v_mov_b32_e32 v41, v225
	v_mov_b32_e32 v42, v226
	v_mov_b32_e32 v43, v227
	v_mov_b32_e32 v44, v228
	v_mov_b32_e32 v45, v229
	v_lshlrev_b32_e32 v58, 16, v42
	v_lshlrev_b32_e32 v54, 16, v38
	v_and_b32_e32 v38, 0xffff0000, v38
	v_and_b32_e32 v42, 0xffff0000, v42
	v_fmac_f32_e32 v38, v51, v42
	v_mul_f32_e32 v42, 0x3d372713, v38
	v_mul_f32_e32 v42, v38, v42
	v_fma_f32 v42, v38, v42, v38
	v_mul_f32_e32 v42, 0x3f4c422a, v42
	v_add_f32_e32 v42, v42, v42
	v_mul_f32_e32 v42, 0xbfb8aa3b, v42
	v_exp_f32_e32 v42, v42
	v_lshlrev_b32_e32 v55, 16, v39
	v_and_b32_e32 v39, 0xffff0000, v39
	v_lshlrev_b32_e32 v59, 16, v43
	v_add_f32_e32 v42, 1.0, v42
	v_rcp_f32_e32 v42, v42
	v_and_b32_e32 v43, 0xffff0000, v43
	v_fmac_f32_e32 v55, v52, v59
	v_fmac_f32_e32 v39, v53, v43
	v_fmac_f32_e32 v54, v50, v58
	v_mul_f32_e32 v38, v38, v42
	v_mul_f32_e32 v42, 0x3d372713, v55
	v_mul_f32_e32 v43, 0x3d372713, v39
	v_mul_f32_e32 v50, 0x3d372713, v54
	v_mul_f32_e32 v42, v55, v42
	v_mul_f32_e32 v43, v39, v43
	v_mul_f32_e32 v50, v54, v50
	v_fma_f32 v42, v55, v42, v55
	v_fma_f32 v43, v39, v43, v39
	v_fma_f32 v50, v54, v50, v54
	v_mul_f32_e32 v42, 0x3f4c422a, v42
	v_mul_f32_e32 v43, 0x3f4c422a, v43
	v_mul_f32_e32 v50, 0x3f4c422a, v50
	v_add_f32_e32 v42, v42, v42
	v_add_f32_e32 v43, v43, v43
	v_add_f32_e32 v50, v50, v50
	v_mul_f32_e32 v42, 0xbfb8aa3b, v42
	v_mul_f32_e32 v43, 0xbfb8aa3b, v43
	v_mul_f32_e32 v50, 0xbfb8aa3b, v50
	v_exp_f32_e32 v42, v42
	v_exp_f32_e32 v43, v43
	v_exp_f32_e32 v50, v50
	v_lshlrev_b32_e32 v56, 16, v40
	v_add_f32_e32 v42, 1.0, v42
	v_add_f32_e32 v43, 1.0, v43
	v_add_f32_e32 v50, 1.0, v50
	v_rcp_f32_e32 v42, v42
	v_rcp_f32_e32 v43, v43
	v_rcp_f32_e32 v50, v50
	v_and_b32_e32 v40, 0xffff0000, v40
	v_lshlrev_b32_e32 v60, 16, v44
	v_and_b32_e32 v44, 0xffff0000, v44
	v_mul_f32_e32 v42, v55, v42
	v_mul_f32_e32 v39, v39, v43
	v_fmac_f32_e32 v56, v46, v60
	v_fmac_f32_e32 v40, v47, v44
	v_mul_f32_e32 v50, v54, v50
; __device__ __forceinline__ unsigned cvt_pk_bf16(float lo, float hi) { unsigned r; asm volatile("v_cvt_pk_bf16_f32 %0, %1, %2" : "=v"(r) : "v"(lo), "v"(hi)); return r; }
; __device__ __forceinline__ float gelu_tanh(float x) { const float u = 0.7978845608028654f * (x + 0.044715f * x * x * x); return x * sigm(2.f * u); }
; #define UNPK8(VV_, XX_) float XX_[8] = {bflo((VV_).x), bfhi((VV_).x), bflo((VV_).y), bfhi((VV_).y), bflo((VV_).z), bfhi((VV_).z), bflo((VV_).w), bfhi((VV_).w)}
; __device__ __forceinline__ void glu_task(int t, int l, const float* s5d, const bf16_t* P, const bf16_t* YB, const bf16_t* WGLU, bf16_t* Z1, int fr, int fq) {
;     ...
;     for (int tb = 0; tb < 2; ++tb) { const size_t row = row0 + tb * 16;
; #pragma unroll
;         for (int ks = 0; ks < 8; ++ks) { const int k0 = ks * 32 + fq * 8; const u32x4 yw = ld8(YB + row * 256 + k0), uw = ld8(P + row * INP + OFF_S5 + k0);
;             const f32x4 d0 = *(const f32x4*)(s5d + l * 256 + k0), d1 = *(const f32x4*)(s5d + l * 256 + k0 + 4); UNPK8(yw, y); UNPK8(uw, u); u32x4 o;
;             o.x = cvt_pk_bf16(gelu_tanh(y[0] + d0[0] * u[0]), gelu_tanh(y[1] + d0[1] * u[1])); o.y = cvt_pk_bf16(gelu_tanh(y[2] + d0[2] * u[2]), gelu_tanh(y[3] + d0[3] * u[3]));
;             o.z = cvt_pk_bf16(gelu_tanh(y[4] + d1[0] * u[4]), gelu_tanh(y[5] + d1[1] * u[5])); o.w = cvt_pk_bf16(gelu_tanh(y[6] + d1[2] * u[6]), gelu_tanh(y[7] + d1[3] * u[7]));
;             bfr[tb][ks] = asfrag(o); } }
	v_cvt_pk_bf16_f32 v38, v50, v38
	v_cvt_pk_bf16_f32 v39, v42, v39
	v_mul_f32_e32 v42, 0x3d372713, v56
	v_mul_f32_e32 v43, 0x3d372713, v40
	v_mul_f32_e32 v42, v56, v42
	v_mul_f32_e32 v43, v40, v43
	v_fma_f32 v42, v56, v42, v56
	v_fma_f32 v43, v40, v43, v40
	v_mul_f32_e32 v42, 0x3f4c422a, v42
	v_mul_f32_e32 v43, 0x3f4c422a, v43
	v_add_f32_e32 v42, v42, v42
	v_add_f32_e32 v43, v43, v43
	v_mul_f32_e32 v42, 0xbfb8aa3b, v42
	v_mul_f32_e32 v43, 0xbfb8aa3b, v43
	v_exp_f32_e32 v42, v42
	v_exp_f32_e32 v43, v43
	v_lshlrev_b32_e32 v57, 16, v41
	v_and_b32_e32 v41, 0xffff0000, v41
	v_add_f32_e32 v42, 1.0, v42
	v_add_f32_e32 v43, 1.0, v43
	v_rcp_f32_e32 v42, v42
	v_rcp_f32_e32 v43, v43
	v_lshlrev_b32_e32 v61, 16, v45
	v_and_b32_e32 v45, 0xffff0000, v45
	v_mul_f32_e32 v42, v56, v42
	v_mul_f32_e32 v40, v40, v43
	v_fmac_f32_e32 v57, v48, v61
	v_fmac_f32_e32 v41, v49, v45
	v_cvt_pk_bf16_f32 v40, v42, v40
	v_mul_f32_e32 v42, 0x3d372713, v57
	v_mul_f32_e32 v43, 0x3d372713, v41
	v_mul_f32_e32 v42, v57, v42
	v_mul_f32_e32 v43, v41, v43
	v_fma_f32 v42, v57, v42, v57
	v_fma_f32 v43, v41, v43, v41
	v_mul_f32_e32 v42, 0x3f4c422a, v42
	v_mul_f32_e32 v43, 0x3f4c422a, v43
	v_add_f32_e32 v42, v42, v42
	v_add_f32_e32 v43, v43, v43
	v_mul_f32_e32 v42, 0xbfb8aa3b, v42
	v_mul_f32_e32 v43, 0xbfb8aa3b, v43
	v_exp_f32_e32 v42, v42
	v_exp_f32_e32 v43, v43
	v_add_f32_e32 v42, 1.0, v42
	v_add_f32_e32 v43, 1.0, v43
	v_rcp_f32_e32 v42, v42
	v_rcp_f32_e32 v43, v43
	v_mul_f32_e32 v42, v57, v42
	v_mul_f32_e32 v41, v41, v43
	v_cvt_pk_bf16_f32 v41, v42, v41
	ds_read_b128 v[50:53], v246 offset:144
	ds_read_b128 v[54:57], v246 offset:128
	s_waitcnt vmcnt(12) lgkmcnt(0)
	v_mov_b32_e32 v42, v230
	v_mov_b32_e32 v43, v231
	v_mov_b32_e32 v44, v232
	v_mov_b32_e32 v45, v233
	v_mov_b32_e32 v46, v234
	v_mov_b32_e32 v47, v235
	v_mov_b32_e32 v48, v236
	v_mov_b32_e32 v49, v237
	v_lshlrev_b32_e32 v58, 16, v42
	v_and_b32_e32 v42, 0xffff0000, v42
	v_lshlrev_b32_e32 v62, 16, v46
	v_and_b32_e32 v46, 0xffff0000, v46
	v_fmac_f32_e32 v42, v55, v46
	v_mul_f32_e32 v46, 0x3d372713, v42
	v_mul_f32_e32 v46, v42, v46
	v_fma_f32 v46, v42, v46, v42
	v_mul_f32_e32 v46, 0x3f4c422a, v46
	v_add_f32_e32 v46, v46, v46
	v_mul_f32_e32 v46, 0xbfb8aa3b, v46
	v_exp_f32_e32 v46, v46
	v_lshlrev_b32_e32 v59, 16, v43
	v_and_b32_e32 v43, 0xffff0000, v43
	v_lshlrev_b32_e32 v63, 16, v47
	v_add_f32_e32 v46, 1.0, v46
	v_rcp_f32_e32 v46, v46
	v_and_b32_e32 v47, 0xffff0000, v47
	v_fmac_f32_e32 v59, v56, v63
	v_fmac_f32_e32 v43, v57, v47
	v_fmac_f32_e32 v58, v54, v62
	v_mul_f32_e32 v42, v42, v46
	v_mul_f32_e32 v46, 0x3d372713, v59
	v_mul_f32_e32 v47, 0x3d372713, v43
	v_mul_f32_e32 v54, 0x3d372713, v58
	v_mul_f32_e32 v46, v59, v46
	v_mul_f32_e32 v47, v43, v47
	v_mul_f32_e32 v54, v58, v54
	v_fma_f32 v46, v59, v46, v59
	v_fma_f32 v47, v43, v47, v43
	v_fma_f32 v54, v58, v54, v58
	v_mul_f32_e32 v46, 0x3f4c422a, v46
	v_mul_f32_e32 v47, 0x3f4c422a, v47
	v_mul_f32_e32 v54, 0x3f4c422a, v54
	v_add_f32_e32 v46, v46, v46
	v_add_f32_e32 v47, v47, v47
	v_add_f32_e32 v54, v54, v54
	v_mul_f32_e32 v46, 0xbfb8aa3b, v46
	v_mul_f32_e32 v47, 0xbfb8aa3b, v47
	v_mul_f32_e32 v54, 0xbfb8aa3b, v54
	v_exp_f32_e32 v46, v46
	v_exp_f32_e32 v47, v47
	v_exp_f32_e32 v54, v54
	v_lshlrev_b32_e32 v60, 16, v44
	v_add_f32_e32 v46, 1.0, v46
	v_add_f32_e32 v47, 1.0, v47
	v_add_f32_e32 v54, 1.0, v54
	v_rcp_f32_e32 v46, v46
	v_rcp_f32_e32 v47, v47
	v_rcp_f32_e32 v54, v54
	v_and_b32_e32 v44, 0xffff0000, v44
	v_lshlrev_b32_e32 v64, 16, v48
	v_and_b32_e32 v48, 0xffff0000, v48
	v_mul_f32_e32 v46, v59, v46
	v_mul_f32_e32 v43, v43, v47
	v_fmac_f32_e32 v60, v50, v64
	v_fmac_f32_e32 v44, v51, v48
	v_mul_f32_e32 v54, v58, v54
	v_cvt_pk_bf16_f32 v42, v54, v42
	v_cvt_pk_bf16_f32 v43, v46, v43
	v_mul_f32_e32 v46, 0x3d372713, v60
	v_mul_f32_e32 v47, 0x3d372713, v44
	v_mul_f32_e32 v46, v60, v46
	v_mul_f32_e32 v47, v44, v47
	v_fma_f32 v46, v60, v46, v60
	v_fma_f32 v47, v44, v47, v44
	v_mul_f32_e32 v46, 0x3f4c422a, v46
	v_mul_f32_e32 v47, 0x3f4c422a, v47
	v_add_f32_e32 v46, v46, v46
	v_add_f32_e32 v47, v47, v47
	v_mul_f32_e32 v46, 0xbfb8aa3b, v46
	v_mul_f32_e32 v47, 0xbfb8aa3b, v47
	v_exp_f32_e32 v46, v46
	v_exp_f32_e32 v47, v47
	v_lshlrev_b32_e32 v61, 16, v45
	v_and_b32_e32 v45, 0xffff0000, v45
	v_add_f32_e32 v46, 1.0, v46
	v_add_f32_e32 v47, 1.0, v47
	v_rcp_f32_e32 v46, v46
	v_rcp_f32_e32 v47, v47
	v_lshlrev_b32_e32 v65, 16, v49
	v_and_b32_e32 v49, 0xffff0000, v49
	v_mul_f32_e32 v46, v60, v46
	v_mul_f32_e32 v44, v44, v47
	v_fmac_f32_e32 v61, v52, v65
	v_fmac_f32_e32 v45, v53, v49
	v_cvt_pk_bf16_f32 v44, v46, v44
	v_mul_f32_e32 v46, 0x3d372713, v61
	v_mul_f32_e32 v47, 0x3d372713, v45
	v_mul_f32_e32 v46, v61, v46
	v_mul_f32_e32 v47, v45, v47
	v_fma_f32 v46, v61, v46, v61
	v_fma_f32 v47, v45, v47, v45
	v_mul_f32_e32 v46, 0x3f4c422a, v46
	v_mul_f32_e32 v47, 0x3f4c422a, v47
	v_add_f32_e32 v46, v46, v46
	v_add_f32_e32 v47, v47, v47
	v_mul_f32_e32 v46, 0xbfb8aa3b, v46
	v_mul_f32_e32 v47, 0xbfb8aa3b, v47
	v_exp_f32_e32 v46, v46
	v_exp_f32_e32 v47, v47
	v_add_f32_e32 v46, 1.0, v46
	v_add_f32_e32 v47, 1.0, v47
	v_rcp_f32_e32 v46, v46
	v_rcp_f32_e32 v47, v47
	v_mul_f32_e32 v46, v61, v46
	v_mul_f32_e32 v45, v45, v47
	v_cvt_pk_bf16_f32 v45, v46, v45
	ds_read_b128 v[54:57], v246 offset:272
	ds_read_b128 v[58:61], v246 offset:256
	s_waitcnt vmcnt(10) lgkmcnt(0)
; __device__ __forceinline__ unsigned cvt_pk_bf16(float lo, float hi) { unsigned r; asm volatile("v_cvt_pk_bf16_f32 %0, %1, %2" : "=v"(r) : "v"(lo), "v"(hi)); return r; }
; __device__ __forceinline__ float gelu_tanh(float x) { const float u = 0.7978845608028654f * (x + 0.044715f * x * x * x); return x * sigm(2.f * u); }
; #define UNPK8(VV_, XX_) float XX_[8] = {bflo((VV_).x), bfhi((VV_).x), bflo((VV_).y), bfhi((VV_).y), bflo((VV_).z), bfhi((VV_).z), bflo((VV_).w), bfhi((VV_).w)}
; __device__ __forceinline__ void glu_task(int t, int l, const float* s5d, const bf16_t* P, const bf16_t* YB, const bf16_t* WGLU, bf16_t* Z1, int fr, int fq) {
;     ...
;     for (int tb = 0; tb < 2; ++tb) { const size_t row = row0 + tb * 16;
; #pragma unroll
;         for (int ks = 0; ks < 8; ++ks) { const int k0 = ks * 32 + fq * 8; const u32x4 yw = ld8(YB + row * 256 + k0), uw = ld8(P + row * INP + OFF_S5 + k0);
;             const f32x4 d0 = *(const f32x4*)(s5d + l * 256 + k0), d1 = *(const f32x4*)(s5d + l * 256 + k0 + 4); UNPK8(yw, y); UNPK8(uw, u); u32x4 o;
;             o.x = cvt_pk_bf16(gelu_tanh(y[0] + d0[0] * u[0]), gelu_tanh(y[1] + d0[1] * u[1])); o.y = cvt_pk_bf16(gelu_tanh(y[2] + d0[2] * u[2]), gelu_tanh(y[3] + d0[3] * u[3]));
;             o.z = cvt_pk_bf16(gelu_tanh(y[4] + d1[0] * u[4]), gelu_tanh(y[5] + d1[1] * u[5])); o.w = cvt_pk_bf16(gelu_tanh(y[6] + d1[2] * u[6]), gelu_tanh(y[7] + d1[3] * u[7]));
;             bfr[tb][ks] = asfrag(o); } }
	v_mov_b32_e32 v46, v238
	v_mov_b32_e32 v47, v239
	v_mov_b32_e32 v48, v240
	v_mov_b32_e32 v49, v241
	v_mov_b32_e32 v50, v242
	v_mov_b32_e32 v51, v243
	v_mov_b32_e32 v52, v244
	v_mov_b32_e32 v53, v245
	v_lshlrev_b32_e32 v62, 16, v46
	v_and_b32_e32 v46, 0xffff0000, v46
	v_lshlrev_b32_e32 v78, 16, v50
	v_and_b32_e32 v50, 0xffff0000, v50
	v_fmac_f32_e32 v46, v59, v50
	v_mul_f32_e32 v50, 0x3d372713, v46
	v_mul_f32_e32 v50, v46, v50
	v_fma_f32 v50, v46, v50, v46
	v_mul_f32_e32 v50, 0x3f4c422a, v50
	v_add_f32_e32 v50, v50, v50
	v_mul_f32_e32 v50, 0xbfb8aa3b, v50
	v_exp_f32_e32 v50, v50
	v_lshlrev_b32_e32 v63, 16, v47
	v_and_b32_e32 v47, 0xffff0000, v47
	v_lshlrev_b32_e32 v79, 16, v51
	v_add_f32_e32 v50, 1.0, v50
	v_rcp_f32_e32 v50, v50
	v_and_b32_e32 v51, 0xffff0000, v51
	v_fmac_f32_e32 v63, v60, v79
	v_fmac_f32_e32 v47, v61, v51
	v_fmac_f32_e32 v62, v58, v78
	v_mul_f32_e32 v46, v46, v50
	v_mul_f32_e32 v50, 0x3d372713, v63
	v_mul_f32_e32 v51, 0x3d372713, v47
	v_mul_f32_e32 v58, 0x3d372713, v62
	v_mul_f32_e32 v50, v63, v50
	v_mul_f32_e32 v51, v47, v51
	v_mul_f32_e32 v58, v62, v58
	v_fma_f32 v50, v63, v50, v63
	v_fma_f32 v51, v47, v51, v47
	v_fma_f32 v58, v62, v58, v62
	v_mul_f32_e32 v50, 0x3f4c422a, v50
	v_mul_f32_e32 v51, 0x3f4c422a, v51
	v_mul_f32_e32 v58, 0x3f4c422a, v58
	v_add_f32_e32 v50, v50, v50
	v_add_f32_e32 v51, v51, v51
	v_add_f32_e32 v58, v58, v58
	v_mul_f32_e32 v50, 0xbfb8aa3b, v50
	v_mul_f32_e32 v51, 0xbfb8aa3b, v51
	v_mul_f32_e32 v58, 0xbfb8aa3b, v58
	v_exp_f32_e32 v50, v50
	v_exp_f32_e32 v51, v51
	v_exp_f32_e32 v58, v58
	v_lshlrev_b32_e32 v64, 16, v48
	v_add_f32_e32 v50, 1.0, v50
	v_add_f32_e32 v51, 1.0, v51
	v_add_f32_e32 v58, 1.0, v58
	v_rcp_f32_e32 v50, v50
	v_rcp_f32_e32 v51, v51
	v_rcp_f32_e32 v58, v58
	v_and_b32_e32 v48, 0xffff0000, v48
	v_lshlrev_b32_e32 v80, 16, v52
	v_and_b32_e32 v52, 0xffff0000, v52
	v_mul_f32_e32 v50, v63, v50
	v_mul_f32_e32 v47, v47, v51
	v_fmac_f32_e32 v64, v54, v80
	v_fmac_f32_e32 v48, v55, v52
	v_mul_f32_e32 v58, v62, v58
	v_cvt_pk_bf16_f32 v46, v58, v46
	v_cvt_pk_bf16_f32 v47, v50, v47
	v_mul_f32_e32 v50, 0x3d372713, v64
	v_mul_f32_e32 v51, 0x3d372713, v48
	v_mul_f32_e32 v50, v64, v50
	v_mul_f32_e32 v51, v48, v51
	v_fma_f32 v50, v64, v50, v64
	v_fma_f32 v51, v48, v51, v48
	v_mul_f32_e32 v50, 0x3f4c422a, v50
	v_mul_f32_e32 v51, 0x3f4c422a, v51
	v_add_f32_e32 v50, v50, v50
	v_add_f32_e32 v51, v51, v51
	v_mul_f32_e32 v50, 0xbfb8aa3b, v50
	v_mul_f32_e32 v51, 0xbfb8aa3b, v51
	v_exp_f32_e32 v50, v50
	v_exp_f32_e32 v51, v51
	v_lshlrev_b32_e32 v65, 16, v49
	v_and_b32_e32 v49, 0xffff0000, v49
	v_add_f32_e32 v50, 1.0, v50
	v_add_f32_e32 v51, 1.0, v51
	v_rcp_f32_e32 v50, v50
	v_rcp_f32_e32 v51, v51
	v_lshlrev_b32_e32 v81, 16, v53
	v_and_b32_e32 v53, 0xffff0000, v53
	v_mul_f32_e32 v50, v64, v50
	v_mul_f32_e32 v48, v48, v51
	v_fmac_f32_e32 v65, v56, v81
	v_fmac_f32_e32 v49, v57, v53
	v_cvt_pk_bf16_f32 v48, v50, v48
	v_mul_f32_e32 v50, 0x3d372713, v65
	v_mul_f32_e32 v51, 0x3d372713, v49
	v_mul_f32_e32 v50, v65, v50
	v_mul_f32_e32 v51, v49, v51
	v_fma_f32 v50, v65, v50, v65
	v_fma_f32 v51, v49, v51, v49
	v_mul_f32_e32 v50, 0x3f4c422a, v50
	v_mul_f32_e32 v51, 0x3f4c422a, v51
	v_add_f32_e32 v50, v50, v50
	v_add_f32_e32 v51, v51, v51
	v_mul_f32_e32 v50, 0xbfb8aa3b, v50
	v_mul_f32_e32 v51, 0xbfb8aa3b, v51
	v_exp_f32_e32 v50, v50
	v_exp_f32_e32 v51, v51
	v_add_f32_e32 v50, 1.0, v50
	v_add_f32_e32 v51, 1.0, v51
	v_rcp_f32_e32 v50, v50
	v_rcp_f32_e32 v51, v51
	v_mul_f32_e32 v50, v65, v50
	v_mul_f32_e32 v49, v49, v51
	v_cvt_pk_bf16_f32 v49, v50, v49
	ds_read_b128 v[58:61], v246 offset:400
	ds_read_b128 v[62:65], v246 offset:384
	s_waitcnt vmcnt(8) lgkmcnt(0)
	v_mov_b32_e32 v50, v168
	v_mov_b32_e32 v51, v169
	v_mov_b32_e32 v52, v170
	v_mov_b32_e32 v53, v171
	v_mov_b32_e32 v54, v188
	v_mov_b32_e32 v55, v189
	v_mov_b32_e32 v56, v190
	v_mov_b32_e32 v57, v191
	v_lshlrev_b32_e32 v78, 16, v50
	v_and_b32_e32 v50, 0xffff0000, v50
	v_lshlrev_b32_e32 v82, 16, v54
	v_and_b32_e32 v54, 0xffff0000, v54
	v_fmac_f32_e32 v50, v63, v54
	v_mul_f32_e32 v54, 0x3d372713, v50
	v_mul_f32_e32 v54, v50, v54
	v_fma_f32 v54, v50, v54, v50
	v_mul_f32_e32 v54, 0x3f4c422a, v54
	v_add_f32_e32 v54, v54, v54
	v_mul_f32_e32 v54, 0xbfb8aa3b, v54
	v_exp_f32_e32 v54, v54
	v_lshlrev_b32_e32 v79, 16, v51
	v_and_b32_e32 v51, 0xffff0000, v51
	v_lshlrev_b32_e32 v83, 16, v55
	v_add_f32_e32 v54, 1.0, v54
	v_rcp_f32_e32 v54, v54
	v_and_b32_e32 v55, 0xffff0000, v55
	v_fmac_f32_e32 v79, v64, v83
	v_fmac_f32_e32 v51, v65, v55
	v_fmac_f32_e32 v78, v62, v82
	v_mul_f32_e32 v50, v50, v54
	v_mul_f32_e32 v54, 0x3d372713, v79
	v_mul_f32_e32 v55, 0x3d372713, v51
	v_mul_f32_e32 v62, 0x3d372713, v78
	v_mul_f32_e32 v54, v79, v54
	v_mul_f32_e32 v55, v51, v55
	v_mul_f32_e32 v62, v78, v62
	v_fma_f32 v54, v79, v54, v79
	v_fma_f32 v55, v51, v55, v51
	v_fma_f32 v62, v78, v62, v78
	v_mul_f32_e32 v54, 0x3f4c422a, v54
	v_mul_f32_e32 v55, 0x3f4c422a, v55
	v_mul_f32_e32 v62, 0x3f4c422a, v62
	v_add_f32_e32 v54, v54, v54
	v_add_f32_e32 v55, v55, v55
	v_add_f32_e32 v62, v62, v62
	v_mul_f32_e32 v54, 0xbfb8aa3b, v54
	v_mul_f32_e32 v55, 0xbfb8aa3b, v55
	v_mul_f32_e32 v62, 0xbfb8aa3b, v62
	v_exp_f32_e32 v54, v54
	v_exp_f32_e32 v55, v55
	v_exp_f32_e32 v62, v62
	v_lshlrev_b32_e32 v80, 16, v52
	v_add_f32_e32 v54, 1.0, v54
	v_add_f32_e32 v55, 1.0, v55
	v_add_f32_e32 v62, 1.0, v62
	v_rcp_f32_e32 v54, v54
	v_rcp_f32_e32 v55, v55
	v_rcp_f32_e32 v62, v62
	v_and_b32_e32 v52, 0xffff0000, v52
	v_lshlrev_b32_e32 v84, 16, v56
	v_and_b32_e32 v56, 0xffff0000, v56
	v_mul_f32_e32 v54, v79, v54
	v_mul_f32_e32 v51, v51, v55
	v_fmac_f32_e32 v80, v58, v84
	v_fmac_f32_e32 v52, v59, v56
	v_mul_f32_e32 v62, v78, v62
; __device__ __forceinline__ unsigned cvt_pk_bf16(float lo, float hi) { unsigned r; asm volatile("v_cvt_pk_bf16_f32 %0, %1, %2" : "=v"(r) : "v"(lo), "v"(hi)); return r; }
; __device__ __forceinline__ float gelu_tanh(float x) { const float u = 0.7978845608028654f * (x + 0.044715f * x * x * x); return x * sigm(2.f * u); }
; #define UNPK8(VV_, XX_) float XX_[8] = {bflo((VV_).x), bfhi((VV_).x), bflo((VV_).y), bfhi((VV_).y), bflo((VV_).z), bfhi((VV_).z), bflo((VV_).w), bfhi((VV_).w)}
; __device__ __forceinline__ void glu_task(int t, int l, const float* s5d, const bf16_t* P, const bf16_t* YB, const bf16_t* WGLU, bf16_t* Z1, int fr, int fq) {
;     ...
;     for (int tb = 0; tb < 2; ++tb) { const size_t row = row0 + tb * 16;
; #pragma unroll
;         for (int ks = 0; ks < 8; ++ks) { const int k0 = ks * 32 + fq * 8; const u32x4 yw = ld8(YB + row * 256 + k0), uw = ld8(P + row * INP + OFF_S5 + k0);
;             const f32x4 d0 = *(const f32x4*)(s5d + l * 256 + k0), d1 = *(const f32x4*)(s5d + l * 256 + k0 + 4); UNPK8(yw, y); UNPK8(uw, u); u32x4 o;
;             o.x = cvt_pk_bf16(gelu_tanh(y[0] + d0[0] * u[0]), gelu_tanh(y[1] + d0[1] * u[1])); o.y = cvt_pk_bf16(gelu_tanh(y[2] + d0[2] * u[2]), gelu_tanh(y[3] + d0[3] * u[3]));
;             o.z = cvt_pk_bf16(gelu_tanh(y[4] + d1[0] * u[4]), gelu_tanh(y[5] + d1[1] * u[5])); o.w = cvt_pk_bf16(gelu_tanh(y[6] + d1[2] * u[6]), gelu_tanh(y[7] + d1[3] * u[7]));
;             bfr[tb][ks] = asfrag(o); } }
	v_cvt_pk_bf16_f32 v50, v62, v50
	v_cvt_pk_bf16_f32 v51, v54, v51
	v_mul_f32_e32 v54, 0x3d372713, v80
	v_mul_f32_e32 v55, 0x3d372713, v52
	v_mul_f32_e32 v54, v80, v54
	v_mul_f32_e32 v55, v52, v55
	v_fma_f32 v54, v80, v54, v80
	v_fma_f32 v55, v52, v55, v52
	v_mul_f32_e32 v54, 0x3f4c422a, v54
	v_mul_f32_e32 v55, 0x3f4c422a, v55
	v_add_f32_e32 v54, v54, v54
	v_add_f32_e32 v55, v55, v55
	v_mul_f32_e32 v54, 0xbfb8aa3b, v54
	v_mul_f32_e32 v55, 0xbfb8aa3b, v55
	v_exp_f32_e32 v54, v54
	v_exp_f32_e32 v55, v55
	v_lshlrev_b32_e32 v81, 16, v53
	v_and_b32_e32 v53, 0xffff0000, v53
	v_add_f32_e32 v54, 1.0, v54
	v_add_f32_e32 v55, 1.0, v55
	v_rcp_f32_e32 v54, v54
	v_rcp_f32_e32 v55, v55
	v_lshlrev_b32_e32 v85, 16, v57
	v_and_b32_e32 v57, 0xffff0000, v57
	v_mul_f32_e32 v54, v80, v54
	v_mul_f32_e32 v52, v52, v55
	v_fmac_f32_e32 v81, v60, v85
	v_fmac_f32_e32 v53, v61, v57
	v_cvt_pk_bf16_f32 v52, v54, v52
	v_mul_f32_e32 v54, 0x3d372713, v81
	v_mul_f32_e32 v55, 0x3d372713, v53
	v_mul_f32_e32 v54, v81, v54
	v_mul_f32_e32 v55, v53, v55
	v_fma_f32 v54, v81, v54, v81
	v_fma_f32 v55, v53, v55, v53
	v_mul_f32_e32 v54, 0x3f4c422a, v54
	v_mul_f32_e32 v55, 0x3f4c422a, v55
	v_add_f32_e32 v54, v54, v54
	v_add_f32_e32 v55, v55, v55
	v_mul_f32_e32 v54, 0xbfb8aa3b, v54
	v_mul_f32_e32 v55, 0xbfb8aa3b, v55
	v_exp_f32_e32 v54, v54
	v_exp_f32_e32 v55, v55
	v_add_f32_e32 v54, 1.0, v54
	v_add_f32_e32 v55, 1.0, v55
	v_rcp_f32_e32 v54, v54
	v_rcp_f32_e32 v55, v55
	v_mul_f32_e32 v54, v81, v54
	v_mul_f32_e32 v53, v53, v55
	v_cvt_pk_bf16_f32 v53, v54, v53
	ds_read_b128 v[62:65], v246 offset:528
	ds_read_b128 v[78:81], v246 offset:512
	s_waitcnt vmcnt(6) lgkmcnt(0)
	v_mov_b32_e32 v54, v98
	v_mov_b32_e32 v55, v99
	v_mov_b32_e32 v56, v100
	v_mov_b32_e32 v57, v101
	v_mov_b32_e32 v58, v102
	v_mov_b32_e32 v59, v103
	v_mov_b32_e32 v60, v104
	v_mov_b32_e32 v61, v105
	v_lshlrev_b32_e32 v82, 16, v54
	v_and_b32_e32 v54, 0xffff0000, v54
	v_lshlrev_b32_e32 v86, 16, v58
	v_and_b32_e32 v58, 0xffff0000, v58
	v_fmac_f32_e32 v54, v79, v58
	v_mul_f32_e32 v58, 0x3d372713, v54
	v_mul_f32_e32 v58, v54, v58
	v_fma_f32 v58, v54, v58, v54
	v_mul_f32_e32 v58, 0x3f4c422a, v58
	v_add_f32_e32 v58, v58, v58
	v_mul_f32_e32 v58, 0xbfb8aa3b, v58
	v_exp_f32_e32 v58, v58
	v_lshlrev_b32_e32 v83, 16, v55
	v_and_b32_e32 v55, 0xffff0000, v55
	v_lshlrev_b32_e32 v87, 16, v59
	v_add_f32_e32 v58, 1.0, v58
	v_rcp_f32_e32 v58, v58
	v_and_b32_e32 v59, 0xffff0000, v59
	v_fmac_f32_e32 v83, v80, v87
	v_fmac_f32_e32 v55, v81, v59
	v_fmac_f32_e32 v82, v78, v86
	v_mul_f32_e32 v54, v54, v58
	v_mul_f32_e32 v58, 0x3d372713, v83
	v_mul_f32_e32 v59, 0x3d372713, v55
	v_mul_f32_e32 v78, 0x3d372713, v82
	v_mul_f32_e32 v58, v83, v58
	v_mul_f32_e32 v59, v55, v59
	v_mul_f32_e32 v78, v82, v78
	v_fma_f32 v58, v83, v58, v83
	v_fma_f32 v59, v55, v59, v55
	v_fma_f32 v78, v82, v78, v82
	v_mul_f32_e32 v58, 0x3f4c422a, v58
	v_mul_f32_e32 v59, 0x3f4c422a, v59
	v_mul_f32_e32 v78, 0x3f4c422a, v78
	v_add_f32_e32 v58, v58, v58
	v_add_f32_e32 v59, v59, v59
	v_add_f32_e32 v78, v78, v78
	v_mul_f32_e32 v58, 0xbfb8aa3b, v58
	v_mul_f32_e32 v59, 0xbfb8aa3b, v59
	v_mul_f32_e32 v78, 0xbfb8aa3b, v78
	v_exp_f32_e32 v58, v58
	v_exp_f32_e32 v59, v59
	v_exp_f32_e32 v78, v78
	v_lshlrev_b32_e32 v84, 16, v56
	v_add_f32_e32 v58, 1.0, v58
	v_add_f32_e32 v59, 1.0, v59
	v_add_f32_e32 v78, 1.0, v78
	v_rcp_f32_e32 v58, v58
	v_rcp_f32_e32 v59, v59
	v_rcp_f32_e32 v78, v78
	v_and_b32_e32 v56, 0xffff0000, v56
	v_lshlrev_b32_e32 v88, 16, v60
	v_and_b32_e32 v60, 0xffff0000, v60
	v_mul_f32_e32 v58, v83, v58
	v_mul_f32_e32 v55, v55, v59
	v_fmac_f32_e32 v84, v62, v88
	v_fmac_f32_e32 v56, v63, v60
	v_mul_f32_e32 v78, v82, v78
	v_cvt_pk_bf16_f32 v54, v78, v54
	v_cvt_pk_bf16_f32 v55, v58, v55
	v_mul_f32_e32 v58, 0x3d372713, v84
	v_mul_f32_e32 v59, 0x3d372713, v56
	v_mul_f32_e32 v58, v84, v58
	v_mul_f32_e32 v59, v56, v59
	v_fma_f32 v58, v84, v58, v84
	v_fma_f32 v59, v56, v59, v56
	v_mul_f32_e32 v58, 0x3f4c422a, v58
	v_mul_f32_e32 v59, 0x3f4c422a, v59
	v_add_f32_e32 v58, v58, v58
	v_add_f32_e32 v59, v59, v59
	v_mul_f32_e32 v58, 0xbfb8aa3b, v58
	v_mul_f32_e32 v59, 0xbfb8aa3b, v59
	v_exp_f32_e32 v58, v58
	v_exp_f32_e32 v59, v59
	v_lshlrev_b32_e32 v85, 16, v57
	v_and_b32_e32 v57, 0xffff0000, v57
	v_add_f32_e32 v58, 1.0, v58
	v_add_f32_e32 v59, 1.0, v59
	v_rcp_f32_e32 v58, v58
	v_rcp_f32_e32 v59, v59
	v_lshlrev_b32_e32 v89, 16, v61
	v_and_b32_e32 v61, 0xffff0000, v61
	v_mul_f32_e32 v58, v84, v58
	v_mul_f32_e32 v56, v56, v59
	v_fmac_f32_e32 v85, v64, v89
	v_fmac_f32_e32 v57, v65, v61
	v_cvt_pk_bf16_f32 v56, v58, v56
	v_mul_f32_e32 v58, 0x3d372713, v85
	v_mul_f32_e32 v59, 0x3d372713, v57
	v_mul_f32_e32 v58, v85, v58
	v_mul_f32_e32 v59, v57, v59
	v_fma_f32 v58, v85, v58, v85
	v_fma_f32 v59, v57, v59, v57
	v_mul_f32_e32 v58, 0x3f4c422a, v58
	v_mul_f32_e32 v59, 0x3f4c422a, v59
	v_add_f32_e32 v58, v58, v58
	v_add_f32_e32 v59, v59, v59
	v_mul_f32_e32 v58, 0xbfb8aa3b, v58
	v_mul_f32_e32 v59, 0xbfb8aa3b, v59
	v_exp_f32_e32 v58, v58
	v_exp_f32_e32 v59, v59
	v_add_f32_e32 v58, 1.0, v58
	v_add_f32_e32 v59, 1.0, v59
	v_rcp_f32_e32 v58, v58
	v_rcp_f32_e32 v59, v59
	v_mul_f32_e32 v58, v85, v58
	v_mul_f32_e32 v57, v57, v59
	v_cvt_pk_bf16_f32 v57, v58, v57
	ds_read_b128 v[78:81], v246 offset:656
	ds_read_b128 v[82:85], v246 offset:640
	s_waitcnt vmcnt(4) lgkmcnt(0)
; __device__ __forceinline__ unsigned cvt_pk_bf16(float lo, float hi) { unsigned r; asm volatile("v_cvt_pk_bf16_f32 %0, %1, %2" : "=v"(r) : "v"(lo), "v"(hi)); return r; }
; __device__ __forceinline__ float gelu_tanh(float x) { const float u = 0.7978845608028654f * (x + 0.044715f * x * x * x); return x * sigm(2.f * u); }
; #define UNPK8(VV_, XX_) float XX_[8] = {bflo((VV_).x), bfhi((VV_).x), bflo((VV_).y), bfhi((VV_).y), bflo((VV_).z), bfhi((VV_).z), bflo((VV_).w), bfhi((VV_).w)}
; __device__ __forceinline__ void glu_task(int t, int l, const float* s5d, const bf16_t* P, const bf16_t* YB, const bf16_t* WGLU, bf16_t* Z1, int fr, int fq) {
;     ...
;     for (int tb = 0; tb < 2; ++tb) { const size_t row = row0 + tb * 16;
; #pragma unroll
;         for (int ks = 0; ks < 8; ++ks) { const int k0 = ks * 32 + fq * 8; const u32x4 yw = ld8(YB + row * 256 + k0), uw = ld8(P + row * INP + OFF_S5 + k0);
;             const f32x4 d0 = *(const f32x4*)(s5d + l * 256 + k0), d1 = *(const f32x4*)(s5d + l * 256 + k0 + 4); UNPK8(yw, y); UNPK8(uw, u); u32x4 o;
;             o.x = cvt_pk_bf16(gelu_tanh(y[0] + d0[0] * u[0]), gelu_tanh(y[1] + d0[1] * u[1])); o.y = cvt_pk_bf16(gelu_tanh(y[2] + d0[2] * u[2]), gelu_tanh(y[3] + d0[3] * u[3]));
;             o.z = cvt_pk_bf16(gelu_tanh(y[4] + d1[0] * u[4]), gelu_tanh(y[5] + d1[1] * u[5])); o.w = cvt_pk_bf16(gelu_tanh(y[6] + d1[2] * u[6]), gelu_tanh(y[7] + d1[3] * u[7]));
;             bfr[tb][ks] = asfrag(o); } }
	v_mov_b32_e32 v58, v106
	v_mov_b32_e32 v59, v107
	v_mov_b32_e32 v60, v108
	v_mov_b32_e32 v61, v109
	v_mov_b32_e32 v62, v110
	v_mov_b32_e32 v63, v111
	v_mov_b32_e32 v64, v112
	v_mov_b32_e32 v65, v113
	v_lshlrev_b32_e32 v86, 16, v58
	v_and_b32_e32 v58, 0xffff0000, v58
	v_lshlrev_b32_e32 v90, 16, v62
	v_and_b32_e32 v62, 0xffff0000, v62
	v_fmac_f32_e32 v58, v83, v62
	v_mul_f32_e32 v62, 0x3d372713, v58
	v_mul_f32_e32 v62, v58, v62
	v_fma_f32 v62, v58, v62, v58
	v_mul_f32_e32 v62, 0x3f4c422a, v62
	v_add_f32_e32 v62, v62, v62
	v_mul_f32_e32 v62, 0xbfb8aa3b, v62
	v_exp_f32_e32 v62, v62
	v_lshlrev_b32_e32 v87, 16, v59
	v_and_b32_e32 v59, 0xffff0000, v59
	v_lshlrev_b32_e32 v91, 16, v63
	v_add_f32_e32 v62, 1.0, v62
	v_rcp_f32_e32 v62, v62
	v_and_b32_e32 v63, 0xffff0000, v63
	v_fmac_f32_e32 v87, v84, v91
	v_fmac_f32_e32 v59, v85, v63
	v_fmac_f32_e32 v86, v82, v90
	v_mul_f32_e32 v58, v58, v62
	v_mul_f32_e32 v62, 0x3d372713, v87
	v_mul_f32_e32 v63, 0x3d372713, v59
	v_mul_f32_e32 v82, 0x3d372713, v86
	v_mul_f32_e32 v62, v87, v62
	v_mul_f32_e32 v63, v59, v63
	v_mul_f32_e32 v82, v86, v82
	v_fma_f32 v62, v87, v62, v87
	v_fma_f32 v63, v59, v63, v59
	v_fma_f32 v82, v86, v82, v86
	v_mul_f32_e32 v62, 0x3f4c422a, v62
	v_mul_f32_e32 v63, 0x3f4c422a, v63
	v_mul_f32_e32 v82, 0x3f4c422a, v82
	v_add_f32_e32 v62, v62, v62
	v_add_f32_e32 v63, v63, v63
	v_add_f32_e32 v82, v82, v82
	v_mul_f32_e32 v62, 0xbfb8aa3b, v62
	v_mul_f32_e32 v63, 0xbfb8aa3b, v63
	v_mul_f32_e32 v82, 0xbfb8aa3b, v82
	v_exp_f32_e32 v62, v62
	v_exp_f32_e32 v63, v63
	v_exp_f32_e32 v82, v82
	v_lshlrev_b32_e32 v88, 16, v60
	v_add_f32_e32 v62, 1.0, v62
	v_add_f32_e32 v63, 1.0, v63
	v_add_f32_e32 v82, 1.0, v82
	v_rcp_f32_e32 v62, v62
	v_rcp_f32_e32 v63, v63
	v_rcp_f32_e32 v82, v82
	v_and_b32_e32 v60, 0xffff0000, v60
	v_lshlrev_b32_e32 v92, 16, v64
	v_and_b32_e32 v64, 0xffff0000, v64
	v_mul_f32_e32 v62, v87, v62
	v_mul_f32_e32 v59, v59, v63
	v_fmac_f32_e32 v88, v78, v92
	v_fmac_f32_e32 v60, v79, v64
	v_mul_f32_e32 v82, v86, v82
	v_cvt_pk_bf16_f32 v58, v82, v58
	v_cvt_pk_bf16_f32 v59, v62, v59
	v_mul_f32_e32 v62, 0x3d372713, v88
	v_mul_f32_e32 v63, 0x3d372713, v60
	v_mul_f32_e32 v62, v88, v62
	v_mul_f32_e32 v63, v60, v63
	v_fma_f32 v62, v88, v62, v88
	v_fma_f32 v63, v60, v63, v60
	v_mul_f32_e32 v62, 0x3f4c422a, v62
	v_mul_f32_e32 v63, 0x3f4c422a, v63
	v_add_f32_e32 v62, v62, v62
	v_add_f32_e32 v63, v63, v63
	v_mul_f32_e32 v62, 0xbfb8aa3b, v62
	v_mul_f32_e32 v63, 0xbfb8aa3b, v63
	v_exp_f32_e32 v62, v62
	v_exp_f32_e32 v63, v63
	v_lshlrev_b32_e32 v89, 16, v61
	v_and_b32_e32 v61, 0xffff0000, v61
	v_add_f32_e32 v62, 1.0, v62
	v_add_f32_e32 v63, 1.0, v63
	v_rcp_f32_e32 v62, v62
	v_rcp_f32_e32 v63, v63
	v_lshlrev_b32_e32 v93, 16, v65
	v_and_b32_e32 v65, 0xffff0000, v65
	v_mul_f32_e32 v62, v88, v62
	v_mul_f32_e32 v60, v60, v63
	v_fmac_f32_e32 v89, v80, v93
	v_fmac_f32_e32 v61, v81, v65
	v_cvt_pk_bf16_f32 v60, v62, v60
	v_mul_f32_e32 v62, 0x3d372713, v89
	v_mul_f32_e32 v63, 0x3d372713, v61
	v_mul_f32_e32 v62, v89, v62
	v_mul_f32_e32 v63, v61, v63
	v_fma_f32 v62, v89, v62, v89
	v_fma_f32 v63, v61, v63, v61
	v_mul_f32_e32 v62, 0x3f4c422a, v62
	v_mul_f32_e32 v63, 0x3f4c422a, v63
	v_add_f32_e32 v62, v62, v62
	v_add_f32_e32 v63, v63, v63
	v_mul_f32_e32 v62, 0xbfb8aa3b, v62
	v_mul_f32_e32 v63, 0xbfb8aa3b, v63
	v_exp_f32_e32 v62, v62
	v_exp_f32_e32 v63, v63
	v_add_f32_e32 v62, 1.0, v62
	v_add_f32_e32 v63, 1.0, v63
	v_rcp_f32_e32 v62, v62
	v_rcp_f32_e32 v63, v63
	v_mul_f32_e32 v62, v89, v62
	v_mul_f32_e32 v61, v61, v63
	v_cvt_pk_bf16_f32 v61, v62, v61
	ds_read_b128 v[82:85], v246 offset:784
	ds_read_b128 v[86:89], v246 offset:768
	s_waitcnt vmcnt(2) lgkmcnt(0)
	v_mov_b32_e32 v62, v118
	v_mov_b32_e32 v63, v119
	v_mov_b32_e32 v64, v120
	v_mov_b32_e32 v65, v121
	v_mov_b32_e32 v78, v122
	v_mov_b32_e32 v79, v123
	v_mov_b32_e32 v80, v124
	v_mov_b32_e32 v81, v125
	v_lshlrev_b32_e32 v90, 16, v62
	v_and_b32_e32 v62, 0xffff0000, v62
	v_lshlrev_b32_e32 v94, 16, v78
	v_and_b32_e32 v78, 0xffff0000, v78
	v_fmac_f32_e32 v62, v87, v78
	v_mul_f32_e32 v78, 0x3d372713, v62
	v_mul_f32_e32 v78, v62, v78
	v_fma_f32 v78, v62, v78, v62
	v_mul_f32_e32 v78, 0x3f4c422a, v78
	v_add_f32_e32 v78, v78, v78
	v_mul_f32_e32 v78, 0xbfb8aa3b, v78
	v_exp_f32_e32 v78, v78
	v_lshlrev_b32_e32 v91, 16, v63
	v_and_b32_e32 v63, 0xffff0000, v63
	v_lshlrev_b32_e32 v95, 16, v79
	v_add_f32_e32 v78, 1.0, v78
	v_rcp_f32_e32 v78, v78
	v_and_b32_e32 v79, 0xffff0000, v79
	v_fmac_f32_e32 v91, v88, v95
	v_fmac_f32_e32 v63, v89, v79
	v_fmac_f32_e32 v90, v86, v94
	v_mul_f32_e32 v62, v62, v78
	v_mul_f32_e32 v78, 0x3d372713, v91
	v_mul_f32_e32 v79, 0x3d372713, v63
	v_mul_f32_e32 v86, 0x3d372713, v90
	v_mul_f32_e32 v78, v91, v78
	v_mul_f32_e32 v79, v63, v79
	v_mul_f32_e32 v86, v90, v86
	v_fma_f32 v78, v91, v78, v91
	v_fma_f32 v79, v63, v79, v63
	v_fma_f32 v86, v90, v86, v90
	v_mul_f32_e32 v78, 0x3f4c422a, v78
	v_mul_f32_e32 v79, 0x3f4c422a, v79
	v_mul_f32_e32 v86, 0x3f4c422a, v86
	v_add_f32_e32 v78, v78, v78
	v_add_f32_e32 v79, v79, v79
	v_add_f32_e32 v86, v86, v86
	v_mul_f32_e32 v78, 0xbfb8aa3b, v78
	v_mul_f32_e32 v79, 0xbfb8aa3b, v79
	v_mul_f32_e32 v86, 0xbfb8aa3b, v86
	v_exp_f32_e32 v78, v78
	v_exp_f32_e32 v79, v79
	v_exp_f32_e32 v86, v86
	v_lshlrev_b32_e32 v92, 16, v64
	v_add_f32_e32 v78, 1.0, v78
	v_add_f32_e32 v79, 1.0, v79
	v_add_f32_e32 v86, 1.0, v86
	v_rcp_f32_e32 v78, v78
	v_rcp_f32_e32 v79, v79
	v_rcp_f32_e32 v86, v86
	v_and_b32_e32 v64, 0xffff0000, v64
	v_lshlrev_b32_e32 v96, 16, v80
	v_and_b32_e32 v80, 0xffff0000, v80
	v_mul_f32_e32 v78, v91, v78
	v_mul_f32_e32 v63, v63, v79
	v_fmac_f32_e32 v92, v82, v96
	v_fmac_f32_e32 v64, v83, v80
	v_mul_f32_e32 v86, v90, v86
; __device__ __forceinline__ unsigned cvt_pk_bf16(float lo, float hi) { unsigned r; asm volatile("v_cvt_pk_bf16_f32 %0, %1, %2" : "=v"(r) : "v"(lo), "v"(hi)); return r; }
; __device__ __forceinline__ float gelu_tanh(float x) { const float u = 0.7978845608028654f * (x + 0.044715f * x * x * x); return x * sigm(2.f * u); }
; #define UNPK8(VV_, XX_) float XX_[8] = {bflo((VV_).x), bfhi((VV_).x), bflo((VV_).y), bfhi((VV_).y), bflo((VV_).z), bfhi((VV_).z), bflo((VV_).w), bfhi((VV_).w)}
; __device__ __forceinline__ void glu_task(int t, int l, const float* s5d, const bf16_t* P, const bf16_t* YB, const bf16_t* WGLU, bf16_t* Z1, int fr, int fq) {
;     ...
;     for (int tb = 0; tb < 2; ++tb) { const size_t row = row0 + tb * 16;
; #pragma unroll
;         for (int ks = 0; ks < 8; ++ks) { const int k0 = ks * 32 + fq * 8; const u32x4 yw = ld8(YB + row * 256 + k0), uw = ld8(P + row * INP + OFF_S5 + k0);
;             const f32x4 d0 = *(const f32x4*)(s5d + l * 256 + k0), d1 = *(const f32x4*)(s5d + l * 256 + k0 + 4); UNPK8(yw, y); UNPK8(uw, u); u32x4 o;
;             o.x = cvt_pk_bf16(gelu_tanh(y[0] + d0[0] * u[0]), gelu_tanh(y[1] + d0[1] * u[1])); o.y = cvt_pk_bf16(gelu_tanh(y[2] + d0[2] * u[2]), gelu_tanh(y[3] + d0[3] * u[3]));
;             o.z = cvt_pk_bf16(gelu_tanh(y[4] + d1[0] * u[4]), gelu_tanh(y[5] + d1[1] * u[5])); o.w = cvt_pk_bf16(gelu_tanh(y[6] + d1[2] * u[6]), gelu_tanh(y[7] + d1[3] * u[7]));
;             bfr[tb][ks] = asfrag(o); } }
;     const bf16_t* wg0 = WGLU + ((size_t)l * 256 + cb0 * 16 + fr) * 256 + fq * 8;
;     bf16x8 wf[2][8];
; #pragma unroll
;     for (int ks = 0; ks < 8; ++ks) wf[0][ks] = asfrag(ld8(wg0 + ks * 32));
	v_cvt_pk_bf16_f32 v62, v86, v62
	v_cvt_pk_bf16_f32 v63, v78, v63
	v_mul_f32_e32 v78, 0x3d372713, v92
	v_mul_f32_e32 v79, 0x3d372713, v64
	v_mul_f32_e32 v78, v92, v78
	v_mul_f32_e32 v79, v64, v79
	v_fma_f32 v78, v92, v78, v92
	v_fma_f32 v79, v64, v79, v64
	v_mul_f32_e32 v78, 0x3f4c422a, v78
	v_mul_f32_e32 v79, 0x3f4c422a, v79
	v_add_f32_e32 v78, v78, v78
	v_add_f32_e32 v79, v79, v79
	v_mul_f32_e32 v78, 0xbfb8aa3b, v78
	v_mul_f32_e32 v79, 0xbfb8aa3b, v79
	v_exp_f32_e32 v78, v78
	v_exp_f32_e32 v79, v79
	v_lshlrev_b32_e32 v93, 16, v65
	v_and_b32_e32 v65, 0xffff0000, v65
	v_add_f32_e32 v78, 1.0, v78
	v_add_f32_e32 v79, 1.0, v79
	v_rcp_f32_e32 v78, v78
	v_rcp_f32_e32 v79, v79
	v_lshlrev_b32_e32 v97, 16, v81
	v_and_b32_e32 v81, 0xffff0000, v81
	v_mul_f32_e32 v78, v92, v78
	v_mul_f32_e32 v64, v64, v79
	v_fmac_f32_e32 v93, v84, v97
	v_fmac_f32_e32 v65, v85, v81
	v_cvt_pk_bf16_f32 v64, v78, v64
	v_mul_f32_e32 v78, 0x3d372713, v93
	v_mul_f32_e32 v79, 0x3d372713, v65
	v_mul_f32_e32 v78, v93, v78
	v_mul_f32_e32 v79, v65, v79
	v_fma_f32 v78, v93, v78, v93
	v_fma_f32 v79, v65, v79, v65
	v_mul_f32_e32 v78, 0x3f4c422a, v78
	v_mul_f32_e32 v79, 0x3f4c422a, v79
	v_add_f32_e32 v78, v78, v78
	v_add_f32_e32 v79, v79, v79
	v_mul_f32_e32 v78, 0xbfb8aa3b, v78
	v_mul_f32_e32 v79, 0xbfb8aa3b, v79
	v_exp_f32_e32 v78, v78
	v_exp_f32_e32 v79, v79
	v_add_f32_e32 v78, 1.0, v78
	v_add_f32_e32 v79, 1.0, v79
	v_rcp_f32_e32 v78, v78
	v_rcp_f32_e32 v79, v79
	v_mul_f32_e32 v78, v93, v78
	v_mul_f32_e32 v65, v65, v79
	v_cvt_pk_bf16_f32 v65, v78, v65
	s_nop 0
	s_nop 0
	ds_read_b128 v[82:85], v246 offset:912
	ds_read_b128 v[86:89], v246 offset:896
	s_waitcnt vmcnt(0) lgkmcnt(0)
	v_mov_b32_e32 v78, v126
	v_mov_b32_e32 v79, v127
	v_mov_b32_e32 v80, v128
	v_mov_b32_e32 v81, v129
	v_mov_b32_e32 v66, v130
	v_mov_b32_e32 v67, v131
	v_mov_b32_e32 v68, v132
	v_mov_b32_e32 v69, v133
	v_lshlrev_b32_e32 v90, 16, v78
	v_and_b32_e32 v78, 0xffff0000, v78
	v_lshlrev_b32_e32 v94, 16, v66
	v_and_b32_e32 v66, 0xffff0000, v66
	v_fmac_f32_e32 v78, v87, v66
	v_mul_f32_e32 v66, 0x3d372713, v78
	v_mul_f32_e32 v66, v78, v66
	v_fma_f32 v66, v78, v66, v78
	v_mul_f32_e32 v66, 0x3f4c422a, v66
	v_add_f32_e32 v66, v66, v66
	v_mul_f32_e32 v66, 0xbfb8aa3b, v66
	v_exp_f32_e32 v66, v66
	v_lshlrev_b32_e32 v91, 16, v79
	v_and_b32_e32 v79, 0xffff0000, v79
	v_lshlrev_b32_e32 v95, 16, v67
	v_add_f32_e32 v66, 1.0, v66
	v_rcp_f32_e32 v66, v66
	v_and_b32_e32 v67, 0xffff0000, v67
	v_fmac_f32_e32 v91, v88, v95
	v_fmac_f32_e32 v79, v89, v67
	v_fmac_f32_e32 v90, v86, v94
	v_mul_f32_e32 v66, v78, v66
	v_mul_f32_e32 v78, 0x3d372713, v91
	v_mul_f32_e32 v67, 0x3d372713, v79
	v_mul_f32_e32 v86, 0x3d372713, v90
	v_mul_f32_e32 v78, v91, v78
	v_mul_f32_e32 v67, v79, v67
	v_mul_f32_e32 v86, v90, v86
	v_fma_f32 v78, v91, v78, v91
	v_fma_f32 v67, v79, v67, v79
	v_fma_f32 v86, v90, v86, v90
	v_mul_f32_e32 v78, 0x3f4c422a, v78
	v_mul_f32_e32 v67, 0x3f4c422a, v67
	v_mul_f32_e32 v86, 0x3f4c422a, v86
	v_add_f32_e32 v78, v78, v78
	v_add_f32_e32 v67, v67, v67
	v_add_f32_e32 v86, v86, v86
	v_mul_f32_e32 v78, 0xbfb8aa3b, v78
	v_mul_f32_e32 v67, 0xbfb8aa3b, v67
	v_mul_f32_e32 v86, 0xbfb8aa3b, v86
	v_exp_f32_e32 v78, v78
	v_exp_f32_e32 v67, v67
	v_exp_f32_e32 v86, v86
	v_lshlrev_b32_e32 v92, 16, v80
	v_add_f32_e32 v78, 1.0, v78
	v_add_f32_e32 v67, 1.0, v67
	v_add_f32_e32 v86, 1.0, v86
	v_rcp_f32_e32 v78, v78
	v_rcp_f32_e32 v67, v67
	v_rcp_f32_e32 v86, v86
	v_and_b32_e32 v80, 0xffff0000, v80
	v_lshlrev_b32_e32 v96, 16, v68
	v_and_b32_e32 v68, 0xffff0000, v68
	v_mul_f32_e32 v78, v91, v78
	v_mul_f32_e32 v67, v79, v67
	v_fmac_f32_e32 v92, v82, v96
	v_fmac_f32_e32 v80, v83, v68
	v_mul_f32_e32 v86, v90, v86
	v_cvt_pk_bf16_f32 v66, v86, v66
	v_cvt_pk_bf16_f32 v67, v78, v67
	v_mul_f32_e32 v78, 0x3d372713, v92
	v_mul_f32_e32 v68, 0x3d372713, v80
	v_mul_f32_e32 v78, v92, v78
	v_mul_f32_e32 v68, v80, v68
	v_fma_f32 v78, v92, v78, v92
	v_fma_f32 v68, v80, v68, v80
	v_mul_f32_e32 v78, 0x3f4c422a, v78
	v_mul_f32_e32 v68, 0x3f4c422a, v68
	v_add_f32_e32 v78, v78, v78
	v_add_f32_e32 v68, v68, v68
	v_mul_f32_e32 v78, 0xbfb8aa3b, v78
	v_mul_f32_e32 v68, 0xbfb8aa3b, v68
	v_exp_f32_e32 v78, v78
	v_exp_f32_e32 v68, v68
	v_lshlrev_b32_e32 v93, 16, v81
	v_and_b32_e32 v81, 0xffff0000, v81
	v_add_f32_e32 v78, 1.0, v78
	v_add_f32_e32 v68, 1.0, v68
	v_rcp_f32_e32 v78, v78
	v_rcp_f32_e32 v68, v68
	v_lshlrev_b32_e32 v97, 16, v69
	v_and_b32_e32 v69, 0xffff0000, v69
	v_mul_f32_e32 v78, v92, v78
	v_mul_f32_e32 v68, v80, v68
	v_fmac_f32_e32 v93, v84, v97
	v_fmac_f32_e32 v81, v85, v69
	v_cvt_pk_bf16_f32 v68, v78, v68
	v_mul_f32_e32 v78, 0x3d372713, v93
	v_mul_f32_e32 v69, 0x3d372713, v81
	v_mul_f32_e32 v78, v93, v78
	v_mul_f32_e32 v69, v81, v69
	v_fma_f32 v78, v93, v78, v93
	v_fma_f32 v69, v81, v69, v81
	v_mul_f32_e32 v78, 0x3f4c422a, v78
	v_mul_f32_e32 v69, 0x3f4c422a, v69
	v_add_f32_e32 v78, v78, v78
	v_add_f32_e32 v69, v69, v69
	v_mul_f32_e32 v78, 0xbfb8aa3b, v78
	v_mul_f32_e32 v69, 0xbfb8aa3b, v69
	v_exp_f32_e32 v78, v78
	v_exp_f32_e32 v69, v69
	v_mov_b32_e32 v79, v1
	v_add_f32_e32 v78, 1.0, v78
	v_add_f32_e32 v69, 1.0, v69
	v_rcp_f32_e32 v78, v78
	v_rcp_f32_e32 v69, v69
	v_mul_f32_e32 v78, v93, v78
	v_mul_f32_e32 v69, v81, v69
	v_cvt_pk_bf16_f32 v69, v78, v69
	v_or_b32_e32 v78, s5, v176
	v_lshlrev_b32_e32 v78, 9, v78
	v_lshl_add_u64 v[116:117], v[136:137], 0, v[78:79]
	flat_load_dwordx4 v[78:81], v[116:117]
	flat_load_dwordx4 v[82:85], v[116:117] offset:64
	flat_load_dwordx4 v[86:89], v[116:117] offset:128
	flat_load_dwordx4 v[90:93], v[116:117] offset:192
	flat_load_dwordx4 v[94:97], v[116:117] offset:256
	flat_load_dwordx4 v[98:101], v[116:117] offset:320
; __device__ __forceinline__ unsigned cvt_pk_bf16(float lo, float hi) { unsigned r; asm volatile("v_cvt_pk_bf16_f32 %0, %1, %2" : "=v"(r) : "v"(lo), "v"(hi)); return r; }
; __device__ __forceinline__ float bflo(unsigned w) { return __uint_as_float(w << 16); }
; __device__ __forceinline__ float bfhi(unsigned w) { return __uint_as_float(w & 0xffff0000u); }
; __device__ __forceinline__ float sigm(float x) { return __builtin_amdgcn_rcpf(1.f + __expf(-x)); }
; __device__ __forceinline__ void glu_task(int t, int l, const float* s5d, const bf16_t* P, const bf16_t* YB, const bf16_t* WGLU, bf16_t* Z1, int fr, int fq) {
;     ...
;     u32x2 eyw[2][4], euw[2][4], egw[2][4];
; #pragma unroll
;     for (int tb = 0; tb < 2; ++tb)
; #pragma unroll
;         for (int c4 = 0; c4 < 4; ++c4) { const size_t row = row0 + tb * 16; const int n4 = (cb0 + c4) * 16 + fq * 4; eyw[tb][c4] = ld4(YB + row * 256 + n4); euw[tb][c4] = ld4(P + row * INP + OFF_S5 + n4); egw[tb][c4] = ld4(P + row * INP + OFF_GATE + 256 + n4); }
; #pragma unroll
;     for (int c4 = 0; c4 < 4; ++c4) { f32x4 acc[2]; acc[0] = (f32x4){0.f, 0.f, 0.f, 0.f}; acc[1] = acc[0];
;         const int nrow = c4 < 3 ? (c4 + 1) * 16 : 0;
; #pragma unroll
;         for (int ks = 0; ks < 8; ++ks) wf[(c4 + 1) & 1][ks] = asfrag(ld8(wg0 + (size_t)nrow * 256 + ks * 32));
; #pragma unroll
;         for (int ks = 0; ks < 8; ++ks) { acc[0] = MFMA16(wf[c4 & 1][ks], bfr[0][ks], acc[0]); acc[1] = MFMA16(wf[c4 & 1][ks], bfr[1][ks], acc[1]); }
;         const int n4 = (cb0 + c4) * 16 + fq * 4;
;         const f32x4 dd = *(const f32x4*)(s5d + l * 256 + n4);
; #pragma unroll
;         for (int tb = 0; tb < 2; ++tb) { const u32x2 yw = eyw[tb][c4], uw = euw[tb][c4], gw = egw[tb][c4];
;             const float y0 = bflo(yw.x), y1 = bfhi(yw.x), y2 = bflo(yw.y), y3 = bfhi(yw.y), u0 = bflo(uw.x), u1 = bfhi(uw.x), u2 = bflo(uw.y), u3 = bfhi(uw.y);
;             const float g0 = gelu_tanh(y0 + dd[0] * u0), g1 = gelu_tanh(y1 + dd[1] * u1), g2 = gelu_tanh(y2 + dd[2] * u2), g3 = gelu_tanh(y3 + dd[3] * u3);
;             u32x2 w; w.x = cvt_pk_bf16(g0 * sigm(acc[tb][0]) * siluf(bflo(gw.x)), g1 * sigm(acc[tb][1]) * siluf(bfhi(gw.x)));
;             w.y = cvt_pk_bf16(g2 * sigm(acc[tb][2]) * siluf(bflo(gw.y)), g3 * sigm(acc[tb][3]) * siluf(bfhi(gw.y)));
;             *(u32x2*)(Z1 + (row0 + tb * 16) * 256 + n4) = w; } }
	flat_load_dwordx4 v[102:105], v[116:117] offset:384
	flat_load_dwordx4 v[106:109], v[116:117] offset:448
	flat_load_dwordx2 v[172:173], v[70:71]
	flat_load_dwordx2 v[192:193], v[72:73] offset:320
	flat_load_dwordx2 v[226:227], v[72:73] offset:2880
	flat_load_dwordx2 v[128:129], v[70:71] offset:32
	flat_load_dwordx2 v[126:127], v[72:73] offset:352
	flat_load_dwordx2 v[124:125], v[72:73] offset:2912
	flat_load_dwordx2 v[170:171], v[70:71] offset:64
	flat_load_dwordx2 v[168:169], v[72:73] offset:384
	flat_load_dwordx2 v[166:167], v[72:73] offset:2944
	flat_load_dwordx2 v[156:157], v[70:71] offset:96
	flat_load_dwordx2 v[148:149], v[72:73] offset:416
	flat_load_dwordx2 v[146:147], v[72:73] offset:2976
	v_lshl_add_u64 v[70:71], v[74:75], 0, v[158:159]
	v_lshl_add_u64 v[72:73], v[76:77], 0, v[158:159]
	flat_load_dwordx2 v[228:229], v[70:71]
	flat_load_dwordx2 v[230:231], v[72:73] offset:320
	flat_load_dwordx2 v[232:233], v[72:73] offset:2880
	flat_load_dwordx2 v[122:123], v[70:71] offset:32
	flat_load_dwordx2 v[120:121], v[72:73] offset:352
	flat_load_dwordx2 v[118:119], v[72:73] offset:2912
	flat_load_dwordx2 v[164:165], v[70:71] offset:64
	flat_load_dwordx2 v[162:163], v[72:73] offset:384
	flat_load_dwordx2 v[160:161], v[72:73] offset:2944
	flat_load_dwordx2 v[144:145], v[70:71] offset:96
	flat_load_dwordx2 v[142:143], v[72:73] offset:416
	flat_load_dwordx2 v[140:141], v[72:73] offset:2976
	v_add_co_u32_e32 v70, vcc, s33, v116
	s_waitcnt vmcnt(0) lgkmcnt(0)
	v_mfma_f32_16x16x32_bf16 v[74:77], v[78:81], v[38:41], 0
	v_addc_co_u32_e32 v71, vcc, 0, v117, vcc
	flat_load_dwordx4 v[110:113], v[70:71]
	flat_load_dwordx4 v[130:133], v[70:71] offset:64
	flat_load_dwordx4 v[180:183], v[70:71] offset:128
	flat_load_dwordx4 v[184:187], v[70:71] offset:192
	flat_load_dwordx4 v[188:191], v[70:71] offset:256
	flat_load_dwordx4 v[214:217], v[70:71] offset:320
	flat_load_dwordx4 v[218:221], v[70:71] offset:384
	flat_load_dwordx4 v[222:225], v[70:71] offset:448
	v_mfma_f32_16x16x32_bf16 v[70:73], v[78:81], v[2:5], 0
	global_load_dwordx4 v[78:81], v178, s[22:23]
	v_and_b32_e32 v179, 0xffff0000, v129
	v_mfma_f32_16x16x32_bf16 v[70:73], v[82:85], v[6:9], v[70:73]
	v_mfma_f32_16x16x32_bf16 v[74:77], v[82:85], v[42:45], v[74:77]
	v_lshlrev_b32_e32 v84, 16, v172
	v_lshlrev_b32_e32 v85, 16, v192
	v_lshl_add_u64 v[82:83], s[40:41], 0, v[158:159]
	v_mfma_f32_16x16x32_bf16 v[70:73], v[86:89], v[14:17], v[70:73]
	v_lshlrev_b32_e32 v159, 16, v128
	v_and_b32_e32 v128, 0xffff0000, v128
	s_waitcnt vmcnt(0)
	v_fmac_f32_e32 v84, v78, v85
	v_mul_f32_e32 v85, 0x3d372713, v84
	v_mul_f32_e32 v85, v84, v85
	v_fma_f32 v85, v84, v85, v84
	v_mul_f32_e32 v85, 0x3f4c422a, v85
	v_add_f32_e32 v85, v85, v85
	v_mul_f32_e32 v85, 0xbfb8aa3b, v85
	v_exp_f32_e32 v85, v85
	v_mfma_f32_16x16x32_bf16 v[74:77], v[86:89], v[46:49], v[74:77]
	v_and_b32_e32 v86, 0xffff0000, v172
	v_and_b32_e32 v87, 0xffff0000, v192
	v_add_f32_e32 v85, 1.0, v85
	v_rcp_f32_e32 v85, v85
	v_fmac_f32_e32 v86, v79, v87
	v_lshlrev_b32_e32 v88, 16, v173
	v_lshlrev_b32_e32 v89, 16, v193
	v_mul_f32_e32 v85, v84, v85
	v_mul_f32_e32 v84, 0x3d372713, v86
	v_mul_f32_e32 v84, v86, v84
	v_fma_f32 v84, v86, v84, v86
	v_mul_f32_e32 v84, 0x3f4c422a, v84
	v_add_f32_e32 v84, v84, v84
	v_mul_f32_e32 v84, 0xbfb8aa3b, v84
	v_exp_f32_e32 v84, v84
	v_fmac_f32_e32 v88, v80, v89
	v_mfma_f32_16x16x32_bf16 v[70:73], v[90:93], v[18:21], v[70:73]
	v_lshlrev_b32_e32 v172, 16, v129
	v_add_f32_e32 v84, 1.0, v84
	v_rcp_f32_e32 v84, v84
	v_mfma_f32_16x16x32_bf16 v[70:73], v[94:97], v[22:25], v[70:73]
	v_lshlrev_b32_e32 v129, 16, v126
	v_and_b32_e32 v126, 0xffff0000, v126
	v_mul_f32_e32 v87, v86, v84
	v_mul_f32_e32 v84, 0x3d372713, v88
	v_mul_f32_e32 v84, v88, v84
	v_fma_f32 v84, v88, v84, v88
	v_mul_f32_e32 v84, 0x3f4c422a, v84
	v_add_f32_e32 v84, v84, v84
	v_mul_f32_e32 v84, 0xbfb8aa3b, v84
	v_exp_f32_e32 v84, v84
	v_mfma_f32_16x16x32_bf16 v[74:77], v[90:93], v[50:53], v[74:77]
	v_and_b32_e32 v90, 0xffff0000, v173
	v_and_b32_e32 v91, 0xffff0000, v193
	v_add_f32_e32 v84, 1.0, v84
	v_rcp_f32_e32 v84, v84
	v_mfma_f32_16x16x32_bf16 v[70:73], v[98:101], v[26:29], v[70:73]
	v_fmac_f32_e32 v90, v81, v91
	v_and_b32_e32 v86, 0xffff0000, v226
	v_mul_f32_e32 v89, v88, v84
	v_mul_f32_e32 v84, 0x3d372713, v90
	v_mul_f32_e32 v84, v90, v84
	v_mfma_f32_16x16x32_bf16 v[70:73], v[102:105], v[30:33], v[70:73]
	v_fma_f32 v84, v90, v84, v90
	v_mul_f32_e32 v84, 0x3f4c422a, v84
	v_add_f32_e32 v84, v84, v84
	v_mul_f32_e32 v84, 0xbfb8aa3b, v84
	v_mfma_f32_16x16x32_bf16 v[70:73], v[106:109], v[34:37], v[70:73]
	v_exp_f32_e32 v84, v84
	v_lshlrev_b32_e32 v88, 16, v227
	v_lshlrev_b32_e32 v173, 16, v127
	v_mfma_f32_16x16x32_bf16 v[74:77], v[94:97], v[54:57], v[74:77]
	v_add_f32_e32 v84, 1.0, v84
	s_nop 2
	v_mul_f32_e32 v70, 0xbfb8aa3b, v70
	v_rcp_f32_e32 v84, v84
	v_exp_f32_e32 v70, v70
	v_mfma_f32_16x16x32_bf16 v[74:77], v[98:101], v[58:61], v[74:77]
	v_mul_f32_e32 v91, v90, v84
	v_add_f32_e32 v70, 1.0, v70
	v_lshlrev_b32_e32 v84, 16, v226
	v_rcp_f32_e32 v93, v70
	v_mul_f32_e32 v70, 0xbfb8aa3b, v84
	v_exp_f32_e32 v70, v70
	v_and_b32_e32 v90, 0xffff0000, v227
	v_mfma_f32_16x16x32_bf16 v[74:77], v[102:105], v[62:65], v[74:77]
	v_add_f32_e32 v70, 1.0, v70
	v_rcp_f32_e32 v92, v70
	v_mul_f32_e32 v70, 0xbfb8aa3b, v71
	v_exp_f32_e32 v70, v70
	v_mfma_f32_16x16x32_bf16 v[74:77], v[106:109], v[66:69], v[74:77]
	v_mul_f32_e64 v84, v92, v84
	v_mul_f32_e64 v85, v93, v85
	v_add_f32_e32 v70, 1.0, v70
	v_rcp_f32_e32 v71, v70
	v_mul_f32_e32 v70, 0xbfb8aa3b, v86
	v_exp_f32_e32 v70, v70
	v_mul_f32_e32 v84, v84, v85
	s_waitcnt lgkmcnt(0)
; __device__ __forceinline__ unsigned cvt_pk_bf16(float lo, float hi) { unsigned r; asm volatile("v_cvt_pk_bf16_f32 %0, %1, %2" : "=v"(r) : "v"(lo), "v"(hi)); return r; }
; __device__ __forceinline__ float bflo(unsigned w) { return __uint_as_float(w << 16); }
; __device__ __forceinline__ float bfhi(unsigned w) { return __uint_as_float(w & 0xffff0000u); }
; __device__ __forceinline__ float sigm(float x) { return __builtin_amdgcn_rcpf(1.f + __expf(-x)); }
; __device__ __forceinline__ float siluf(float x) { return x * __builtin_amdgcn_rcpf(1.f + __expf(-x)); }
; __device__ __forceinline__ float gelu_tanh(float x) { const float u = 0.7978845608028654f * (x + 0.044715f * x * x * x); return x * sigm(2.f * u); }
; #define MFMA16(a, b, c) __builtin_amdgcn_mfma_f32_16x16x32_bf16((a), (b), (c), 0, 0, 0)
; __device__ __forceinline__ void glu_task(int t, int l, const float* s5d, const bf16_t* P, const bf16_t* YB, const bf16_t* WGLU, bf16_t* Z1, int fr, int fq) {
;     ...
;     for (int c4 = 0; c4 < 4; ++c4) { f32x4 acc[2]; acc[0] = (f32x4){0.f, 0.f, 0.f, 0.f}; acc[1] = acc[0];
;         const int nrow = c4 < 3 ? (c4 + 1) * 16 : 0;
; #pragma unroll
;         for (int ks = 0; ks < 8; ++ks) wf[(c4 + 1) & 1][ks] = asfrag(ld8(wg0 + (size_t)nrow * 256 + ks * 32));
; #pragma unroll
;         for (int ks = 0; ks < 8; ++ks) { acc[0] = MFMA16(wf[c4 & 1][ks], bfr[0][ks], acc[0]); acc[1] = MFMA16(wf[c4 & 1][ks], bfr[1][ks], acc[1]); }
;         const int n4 = (cb0 + c4) * 16 + fq * 4;
;         const f32x4 dd = *(const f32x4*)(s5d + l * 256 + n4);
; #pragma unroll
;         for (int tb = 0; tb < 2; ++tb) { const u32x2 yw = eyw[tb][c4], uw = euw[tb][c4], gw = egw[tb][c4];
;             const float y0 = bflo(yw.x), y1 = bfhi(yw.x), y2 = bflo(yw.y), y3 = bfhi(yw.y), u0 = bflo(uw.x), u1 = bfhi(uw.x), u2 = bflo(uw.y), u3 = bfhi(uw.y);
;             const float g0 = gelu_tanh(y0 + dd[0] * u0), g1 = gelu_tanh(y1 + dd[1] * u1), g2 = gelu_tanh(y2 + dd[2] * u2), g3 = gelu_tanh(y3 + dd[3] * u3);
;             u32x2 w; w.x = cvt_pk_bf16(g0 * sigm(acc[tb][0]) * siluf(bflo(gw.x)), g1 * sigm(acc[tb][1]) * siluf(bfhi(gw.x)));
;             w.y = cvt_pk_bf16(g2 * sigm(acc[tb][2]) * siluf(bflo(gw.y)), g3 * sigm(acc[tb][3]) * siluf(bfhi(gw.y)));
;             *(u32x2*)(Z1 + (row0 + tb * 16) * 256 + n4) = w; } }
	v_mfma_f32_16x16x32_bf16 v[102:105], v[110:113], v[2:5], 0
	v_add_f32_e32 v70, 1.0, v70
	v_rcp_f32_e32 v70, v70
	v_mfma_f32_16x16x32_bf16 v[106:109], v[110:113], v[38:41], 0
	v_mul_f32_e64 v70, v70, v86
	v_mul_f32_e64 v71, v71, v87
	v_mul_f32_e32 v70, v70, v71
	v_mul_f32_e32 v71, 0xbfb8aa3b, v72
	v_mul_f32_e32 v72, 0xbfb8aa3b, v73
	v_exp_f32_e32 v71, v71
	v_exp_f32_e32 v72, v72
	v_cvt_pk_bf16_f32 v70, v84, v70
	v_lshlrev_b32_e32 v86, 16, v231
	v_add_f32_e32 v71, 1.0, v71
	v_add_f32_e32 v72, 1.0, v72
	v_rcp_f32_e32 v85, v71
	v_mul_f32_e32 v71, 0xbfb8aa3b, v88
	v_rcp_f32_e32 v73, v72
	v_mul_f32_e32 v72, 0xbfb8aa3b, v90
	v_exp_f32_e32 v71, v71
	v_exp_f32_e32 v72, v72
	v_and_b32_e32 v87, 0xffff0000, v231
	v_mfma_f32_16x16x32_bf16 v[102:105], v[130:133], v[6:9], v[102:105]
	v_add_f32_e32 v71, 1.0, v71
	v_add_f32_e32 v72, 1.0, v72
	v_rcp_f32_e32 v84, v71
	v_rcp_f32_e32 v72, v72
	v_mfma_f32_16x16x32_bf16 v[106:109], v[130:133], v[42:45], v[106:109]
	v_or_b32_e32 v130, 32, v158
	v_pk_mul_f32 v[84:85], v[84:85], v[88:89]
	v_pk_mul_f32 v[72:73], v[72:73], v[90:91]
	v_mul_f32_e32 v71, v84, v85
	v_mul_f32_e32 v72, v72, v73
	v_cvt_pk_bf16_f32 v71, v71, v72
	v_lshl_add_u64 v[72:73], v[82:83], 0, v[114:115]
	flat_store_dwordx2 v[72:73], v[70:71]
	v_lshlrev_b32_e32 v70, 16, v228
	v_lshlrev_b32_e32 v71, 16, v230
	v_fmac_f32_e32 v70, v78, v71
	v_mul_f32_e32 v71, 0x3d372713, v70
	v_mul_f32_e32 v71, v70, v71
	v_fma_f32 v71, v70, v71, v70
	v_mul_f32_e32 v71, 0x3f4c422a, v71
	v_add_f32_e32 v71, v71, v71
	v_mul_f32_e32 v71, 0xbfb8aa3b, v71
	v_exp_f32_e32 v71, v71
	v_and_b32_e32 v72, 0xffff0000, v228
	v_and_b32_e32 v73, 0xffff0000, v230
	v_fmac_f32_e32 v72, v79, v73
	v_add_f32_e32 v71, 1.0, v71
	v_rcp_f32_e32 v71, v71
	v_lshlrev_b32_e32 v84, 16, v229
	v_fmac_f32_e32 v84, v80, v86
	v_and_b32_e32 v85, 0xffff0000, v229
	v_mul_f32_e32 v71, v70, v71
	v_mul_f32_e32 v70, 0x3d372713, v72
	v_mul_f32_e32 v70, v72, v70
	v_fma_f32 v70, v72, v70, v72
	v_mul_f32_e32 v70, 0x3f4c422a, v70
	v_add_f32_e32 v70, v70, v70
	v_mul_f32_e32 v70, 0xbfb8aa3b, v70
	v_exp_f32_e32 v70, v70
	v_fmac_f32_e32 v85, v81, v87
	v_lshlrev_b32_e32 v78, 16, v233
	v_mfma_f32_16x16x32_bf16 v[102:105], v[180:183], v[14:17], v[102:105]
	v_add_f32_e32 v70, 1.0, v70
	v_rcp_f32_e32 v70, v70
	v_and_b32_e32 v80, 0xffff0000, v233
	v_mfma_f32_16x16x32_bf16 v[106:109], v[180:183], v[46:49], v[106:109]
	v_and_b32_e32 v180, 0xffff0000, v127
	v_mul_f32_e32 v73, v72, v70
	v_mul_f32_e32 v70, 0x3d372713, v84
	v_mul_f32_e32 v70, v84, v70
	v_fma_f32 v70, v84, v70, v84
	v_mul_f32_e32 v70, 0x3f4c422a, v70
	v_add_f32_e32 v70, v70, v70
	v_mul_f32_e32 v70, 0xbfb8aa3b, v70
	v_exp_f32_e32 v70, v70
	v_mfma_f32_16x16x32_bf16 v[102:105], v[184:187], v[18:21], v[102:105]
	v_mov_b32_e32 v131, v1
	v_lshl_add_u64 v[132:133], s[40:41], 0, v[130:131]
	v_add_f32_e32 v70, 1.0, v70
	v_rcp_f32_e32 v70, v70
	v_mfma_f32_16x16x32_bf16 v[106:109], v[184:187], v[50:53], v[106:109]
	v_mul_f32_e32 v79, v84, v70
	v_mul_f32_e32 v70, 0x3d372713, v85
	v_mul_f32_e32 v70, v85, v70
	v_fma_f32 v70, v85, v70, v85
	v_mul_f32_e32 v70, 0x3f4c422a, v70
	v_add_f32_e32 v70, v70, v70
	v_mul_f32_e32 v70, 0xbfb8aa3b, v70
	v_exp_f32_e32 v70, v70
	v_mfma_f32_16x16x32_bf16 v[102:105], v[188:191], v[22:25], v[102:105]
	v_add_f32_e32 v70, 1.0, v70
	v_rcp_f32_e32 v70, v70
	v_mfma_f32_16x16x32_bf16 v[106:109], v[188:191], v[54:57], v[106:109]
	v_mul_f32_e32 v81, v85, v70
	v_mul_f32_e32 v70, 0xbfb8aa3b, v74
	v_exp_f32_e32 v70, v70
	v_mfma_f32_16x16x32_bf16 v[102:105], v[214:217], v[26:29], v[102:105]
	v_add_f32_e32 v70, 1.0, v70
	v_rcp_f32_e32 v85, v70
	v_lshlrev_b32_e32 v70, 16, v232
	v_mul_f32_e32 v72, 0xbfb8aa3b, v70
	v_exp_f32_e32 v72, v72
	v_mfma_f32_16x16x32_bf16 v[106:109], v[214:217], v[58:61], v[106:109]
	v_add_f32_e32 v72, 1.0, v72
	v_rcp_f32_e32 v84, v72
	v_and_b32_e32 v72, 0xffff0000, v232
	v_mfma_f32_16x16x32_bf16 v[102:105], v[218:221], v[30:33], v[102:105]
	v_mul_f32_e64 v70, v84, v70
	v_mul_f32_e64 v71, v85, v71
	v_mul_f32_e32 v74, v70, v71
	v_mul_f32_e32 v70, 0xbfb8aa3b, v75
	v_exp_f32_e32 v70, v70
	v_mfma_f32_16x16x32_bf16 v[106:109], v[218:221], v[62:65], v[106:109]
	v_add_f32_e32 v70, 1.0, v70
	v_rcp_f32_e32 v71, v70
	v_mul_f32_e32 v70, 0xbfb8aa3b, v72
	v_exp_f32_e32 v70, v70
	v_mfma_f32_16x16x32_bf16 v[110:113], v[222:225], v[34:37], v[102:105]
	v_add_f32_e32 v70, 1.0, v70
	v_rcp_f32_e32 v70, v70
	v_mfma_f32_16x16x32_bf16 v[102:105], v[222:225], v[66:69], v[106:109]
	s_nop 4
	v_mul_f32_e32 v110, 0xbfb8aa3b, v110
	v_exp_f32_e32 v110, v110
	v_pk_mul_f32 v[70:71], v[70:71], v[72:73]
	v_add_f32_e32 v110, 1.0, v110
	v_mul_f32_e32 v70, v70, v71
	v_mul_f32_e32 v71, 0xbfb8aa3b, v76
	v_exp_f32_e32 v71, v71
	v_cvt_pk_bf16_f32 v70, v74, v70
	v_rcp_f32_e32 v183, v110
	v_mul_f32_e32 v102, 0xbfb8aa3b, v102
	v_add_f32_e32 v71, 1.0, v71
	v_rcp_f32_e32 v73, v71
	v_mul_f32_e32 v71, 0xbfb8aa3b, v78
	v_exp_f32_e32 v71, v71
	v_exp_f32_e32 v102, v102
	v_add_f32_e32 v71, 1.0, v71
	v_rcp_f32_e32 v72, v71
	v_add_f32_e32 v102, 1.0, v102
	v_pk_mul_f32 v[72:73], v[72:73], v[78:79]
	s_nop 0
	v_mul_f32_e32 v71, v72, v73
	v_mul_f32_e32 v72, 0xbfb8aa3b, v77
	v_exp_f32_e32 v72, v72
	s_nop 0
	v_add_f32_e32 v72, 1.0, v72
	v_rcp_f32_e32 v73, v72
	v_mul_f32_e32 v72, 0xbfb8aa3b, v80
	v_exp_f32_e32 v72, v72
	s_nop 0
	v_add_f32_e32 v72, 1.0, v72
	v_rcp_f32_e32 v72, v72
	s_nop 0
	v_pk_mul_f32 v[72:73], v[72:73], v[80:81]
	s_nop 0
	v_mul_f32_e32 v72, v72, v73
	v_cvt_pk_bf16_f32 v71, v71, v72
	v_lshl_add_u64 v[72:73], v[82:83], 0, v[138:139]
	flat_store_dwordx2 v[72:73], v[70:71]
	v_add_co_u32_e32 v70, vcc, s0, v116
	s_nop 1
	v_addc_co_u32_e32 v71, vcc, 0, v117, vcc
	flat_load_dwordx4 v[98:101], v[70:71]
	flat_load_dwordx4 v[94:97], v[70:71] offset:64
	flat_load_dwordx4 v[90:93], v[70:71] offset:128
	flat_load_dwordx4 v[86:89], v[70:71] offset:192
	flat_load_dwordx4 v[82:85], v[70:71] offset:256
	flat_load_dwordx4 v[78:81], v[70:71] offset:320
	flat_load_dwordx4 v[74:77], v[70:71] offset:384
	s_nop 0
	flat_load_dwordx4 v[70:73], v[70:71] offset:448
	s_nop 0
	global_load_dwordx4 v[106:109], v178, s[22:23] offset:64
	s_waitcnt vmcnt(0)
; __device__ __forceinline__ unsigned cvt_pk_bf16(float lo, float hi) { unsigned r; asm volatile("v_cvt_pk_bf16_f32 %0, %1, %2" : "=v"(r) : "v"(lo), "v"(hi)); return r; }
; __device__ __forceinline__ float bflo(unsigned w) { return __uint_as_float(w << 16); }
; __device__ __forceinline__ float bfhi(unsigned w) { return __uint_as_float(w & 0xffff0000u); }
; __device__ __forceinline__ float sigm(float x) { return __builtin_amdgcn_rcpf(1.f + __expf(-x)); }
; __device__ __forceinline__ float siluf(float x) { return x * __builtin_amdgcn_rcpf(1.f + __expf(-x)); }
; __device__ __forceinline__ float gelu_tanh(float x) { const float u = 0.7978845608028654f * (x + 0.044715f * x * x * x); return x * sigm(2.f * u); }
; #define MFMA16(a, b, c) __builtin_amdgcn_mfma_f32_16x16x32_bf16((a), (b), (c), 0, 0, 0)
; __device__ __forceinline__ void glu_task(int t, int l, const float* s5d, const bf16_t* P, const bf16_t* YB, const bf16_t* WGLU, bf16_t* Z1, int fr, int fq) {
;     ...
;     for (int c4 = 0; c4 < 4; ++c4) { f32x4 acc[2]; acc[0] = (f32x4){0.f, 0.f, 0.f, 0.f}; acc[1] = acc[0];
;         const int nrow = c4 < 3 ? (c4 + 1) * 16 : 0;
; #pragma unroll
;         for (int ks = 0; ks < 8; ++ks) wf[(c4 + 1) & 1][ks] = asfrag(ld8(wg0 + (size_t)nrow * 256 + ks * 32));
; #pragma unroll
;         for (int ks = 0; ks < 8; ++ks) { acc[0] = MFMA16(wf[c4 & 1][ks], bfr[0][ks], acc[0]); acc[1] = MFMA16(wf[c4 & 1][ks], bfr[1][ks], acc[1]); }
;         const int n4 = (cb0 + c4) * 16 + fq * 4;
;         const f32x4 dd = *(const f32x4*)(s5d + l * 256 + n4);
; #pragma unroll
;         for (int tb = 0; tb < 2; ++tb) { const u32x2 yw = eyw[tb][c4], uw = euw[tb][c4], gw = egw[tb][c4];
;             const float y0 = bflo(yw.x), y1 = bfhi(yw.x), y2 = bflo(yw.y), y3 = bfhi(yw.y), u0 = bflo(uw.x), u1 = bfhi(uw.x), u2 = bflo(uw.y), u3 = bfhi(uw.y);
;             const float g0 = gelu_tanh(y0 + dd[0] * u0), g1 = gelu_tanh(y1 + dd[1] * u1), g2 = gelu_tanh(y2 + dd[2] * u2), g3 = gelu_tanh(y3 + dd[3] * u3);
;             u32x2 w; w.x = cvt_pk_bf16(g0 * sigm(acc[tb][0]) * siluf(bflo(gw.x)), g1 * sigm(acc[tb][1]) * siluf(bfhi(gw.x)));
;             w.y = cvt_pk_bf16(g2 * sigm(acc[tb][2]) * siluf(bflo(gw.y)), g3 * sigm(acc[tb][3]) * siluf(bfhi(gw.y)));
;             *(u32x2*)(Z1 + (row0 + tb * 16) * 256 + n4) = w; } }
	v_fmac_f32_e32 v128, v107, v126
	v_mul_f32_e32 v126, 0x3d372713, v128
	v_mul_f32_e32 v126, v128, v126
	v_fma_f32 v126, v128, v126, v128
	v_mul_f32_e32 v126, 0x3f4c422a, v126
	v_add_f32_e32 v126, v126, v126
	v_mul_f32_e32 v126, 0xbfb8aa3b, v126
	v_exp_f32_e32 v126, v126
	v_fmac_f32_e32 v172, v108, v173
	v_fmac_f32_e32 v159, v106, v129
	v_fmac_f32_e32 v179, v109, v180
	v_add_f32_e32 v126, 1.0, v126
	v_rcp_f32_e32 v126, v126
	v_mul_f32_e32 v127, 0x3d372713, v159
	v_mul_f32_e32 v127, v159, v127
	v_fma_f32 v127, v159, v127, v159
	v_mul_f32_e32 v129, v128, v126
	v_mul_f32_e32 v126, 0x3d372713, v172
	v_mul_f32_e32 v126, v172, v126
	v_fma_f32 v126, v172, v126, v172
	v_mul_f32_e32 v126, 0x3f4c422a, v126
	v_add_f32_e32 v126, v126, v126
	v_mul_f32_e32 v126, 0xbfb8aa3b, v126
	v_exp_f32_e32 v126, v126
	v_and_b32_e32 v128, 0xffff0000, v124
	v_mul_f32_e32 v127, 0x3f4c422a, v127
	v_add_f32_e32 v127, v127, v127
	v_add_f32_e32 v126, 1.0, v126
	v_rcp_f32_e32 v126, v126
	v_mul_f32_e32 v127, 0xbfb8aa3b, v127
	v_exp_f32_e32 v127, v127
	v_and_b32_e32 v180, 0xffff0000, v125
	v_mul_f32_e32 v173, v172, v126
	v_mul_f32_e32 v126, 0x3d372713, v179
	v_mul_f32_e32 v126, v179, v126
	v_fma_f32 v126, v179, v126, v179
	v_mul_f32_e32 v126, 0x3f4c422a, v126
	v_add_f32_e32 v126, v126, v126
	v_mul_f32_e32 v126, 0xbfb8aa3b, v126
	v_exp_f32_e32 v126, v126
	v_add_f32_e32 v127, 1.0, v127
	v_rcp_f32_e32 v127, v127
	v_lshlrev_b32_e32 v172, 16, v125
	v_add_f32_e32 v126, 1.0, v126
	v_rcp_f32_e32 v126, v126
	v_mul_f32_e32 v127, v159, v127
	v_mul_f32_e32 v181, v179, v126
	v_lshlrev_b32_e32 v126, 16, v124
	v_mul_f32_e32 v110, 0xbfb8aa3b, v126
	v_exp_f32_e32 v110, v110
	s_nop 0
	v_add_f32_e32 v110, 1.0, v110
	v_rcp_f32_e32 v182, v110
	v_mul_f32_e32 v110, 0xbfb8aa3b, v111
	v_exp_f32_e32 v110, v110
	v_pk_mul_f32 v[126:127], v[182:183], v[126:127]
	s_nop 0
	v_mul_f32_e32 v126, v126, v127
	v_add_f32_e32 v110, 1.0, v110
	v_rcp_f32_e32 v111, v110
	v_mul_f32_e32 v110, 0xbfb8aa3b, v128
	v_exp_f32_e32 v110, v110
	s_nop 0
	v_add_f32_e32 v110, 1.0, v110
	v_rcp_f32_e32 v110, v110
	s_nop 0
	v_pk_mul_f32 v[110:111], v[110:111], v[128:129]
	s_nop 0
	v_mul_f32_e32 v110, v110, v111
	v_mul_f32_e32 v111, 0xbfb8aa3b, v112
	v_mul_f32_e32 v112, 0xbfb8aa3b, v113
	v_exp_f32_e32 v111, v111
	v_exp_f32_e32 v112, v112
	v_cvt_pk_bf16_f32 v110, v126, v110
	v_add_f32_e32 v111, 1.0, v111
	v_add_f32_e32 v112, 1.0, v112
	v_rcp_f32_e32 v127, v111
	v_mul_f32_e32 v111, 0xbfb8aa3b, v172
	v_rcp_f32_e32 v113, v112
	v_mul_f32_e32 v112, 0xbfb8aa3b, v180
	v_exp_f32_e32 v111, v111
	v_exp_f32_e32 v112, v112
	v_add_f32_e32 v111, 1.0, v111
	v_add_f32_e32 v112, 1.0, v112
	v_rcp_f32_e32 v126, v111
	v_rcp_f32_e32 v112, v112
	v_pk_mul_f32 v[126:127], v[126:127], v[172:173]
	v_pk_mul_f32 v[112:113], v[112:113], v[180:181]
	v_mul_f32_e32 v111, v126, v127
	v_mul_f32_e32 v112, v112, v113
	v_lshl_add_u64 v[172:173], s[40:41], 0, v[114:115]
	v_cvt_pk_bf16_f32 v111, v111, v112
	v_lshl_add_u64 v[112:113], v[172:173], 0, v[130:131]
	flat_store_dwordx2 v[112:113], v[110:111]
	v_lshlrev_b32_e32 v110, 16, v122
	v_lshlrev_b32_e32 v111, 16, v120
	v_fmac_f32_e32 v110, v106, v111
	v_mul_f32_e32 v106, 0x3d372713, v110
	v_mul_f32_e32 v106, v110, v106
	v_fma_f32 v106, v110, v106, v110
	v_mul_f32_e32 v106, 0x3f4c422a, v106
	v_add_f32_e32 v106, v106, v106
	v_mul_f32_e32 v106, 0xbfb8aa3b, v106
	v_exp_f32_e32 v106, v106
	v_and_b32_e32 v112, 0xffff0000, v122
	v_and_b32_e32 v115, 0xffff0000, v120
	v_fmac_f32_e32 v112, v107, v115
	v_add_f32_e32 v106, 1.0, v106
	v_rcp_f32_e32 v106, v106
	v_lshlrev_b32_e32 v113, 16, v123
	v_lshlrev_b32_e32 v120, 16, v121
	v_fmac_f32_e32 v113, v108, v120
	v_mul_f32_e32 v111, v110, v106
	v_mul_f32_e32 v106, 0x3d372713, v112
	v_mul_f32_e32 v106, v112, v106
	v_fma_f32 v106, v112, v106, v112
	v_mul_f32_e32 v106, 0x3f4c422a, v106
	v_add_f32_e32 v106, v106, v106
	v_mul_f32_e32 v106, 0xbfb8aa3b, v106
	v_exp_f32_e32 v106, v106
	v_and_b32_e32 v114, 0xffff0000, v123
	v_and_b32_e32 v121, 0xffff0000, v121
	v_fmac_f32_e32 v114, v109, v121
	v_add_f32_e32 v106, 1.0, v106
	v_rcp_f32_e32 v106, v106
	v_lshlrev_b32_e32 v110, 16, v118
	v_rcp_f32_e32 v115, v102
	v_mul_f32_e32 v102, 0xbfb8aa3b, v110
	v_mul_f32_e32 v107, v112, v106
	v_mul_f32_e32 v106, 0x3d372713, v113
	v_mul_f32_e32 v106, v113, v106
	v_fma_f32 v106, v113, v106, v113
	v_mul_f32_e32 v106, 0x3f4c422a, v106
	v_add_f32_e32 v106, v106, v106
	v_mul_f32_e32 v106, 0xbfb8aa3b, v106
	v_exp_f32_e32 v106, v106
	v_exp_f32_e32 v102, v102
	s_waitcnt lgkmcnt(0)
; __device__ __forceinline__ unsigned cvt_pk_bf16(float lo, float hi) { unsigned r; asm volatile("v_cvt_pk_bf16_f32 %0, %1, %2" : "=v"(r) : "v"(lo), "v"(hi)); return r; }
; __device__ __forceinline__ float bflo(unsigned w) { return __uint_as_float(w << 16); }
; __device__ __forceinline__ float bfhi(unsigned w) { return __uint_as_float(w & 0xffff0000u); }
; __device__ __forceinline__ float sigm(float x) { return __builtin_amdgcn_rcpf(1.f + __expf(-x)); }
; __device__ __forceinline__ float siluf(float x) { return x * __builtin_amdgcn_rcpf(1.f + __expf(-x)); }
; __device__ __forceinline__ void glu_task(int t, int l, const float* s5d, const bf16_t* P, const bf16_t* YB, const bf16_t* WGLU, bf16_t* Z1, int fr, int fq) {
;     ...
;     for (int c4 = 0; c4 < 4; ++c4) { f32x4 acc[2]; acc[0] = (f32x4){0.f, 0.f, 0.f, 0.f}; acc[1] = acc[0];
;         const int nrow = c4 < 3 ? (c4 + 1) * 16 : 0;
; #pragma unroll
;         for (int ks = 0; ks < 8; ++ks) wf[(c4 + 1) & 1][ks] = asfrag(ld8(wg0 + (size_t)nrow * 256 + ks * 32));
; #pragma unroll
;         for (int ks = 0; ks < 8; ++ks) { acc[0] = MFMA16(wf[c4 & 1][ks], bfr[0][ks], acc[0]); acc[1] = MFMA16(wf[c4 & 1][ks], bfr[1][ks], acc[1]); }
;         const int n4 = (cb0 + c4) * 16 + fq * 4;
;         const f32x4 dd = *(const f32x4*)(s5d + l * 256 + n4);
; #pragma unroll
;         for (int tb = 0; tb < 2; ++tb) { const u32x2 yw = eyw[tb][c4], uw = euw[tb][c4], gw = egw[tb][c4];
;             const float y0 = bflo(yw.x), y1 = bfhi(yw.x), y2 = bflo(yw.y), y3 = bfhi(yw.y), u0 = bflo(uw.x), u1 = bfhi(uw.x), u2 = bflo(uw.y), u3 = bfhi(uw.y);
;             const float g0 = gelu_tanh(y0 + dd[0] * u0), g1 = gelu_tanh(y1 + dd[1] * u1), g2 = gelu_tanh(y2 + dd[2] * u2), g3 = gelu_tanh(y3 + dd[3] * u3);
;             u32x2 w; w.x = cvt_pk_bf16(g0 * sigm(acc[tb][0]) * siluf(bflo(gw.x)), g1 * sigm(acc[tb][1]) * siluf(bfhi(gw.x)));
;             w.y = cvt_pk_bf16(g2 * sigm(acc[tb][2]) * siluf(bflo(gw.y)), g3 * sigm(acc[tb][3]) * siluf(bfhi(gw.y)));
;             *(u32x2*)(Z1 + (row0 + tb * 16) * 256 + n4) = w; } }
; __global__ void __launch_bounds__(512, 2) fwd_kernel(KArgs a) {
;     ...
;             { IDS; for (int t = gw, k_ = 0; t < (wctx ? MH : ML) / 8; t = NGW != 2048 ? t + NGW : (((gw & 7) == 0 && k_ == 0) ? NGW + (gw >> 3) : (wctx ? MH : ML) / 8), ++k_) glu_task(t, l, a.in[21], P, YB, WGLU, Z1, fr, fq); }
	v_mfma_f32_16x16x32_bf16 v[180:183], v[98:101], v[2:5], 0
	v_lshlrev_b32_e32 v112, 16, v119
	v_add_f32_e32 v106, 1.0, v106
	v_rcp_f32_e32 v106, v106
	v_add_f32_e32 v102, 1.0, v102
	v_mfma_f32_16x16x32_bf16 v[98:101], v[98:101], v[38:41], 0
	v_mul_f32_e32 v113, v113, v106
	v_mul_f32_e32 v106, 0x3d372713, v114
	v_mul_f32_e32 v106, v114, v106
	v_fma_f32 v106, v114, v106, v114
	v_mul_f32_e32 v106, 0x3f4c422a, v106
	v_add_f32_e32 v106, v106, v106
	v_mul_f32_e32 v106, 0xbfb8aa3b, v106
	v_exp_f32_e32 v106, v106
	v_mfma_f32_16x16x32_bf16 v[180:183], v[94:97], v[6:9], v[180:183]
	v_add_f32_e32 v106, 1.0, v106
	v_rcp_f32_e32 v106, v106
	v_mfma_f32_16x16x32_bf16 v[94:97], v[94:97], v[42:45], v[98:101]
	v_mul_f32_e32 v109, v114, v106
	v_rcp_f32_e32 v114, v102
	v_mul_f32_e32 v102, 0xbfb8aa3b, v103
	v_exp_f32_e32 v102, v102
	v_and_b32_e32 v106, 0xffff0000, v118
	v_mfma_f32_16x16x32_bf16 v[98:101], v[90:93], v[14:17], v[180:183]
	v_mul_f32_e64 v110, v114, v110
	v_mul_f32_e64 v111, v115, v111
	v_add_f32_e32 v102, 1.0, v102
	v_rcp_f32_e32 v103, v102
	v_mul_f32_e32 v102, 0xbfb8aa3b, v106
	v_exp_f32_e32 v102, v102
	v_mfma_f32_16x16x32_bf16 v[90:93], v[90:93], v[46:49], v[94:97]
	v_mul_f32_e32 v108, v110, v111
	v_add_f32_e32 v102, 1.0, v102
	v_rcp_f32_e32 v102, v102
	v_mfma_f32_16x16x32_bf16 v[94:97], v[86:89], v[18:21], v[98:101]
	v_mul_f32_e64 v102, v102, v106
	v_mul_f32_e64 v103, v103, v107
	v_mul_f32_e32 v102, v102, v103
	v_mul_f32_e32 v103, 0xbfb8aa3b, v104
	v_mul_f32_e32 v104, 0xbfb8aa3b, v105
	v_exp_f32_e32 v103, v103
	v_exp_f32_e32 v104, v104
	v_cvt_pk_bf16_f32 v102, v108, v102
	v_and_b32_e32 v108, 0xffff0000, v119
	v_add_f32_e32 v103, 1.0, v103
	v_add_f32_e32 v104, 1.0, v104
	v_mfma_f32_16x16x32_bf16 v[86:89], v[86:89], v[50:53], v[90:93]
	v_rcp_f32_e32 v107, v103
	v_mul_f32_e32 v103, 0xbfb8aa3b, v112
	v_rcp_f32_e32 v105, v104
	v_mul_f32_e32 v104, 0xbfb8aa3b, v108
	v_exp_f32_e32 v103, v103
	v_exp_f32_e32 v104, v104
	v_mfma_f32_16x16x32_bf16 v[90:93], v[82:85], v[22:25], v[94:97]
	v_add_f32_e32 v103, 1.0, v103
	v_add_f32_e32 v104, 1.0, v104
	v_mfma_f32_16x16x32_bf16 v[82:85], v[82:85], v[54:57], v[86:89]
	v_rcp_f32_e32 v106, v103
	v_rcp_f32_e32 v104, v104
	v_pk_mul_f32 v[106:107], v[106:107], v[112:113]
	v_mfma_f32_16x16x32_bf16 v[86:89], v[78:81], v[26:29], v[90:93]
	v_mul_f32_e64 v104, v104, v108
	v_mul_f32_e64 v105, v105, v109
	v_mul_f32_e32 v103, v106, v107
	v_mul_f32_e32 v104, v104, v105
	v_mfma_f32_16x16x32_bf16 v[78:81], v[78:81], v[58:61], v[82:85]
	v_cvt_pk_bf16_f32 v103, v103, v104
	v_lshl_add_u64 v[104:105], v[132:133], 0, v[138:139]
	flat_store_dwordx2 v[104:105], v[102:103]
	v_mfma_f32_16x16x32_bf16 v[82:85], v[74:77], v[30:33], v[86:89]
	v_add_co_u32_e32 v102, vcc, s18, v116
	v_lshlrev_b32_e32 v90, 16, v171
	v_mfma_f32_16x16x32_bf16 v[74:77], v[74:77], v[62:65], v[78:81]
	v_addc_co_u32_e32 v103, vcc, 0, v117, vcc
	flat_load_dwordx4 v[130:133], v[102:103]
	flat_load_dwordx4 v[126:129], v[102:103] offset:64
	flat_load_dwordx4 v[122:125], v[102:103] offset:128
	flat_load_dwordx4 v[118:121], v[102:103] offset:192
	flat_load_dwordx4 v[114:117], v[102:103] offset:256
	flat_load_dwordx4 v[110:113], v[102:103] offset:320
	flat_load_dwordx4 v[106:109], v[102:103] offset:384
	s_nop 0
	flat_load_dwordx4 v[102:105], v[102:103] offset:448
	v_mfma_f32_16x16x32_bf16 v[78:81], v[70:73], v[34:37], v[82:85]
	v_lshlrev_b32_e32 v86, 16, v170
	v_lshlrev_b32_e32 v87, 16, v168
	v_and_b32_e32 v88, 0xffff0000, v170
	v_mfma_f32_16x16x32_bf16 v[70:73], v[70:73], v[66:69], v[74:77]
	v_and_b32_e32 v89, 0xffff0000, v168
	v_lshlrev_b32_e32 v91, 16, v169
	v_and_b32_e32 v92, 0xffff0000, v171
	global_load_dwordx4 v[74:77], v178, s[22:23] offset:128
	v_and_b32_e32 v93, 0xffff0000, v169
	v_mul_f32_e32 v78, 0xbfb8aa3b, v78
	v_exp_f32_e32 v78, v78
	v_or_b32_e32 v82, 64, v158
	v_mov_b32_e32 v83, v1
	v_lshl_add_u64 v[84:85], s[40:41], 0, v[82:83]
	v_add_f32_e32 v78, 1.0, v78
	v_rcp_f32_e32 v95, v78
	v_mul_f32_e32 v70, 0xbfb8aa3b, v70
	v_exp_f32_e32 v70, v70
	s_waitcnt vmcnt(0) lgkmcnt(0)
	v_mfma_f32_16x16x32_bf16 v[2:5], v[130:133], v[2:5], 0
	v_add_f32_e32 v70, 1.0, v70
	v_subrev_co_u32_e32 v177, vcc, 1, v177
	v_mfma_f32_16x16x32_bf16 v[38:41], v[130:133], v[38:41], 0
	s_and_b64 s[6:7], s[42:43], vcc
	s_and_b64 s[6:7], s[6:7], exec
	s_cselect_b32 s5, s4, s19
	v_mfma_f32_16x16x32_bf16 v[2:5], v[126:129], v[6:9], v[2:5]
	s_and_b64 s[6:7], s[14:15], exec
	s_cselect_b32 s20, s5, s1
	s_cmp_ge_i32 s20, s19
	v_mfma_f32_16x16x32_bf16 v[6:9], v[126:129], v[42:45], v[38:41]
	v_fmac_f32_e32 v86, v74, v87
	v_mul_f32_e32 v87, 0x3d372713, v86
	v_mul_f32_e32 v87, v86, v87
	v_fma_f32 v87, v86, v87, v86
	v_mul_f32_e32 v87, 0x3f4c422a, v87
	v_add_f32_e32 v87, v87, v87
	v_mul_f32_e32 v87, 0xbfb8aa3b, v87
	v_exp_f32_e32 v87, v87
	v_fmac_f32_e32 v88, v75, v89
	v_fmac_f32_e32 v90, v76, v91
	v_fmac_f32_e32 v92, v77, v93
	v_add_f32_e32 v87, 1.0, v87
	v_rcp_f32_e32 v87, v87
	v_mfma_f32_16x16x32_bf16 v[2:5], v[122:125], v[14:17], v[2:5]
	v_mul_f32_e32 v87, v86, v87
	v_mul_f32_e32 v86, 0x3d372713, v88
	v_mul_f32_e32 v86, v88, v86
	v_fma_f32 v86, v88, v86, v88
	v_mul_f32_e32 v86, 0x3f4c422a, v86
	v_add_f32_e32 v86, v86, v86
	v_mul_f32_e32 v86, 0xbfb8aa3b, v86
	v_exp_f32_e32 v86, v86
	v_mfma_f32_16x16x32_bf16 v[6:9], v[122:125], v[46:49], v[6:9]
	v_add_f32_e32 v86, 1.0, v86
	v_rcp_f32_e32 v86, v86
	v_mfma_f32_16x16x32_bf16 v[2:5], v[118:121], v[18:21], v[2:5]
	v_or_b32_e32 v18, 0x60, v158
	v_mov_b32_e32 v19, v1
	v_mul_f32_e32 v89, v88, v86
	v_mul_f32_e32 v86, 0x3d372713, v90
	v_mul_f32_e32 v86, v90, v86
	v_fma_f32 v86, v90, v86, v90
	v_mul_f32_e32 v86, 0x3f4c422a, v86
	v_add_f32_e32 v86, v86, v86
; __device__ __forceinline__ unsigned cvt_pk_bf16(float lo, float hi) { unsigned r; asm volatile("v_cvt_pk_bf16_f32 %0, %1, %2" : "=v"(r) : "v"(lo), "v"(hi)); return r; }
; __device__ __forceinline__ float bflo(unsigned w) { return __uint_as_float(w << 16); }
; __device__ __forceinline__ float bfhi(unsigned w) { return __uint_as_float(w & 0xffff0000u); }
; __device__ __forceinline__ float sigm(float x) { return __builtin_amdgcn_rcpf(1.f + __expf(-x)); }
; __device__ __forceinline__ float siluf(float x) { return x * __builtin_amdgcn_rcpf(1.f + __expf(-x)); }
; __device__ __forceinline__ float gelu_tanh(float x) { const float u = 0.7978845608028654f * (x + 0.044715f * x * x * x); return x * sigm(2.f * u); }
; #define MFMA16(a, b, c) __builtin_amdgcn_mfma_f32_16x16x32_bf16((a), (b), (c), 0, 0, 0)
; __device__ __forceinline__ void glu_task(int t, int l, const float* s5d, const bf16_t* P, const bf16_t* YB, const bf16_t* WGLU, bf16_t* Z1, int fr, int fq) {
;     ...
;     for (int c4 = 0; c4 < 4; ++c4) { f32x4 acc[2]; acc[0] = (f32x4){0.f, 0.f, 0.f, 0.f}; acc[1] = acc[0];
;         const int nrow = c4 < 3 ? (c4 + 1) * 16 : 0;
; #pragma unroll
;         for (int ks = 0; ks < 8; ++ks) wf[(c4 + 1) & 1][ks] = asfrag(ld8(wg0 + (size_t)nrow * 256 + ks * 32));
; #pragma unroll
;         for (int ks = 0; ks < 8; ++ks) { acc[0] = MFMA16(wf[c4 & 1][ks], bfr[0][ks], acc[0]); acc[1] = MFMA16(wf[c4 & 1][ks], bfr[1][ks], acc[1]); }
;         const int n4 = (cb0 + c4) * 16 + fq * 4;
;         const f32x4 dd = *(const f32x4*)(s5d + l * 256 + n4);
; #pragma unroll
;         for (int tb = 0; tb < 2; ++tb) { const u32x2 yw = eyw[tb][c4], uw = euw[tb][c4], gw = egw[tb][c4];
;             const float y0 = bflo(yw.x), y1 = bfhi(yw.x), y2 = bflo(yw.y), y3 = bfhi(yw.y), u0 = bflo(uw.x), u1 = bfhi(uw.x), u2 = bflo(uw.y), u3 = bfhi(uw.y);
;             const float g0 = gelu_tanh(y0 + dd[0] * u0), g1 = gelu_tanh(y1 + dd[1] * u1), g2 = gelu_tanh(y2 + dd[2] * u2), g3 = gelu_tanh(y3 + dd[3] * u3);
;             u32x2 w; w.x = cvt_pk_bf16(g0 * sigm(acc[tb][0]) * siluf(bflo(gw.x)), g1 * sigm(acc[tb][1]) * siluf(bfhi(gw.x)));
;             w.y = cvt_pk_bf16(g2 * sigm(acc[tb][2]) * siluf(bflo(gw.y)), g3 * sigm(acc[tb][3]) * siluf(bfhi(gw.y)));
;             *(u32x2*)(Z1 + (row0 + tb * 16) * 256 + n4) = w; } }
	v_mul_f32_e32 v86, 0xbfb8aa3b, v86
	v_exp_f32_e32 v86, v86
	v_and_b32_e32 v88, 0xffff0000, v166
	v_mfma_f32_16x16x32_bf16 v[6:9], v[118:121], v[50:53], v[6:9]
	v_lshl_add_u64 v[20:21], s[40:41], 0, v[18:19]
	v_add_f32_e32 v86, 1.0, v86
	v_rcp_f32_e32 v86, v86
	v_mfma_f32_16x16x32_bf16 v[2:5], v[114:117], v[22:25], v[2:5]
	v_lshlrev_b32_e32 v22, 16, v156
	v_lshlrev_b32_e32 v23, 16, v148
	v_mul_f32_e32 v91, v90, v86
	v_mul_f32_e32 v86, 0x3d372713, v92
	v_mul_f32_e32 v86, v92, v86
	v_fma_f32 v86, v92, v86, v92
	v_mul_f32_e32 v86, 0x3f4c422a, v86
	v_add_f32_e32 v86, v86, v86
	v_mul_f32_e32 v86, 0xbfb8aa3b, v86
	v_exp_f32_e32 v86, v86
	v_lshlrev_b32_e32 v90, 16, v167
	v_mfma_f32_16x16x32_bf16 v[6:9], v[114:117], v[54:57], v[6:9]
	v_and_b32_e32 v24, 0xffff0000, v156
	v_add_f32_e32 v86, 1.0, v86
	v_rcp_f32_e32 v86, v86
	v_mfma_f32_16x16x32_bf16 v[2:5], v[110:113], v[26:29], v[2:5]
	v_and_b32_e32 v25, 0xffff0000, v148
	v_lshlrev_b32_e32 v26, 16, v157
	v_mul_f32_e32 v93, v92, v86
	v_lshlrev_b32_e32 v86, 16, v166
	v_mul_f32_e32 v78, 0xbfb8aa3b, v86
	v_exp_f32_e32 v78, v78
	v_and_b32_e32 v92, 0xffff0000, v167
	v_mfma_f32_16x16x32_bf16 v[6:9], v[110:113], v[58:61], v[6:9]
	v_lshlrev_b32_e32 v27, 16, v149
	v_add_f32_e32 v78, 1.0, v78
	v_rcp_f32_e32 v94, v78
	v_mul_f32_e32 v78, 0xbfb8aa3b, v79
	v_exp_f32_e32 v78, v78
	v_mfma_f32_16x16x32_bf16 v[2:5], v[106:109], v[30:33], v[2:5]
	v_mul_f32_e64 v86, v94, v86
	v_mul_f32_e64 v87, v95, v87
	v_and_b32_e32 v28, 0xffff0000, v157
	v_add_f32_e32 v78, 1.0, v78
	v_rcp_f32_e32 v79, v78
	v_mul_f32_e32 v78, 0xbfb8aa3b, v88
	v_exp_f32_e32 v78, v78
	v_mul_f32_e32 v86, v86, v87
	v_mfma_f32_16x16x32_bf16 v[6:9], v[106:109], v[62:65], v[6:9]
	v_and_b32_e32 v29, 0xffff0000, v149
	v_add_f32_e32 v78, 1.0, v78
	v_rcp_f32_e32 v78, v78
	v_mfma_f32_16x16x32_bf16 v[14:17], v[102:105], v[34:37], v[2:5]
	v_mul_f32_e64 v78, v78, v88
	v_mul_f32_e64 v79, v79, v89
	v_mul_f32_e32 v78, v78, v79
	v_mul_f32_e32 v79, 0xbfb8aa3b, v80
	v_mul_f32_e32 v80, 0xbfb8aa3b, v81
	v_exp_f32_e32 v79, v79
	v_exp_f32_e32 v80, v80
	v_cvt_pk_bf16_f32 v78, v86, v78
	v_mfma_f32_16x16x32_bf16 v[2:5], v[102:105], v[66:69], v[6:9]
	v_add_f32_e32 v79, 1.0, v79
	v_add_f32_e32 v80, 1.0, v80
	v_rcp_f32_e32 v87, v79
	v_mul_f32_e32 v79, 0xbfb8aa3b, v90
	v_rcp_f32_e32 v81, v80
	v_mul_f32_e32 v80, 0xbfb8aa3b, v92
	v_exp_f32_e32 v79, v79
	v_exp_f32_e32 v80, v80
	v_mul_f32_e32 v14, 0xbfb8aa3b, v14
	v_exp_f32_e32 v14, v14
	v_add_f32_e32 v79, 1.0, v79
	v_add_f32_e32 v80, 1.0, v80
	v_rcp_f32_e32 v86, v79
	v_rcp_f32_e32 v80, v80
	v_add_f32_e32 v14, 1.0, v14
	v_rcp_f32_e32 v31, v14
	v_pk_mul_f32 v[86:87], v[86:87], v[90:91]
	v_pk_mul_f32 v[80:81], v[80:81], v[92:93]
	v_mul_f32_e32 v79, v86, v87
	v_mul_f32_e32 v80, v80, v81
	v_cvt_pk_bf16_f32 v79, v79, v80
	v_lshl_add_u64 v[80:81], v[172:173], 0, v[82:83]
	flat_store_dwordx2 v[80:81], v[78:79]
	v_lshlrev_b32_e32 v78, 16, v164
	v_lshlrev_b32_e32 v79, 16, v162
	v_fmac_f32_e32 v78, v74, v79
	v_mul_f32_e32 v74, 0x3d372713, v78
	v_mul_f32_e32 v74, v78, v74
	v_fma_f32 v74, v78, v74, v78
	v_mul_f32_e32 v74, 0x3f4c422a, v74
	v_add_f32_e32 v74, v74, v74
	v_mul_f32_e32 v74, 0xbfb8aa3b, v74
	v_exp_f32_e32 v74, v74
	v_and_b32_e32 v80, 0xffff0000, v164
	v_and_b32_e32 v83, 0xffff0000, v162
	v_fmac_f32_e32 v80, v75, v83
	v_add_f32_e32 v74, 1.0, v74
	v_rcp_f32_e32 v74, v74
	v_lshlrev_b32_e32 v81, 16, v165
	v_lshlrev_b32_e32 v86, 16, v163
	v_fmac_f32_e32 v81, v76, v86
	v_mul_f32_e32 v79, v78, v74
	v_mul_f32_e32 v74, 0x3d372713, v80
	v_mul_f32_e32 v74, v80, v74
	v_fma_f32 v74, v80, v74, v80
	v_mul_f32_e32 v74, 0x3f4c422a, v74
	v_add_f32_e32 v74, v74, v74
	v_mul_f32_e32 v74, 0xbfb8aa3b, v74
	v_exp_f32_e32 v74, v74
	v_and_b32_e32 v82, 0xffff0000, v165
	v_and_b32_e32 v87, 0xffff0000, v163
	v_fmac_f32_e32 v82, v77, v87
	v_add_f32_e32 v74, 1.0, v74
	v_rcp_f32_e32 v74, v74
	v_lshlrev_b32_e32 v78, 16, v160
	v_rcp_f32_e32 v83, v70
	v_mul_f32_e32 v70, 0xbfb8aa3b, v78
	v_mul_f32_e32 v75, v80, v74
	v_mul_f32_e32 v74, 0x3d372713, v81
	v_mul_f32_e32 v74, v81, v74
	v_fma_f32 v74, v81, v74, v81
	v_mul_f32_e32 v74, 0x3f4c422a, v74
	v_add_f32_e32 v74, v74, v74
	v_mul_f32_e32 v74, 0xbfb8aa3b, v74
	v_exp_f32_e32 v74, v74
	v_exp_f32_e32 v70, v70
	v_lshlrev_b32_e32 v80, 16, v161
	v_mul_f32_e32 v2, 0xbfb8aa3b, v2
	v_add_f32_e32 v74, 1.0, v74
	v_rcp_f32_e32 v74, v74
	v_add_f32_e32 v70, 1.0, v70
	v_exp_f32_e32 v2, v2
	v_mul_f32_e32 v81, v81, v74
	v_mul_f32_e32 v74, 0x3d372713, v82
	v_mul_f32_e32 v74, v82, v74
	v_fma_f32 v74, v82, v74, v82
	v_mul_f32_e32 v74, 0x3f4c422a, v74
	v_add_f32_e32 v74, v74, v74
	v_mul_f32_e32 v74, 0xbfb8aa3b, v74
	v_exp_f32_e32 v74, v74
	v_add_f32_e32 v2, 1.0, v2
	v_add_f32_e32 v74, 1.0, v74
	v_rcp_f32_e32 v74, v74
	s_nop 0
	v_mul_f32_e32 v77, v82, v74
	v_rcp_f32_e32 v82, v70
	v_mul_f32_e32 v70, 0xbfb8aa3b, v71
	v_exp_f32_e32 v70, v70
	v_and_b32_e32 v74, 0xffff0000, v160
	v_pk_mul_f32 v[78:79], v[82:83], v[78:79]
	v_add_f32_e32 v70, 1.0, v70
	v_rcp_f32_e32 v71, v70
	v_mul_f32_e32 v70, 0xbfb8aa3b, v74
	v_exp_f32_e32 v70, v70
	v_mul_f32_e32 v76, v78, v79
	v_add_f32_e32 v70, 1.0, v70
	v_rcp_f32_e32 v70, v70
	s_nop 0
	v_pk_mul_f32 v[70:71], v[70:71], v[74:75]
	s_nop 0
	v_mul_f32_e32 v70, v70, v71
	v_mul_f32_e32 v71, 0xbfb8aa3b, v72
	v_mul_f32_e32 v72, 0xbfb8aa3b, v73
	v_exp_f32_e32 v71, v71
	v_exp_f32_e32 v72, v72
	v_cvt_pk_bf16_f32 v70, v76, v70
	v_and_b32_e32 v76, 0xffff0000, v161
	v_add_f32_e32 v71, 1.0, v71
	v_add_f32_e32 v72, 1.0, v72
	v_rcp_f32_e32 v75, v71
	v_mul_f32_e32 v71, 0xbfb8aa3b, v80
	v_rcp_f32_e32 v73, v72
	v_mul_f32_e32 v72, 0xbfb8aa3b, v76
	v_exp_f32_e32 v71, v71
	v_exp_f32_e32 v72, v72
	v_add_f32_e32 v71, 1.0, v71
	v_add_f32_e32 v72, 1.0, v72
	v_rcp_f32_e32 v74, v71
	v_rcp_f32_e32 v72, v72
	v_pk_mul_f32 v[74:75], v[74:75], v[80:81]
	v_pk_mul_f32 v[72:73], v[72:73], v[76:77]
	v_mul_f32_e32 v71, v74, v75
	v_mul_f32_e32 v72, v72, v73
	v_cvt_pk_bf16_f32 v71, v71, v72
	v_lshl_add_u64 v[72:73], v[84:85], 0, v[138:139]
	flat_store_dwordx2 v[72:73], v[70:71]
	global_load_dwordx4 v[6:9], v178, s[22:23] offset:192
	s_waitcnt vmcnt(0)
; __device__ __forceinline__ unsigned cvt_pk_bf16(float lo, float hi) { unsigned r; asm volatile("v_cvt_pk_bf16_f32 %0, %1, %2" : "=v"(r) : "v"(lo), "v"(hi)); return r; }
; __device__ __forceinline__ float bflo(unsigned w) { return __uint_as_float(w << 16); }
; __device__ __forceinline__ float bfhi(unsigned w) { return __uint_as_float(w & 0xffff0000u); }
; __device__ __forceinline__ float sigm(float x) { return __builtin_amdgcn_rcpf(1.f + __expf(-x)); }
; __device__ __forceinline__ float siluf(float x) { return x * __builtin_amdgcn_rcpf(1.f + __expf(-x)); }
; __device__ __forceinline__ float gelu_tanh(float x) { const float u = 0.7978845608028654f * (x + 0.044715f * x * x * x); return x * sigm(2.f * u); }
; __device__ __forceinline__ unsigned xb_add(unsigned* p, unsigned v) { return __hip_atomic_fetch_add(p, v, __ATOMIC_RELAXED, __HIP_MEMORY_SCOPE_AGENT); }
; __device__ __forceinline__ void xcd_barrier(const XcdBarrier& b) {
;     asm volatile("s_waitcnt vmcnt(0)" ::: "memory");
;     __syncthreads();
;     if (threadIdx.x == 0) {
;         unsigned* bar = b.bar;
;         __builtin_amdgcn_s_waitcnt(0);
;         unsigned nloc = b.st[0], nx = b.st[1];
;         if (nloc == 0u) { xcd_barrier_complete(bar, b.x, nloc, nx); b.st[0] = nloc; b.st[1] = nx; }
;         const unsigned old = xb_add(&bar[XB_XSUB(b.x)], 1u);
; __device__ __forceinline__ void glu_task(int t, int l, const float* s5d, const bf16_t* P, const bf16_t* YB, const bf16_t* WGLU, bf16_t* Z1, int fr, int fq) {
;     ...
;         for (int tb = 0; tb < 2; ++tb) { const u32x2 yw = eyw[tb][c4], uw = euw[tb][c4], gw = egw[tb][c4];
;             const float y0 = bflo(yw.x), y1 = bfhi(yw.x), y2 = bflo(yw.y), y3 = bfhi(yw.y), u0 = bflo(uw.x), u1 = bfhi(uw.x), u2 = bflo(uw.y), u3 = bfhi(uw.y);
;             const float g0 = gelu_tanh(y0 + dd[0] * u0), g1 = gelu_tanh(y1 + dd[1] * u1), g2 = gelu_tanh(y2 + dd[2] * u2), g3 = gelu_tanh(y3 + dd[3] * u3);
;             u32x2 w; w.x = cvt_pk_bf16(g0 * sigm(acc[tb][0]) * siluf(bflo(gw.x)), g1 * sigm(acc[tb][1]) * siluf(bfhi(gw.x)));
;             w.y = cvt_pk_bf16(g2 * sigm(acc[tb][2]) * siluf(bflo(gw.y)), g3 * sigm(acc[tb][3]) * siluf(bfhi(gw.y)));
;             *(u32x2*)(Z1 + (row0 + tb * 16) * 256 + n4) = w; } }
	v_fmac_f32_e32 v22, v6, v23
	v_mul_f32_e32 v23, 0x3d372713, v22
	v_mul_f32_e32 v23, v22, v23
	v_fma_f32 v23, v22, v23, v22
	v_mul_f32_e32 v23, 0x3f4c422a, v23
	v_add_f32_e32 v23, v23, v23
	v_mul_f32_e32 v23, 0xbfb8aa3b, v23
	v_exp_f32_e32 v23, v23
	v_fmac_f32_e32 v24, v7, v25
	v_fmac_f32_e32 v26, v8, v27
	v_fmac_f32_e32 v28, v9, v29
	v_add_f32_e32 v23, 1.0, v23
	v_rcp_f32_e32 v23, v23
	s_nop 0
	v_mul_f32_e32 v23, v22, v23
	v_mul_f32_e32 v22, 0x3d372713, v24
	v_mul_f32_e32 v22, v24, v22
	v_fma_f32 v22, v24, v22, v24
	v_mul_f32_e32 v22, 0x3f4c422a, v22
	v_add_f32_e32 v22, v22, v22
	v_mul_f32_e32 v22, 0xbfb8aa3b, v22
	v_exp_f32_e32 v22, v22
	s_nop 0
	v_add_f32_e32 v22, 1.0, v22
	v_rcp_f32_e32 v22, v22
	s_nop 0
	v_mul_f32_e32 v25, v24, v22
	v_mul_f32_e32 v22, 0x3d372713, v26
	v_mul_f32_e32 v22, v26, v22
	v_fma_f32 v22, v26, v22, v26
	v_mul_f32_e32 v22, 0x3f4c422a, v22
	v_add_f32_e32 v22, v22, v22
	v_mul_f32_e32 v22, 0xbfb8aa3b, v22
	v_exp_f32_e32 v22, v22
	v_and_b32_e32 v24, 0xffff0000, v146
	v_add_f32_e32 v22, 1.0, v22
	v_rcp_f32_e32 v22, v22
	s_nop 0
	v_mul_f32_e32 v27, v26, v22
	v_mul_f32_e32 v22, 0x3d372713, v28
	v_mul_f32_e32 v22, v28, v22
	v_fma_f32 v22, v28, v22, v28
	v_mul_f32_e32 v22, 0x3f4c422a, v22
	v_add_f32_e32 v22, v22, v22
	v_mul_f32_e32 v22, 0xbfb8aa3b, v22
	v_exp_f32_e32 v22, v22
	v_lshlrev_b32_e32 v26, 16, v147
	v_add_f32_e32 v22, 1.0, v22
	v_rcp_f32_e32 v22, v22
	s_nop 0
	v_mul_f32_e32 v29, v28, v22
	v_lshlrev_b32_e32 v22, 16, v146
	v_mul_f32_e32 v14, 0xbfb8aa3b, v22
	v_exp_f32_e32 v14, v14
	v_and_b32_e32 v28, 0xffff0000, v147
	v_add_f32_e32 v14, 1.0, v14
	v_rcp_f32_e32 v30, v14
	v_mul_f32_e32 v14, 0xbfb8aa3b, v15
	v_exp_f32_e32 v14, v14
	v_pk_mul_f32 v[22:23], v[30:31], v[22:23]
	s_nop 0
	v_mul_f32_e32 v22, v22, v23
	v_add_f32_e32 v14, 1.0, v14
	v_rcp_f32_e32 v15, v14
	v_mul_f32_e32 v14, 0xbfb8aa3b, v24
	v_exp_f32_e32 v14, v14
	s_nop 0
	v_add_f32_e32 v14, 1.0, v14
	v_rcp_f32_e32 v14, v14
	s_nop 0
	v_pk_mul_f32 v[14:15], v[14:15], v[24:25]
	s_nop 0
	v_mul_f32_e32 v14, v14, v15
	v_mul_f32_e32 v15, 0xbfb8aa3b, v16
	v_mul_f32_e32 v16, 0xbfb8aa3b, v17
	v_exp_f32_e32 v15, v15
	v_exp_f32_e32 v16, v16
	v_cvt_pk_bf16_f32 v14, v22, v14
	v_add_f32_e32 v15, 1.0, v15
	v_add_f32_e32 v16, 1.0, v16
	v_rcp_f32_e32 v23, v15
	v_mul_f32_e32 v15, 0xbfb8aa3b, v26
	v_rcp_f32_e32 v17, v16
	v_mul_f32_e32 v16, 0xbfb8aa3b, v28
	v_exp_f32_e32 v15, v15
	v_exp_f32_e32 v16, v16
	v_add_f32_e32 v15, 1.0, v15
	v_add_f32_e32 v16, 1.0, v16
	v_rcp_f32_e32 v22, v15
	v_rcp_f32_e32 v16, v16
	v_pk_mul_f32 v[22:23], v[22:23], v[26:27]
	v_pk_mul_f32 v[16:17], v[16:17], v[28:29]
	v_mul_f32_e32 v15, v22, v23
	v_mul_f32_e32 v16, v16, v17
	v_cvt_pk_bf16_f32 v15, v15, v16
	v_lshl_add_u64 v[16:17], v[172:173], 0, v[18:19]
	flat_store_dwordx2 v[16:17], v[14:15]
	v_lshlrev_b32_e32 v14, 16, v144
	v_lshlrev_b32_e32 v15, 16, v142
	v_fmac_f32_e32 v14, v6, v15
	v_mul_f32_e32 v6, 0x3d372713, v14
	v_mul_f32_e32 v6, v14, v6
	v_fma_f32 v6, v14, v6, v14
	v_mul_f32_e32 v6, 0x3f4c422a, v6
	v_add_f32_e32 v6, v6, v6
	v_mul_f32_e32 v6, 0xbfb8aa3b, v6
	v_exp_f32_e32 v6, v6
	v_and_b32_e32 v16, 0xffff0000, v144
	v_and_b32_e32 v19, 0xffff0000, v142
	v_fmac_f32_e32 v16, v7, v19
	v_add_f32_e32 v6, 1.0, v6
	v_rcp_f32_e32 v6, v6
	v_lshlrev_b32_e32 v17, 16, v145
	v_lshlrev_b32_e32 v22, 16, v143
	v_fmac_f32_e32 v17, v8, v22
	v_mul_f32_e32 v15, v14, v6
	v_mul_f32_e32 v6, 0x3d372713, v16
	v_mul_f32_e32 v6, v16, v6
	v_fma_f32 v6, v16, v6, v16
	v_mul_f32_e32 v6, 0x3f4c422a, v6
	v_add_f32_e32 v6, v6, v6
	v_mul_f32_e32 v6, 0xbfb8aa3b, v6
	v_exp_f32_e32 v6, v6
	v_and_b32_e32 v18, 0xffff0000, v145
	v_and_b32_e32 v23, 0xffff0000, v143
	v_fmac_f32_e32 v18, v9, v23
	v_add_f32_e32 v6, 1.0, v6
	v_rcp_f32_e32 v6, v6
	v_lshlrev_b32_e32 v14, 16, v140
	v_rcp_f32_e32 v19, v2
	v_mul_f32_e32 v2, 0xbfb8aa3b, v14
	v_mul_f32_e32 v7, v16, v6
	v_mul_f32_e32 v6, 0x3d372713, v17
	v_mul_f32_e32 v6, v17, v6
	v_fma_f32 v6, v17, v6, v17
	v_mul_f32_e32 v6, 0x3f4c422a, v6
	v_add_f32_e32 v6, v6, v6
	v_mul_f32_e32 v6, 0xbfb8aa3b, v6
	v_exp_f32_e32 v6, v6
	v_exp_f32_e32 v2, v2
	v_lshlrev_b32_e32 v16, 16, v141
	v_add_f32_e32 v6, 1.0, v6
	v_rcp_f32_e32 v6, v6
	v_add_f32_e32 v2, 1.0, v2
	v_mul_f32_e32 v17, v17, v6
	v_mul_f32_e32 v6, 0x3d372713, v18
	v_mul_f32_e32 v6, v18, v6
	v_fma_f32 v6, v18, v6, v18
	v_mul_f32_e32 v6, 0x3f4c422a, v6
	v_add_f32_e32 v6, v6, v6
	v_mul_f32_e32 v6, 0xbfb8aa3b, v6
	v_exp_f32_e32 v6, v6
	s_nop 0
	v_add_f32_e32 v6, 1.0, v6
	v_rcp_f32_e32 v6, v6
	s_nop 0
	v_mul_f32_e32 v9, v18, v6
	v_rcp_f32_e32 v18, v2
	v_mul_f32_e32 v2, 0xbfb8aa3b, v3
	v_exp_f32_e32 v2, v2
	v_and_b32_e32 v6, 0xffff0000, v140
	v_pk_mul_f32 v[14:15], v[18:19], v[14:15]
	v_add_f32_e32 v2, 1.0, v2
	v_rcp_f32_e32 v3, v2
	v_mul_f32_e32 v2, 0xbfb8aa3b, v6
	v_exp_f32_e32 v2, v2
	v_mul_f32_e32 v8, v14, v15
	v_add_f32_e32 v2, 1.0, v2
	v_rcp_f32_e32 v2, v2
	s_nop 0
	v_pk_mul_f32 v[2:3], v[2:3], v[6:7]
	s_nop 0
	v_mul_f32_e32 v2, v2, v3
	v_mul_f32_e32 v3, 0xbfb8aa3b, v4
	v_mul_f32_e32 v4, 0xbfb8aa3b, v5
	v_exp_f32_e32 v3, v3
	v_exp_f32_e32 v4, v4
	v_cvt_pk_bf16_f32 v2, v8, v2
	v_and_b32_e32 v8, 0xffff0000, v141
	v_add_f32_e32 v3, 1.0, v3
	v_add_f32_e32 v4, 1.0, v4
	v_rcp_f32_e32 v7, v3
	v_mul_f32_e32 v3, 0xbfb8aa3b, v16
	v_rcp_f32_e32 v5, v4
	v_mul_f32_e32 v4, 0xbfb8aa3b, v8
	v_exp_f32_e32 v3, v3
	v_exp_f32_e32 v4, v4
	v_add_f32_e32 v3, 1.0, v3
	v_add_f32_e32 v4, 1.0, v4
	v_rcp_f32_e32 v6, v3
	v_rcp_f32_e32 v4, v4
	v_pk_mul_f32 v[6:7], v[6:7], v[16:17]
	v_pk_mul_f32 v[4:5], v[4:5], v[8:9]
	v_mul_f32_e32 v3, v6, v7
	v_mul_f32_e32 v4, v4, v5
	v_cvt_pk_bf16_f32 v3, v3, v4
	v_lshl_add_u64 v[4:5], v[20:21], 0, v[138:139]
	flat_store_dwordx2 v[4:5], v[2:3]
	s_cbranch_scc0 .LBB0_1282
	s_branch .Lmy_shLBB01283
	s_nop 0
	s_nop 0
	s_nop 0
	s_nop 0
	s_nop 0
	s_nop 0
	s_nop 0
	s_nop 0
	s_nop 0
	s_nop 0
	s_nop 0
	s_nop 0
.Lmy_shLBB01283:
.LBB0_1283:
	s_waitcnt vmcnt(0)
	s_waitcnt lgkmcnt(0)
	s_barrier
	s_and_saveexec_b64 s[4:5], s[96:97]
	v_readlane_b32 s91, v254, 1
	v_readlane_b32 s75, v254, 11
	v_readlane_b32 s93, v254, 12
	v_readlane_b32 s18, v254, 14
	v_readlane_b32 s19, v254, 15
	s_cbranch_execz .LBB0_1331
	v_readlane_b32 s1, v253, 44
	s_waitcnt vmcnt(0) expcnt(0) lgkmcnt(0)
	s_nop 0
	v_mov_b32_e32 v0, s1
	ds_read_b32 v3, v0
	v_readlane_b32 s1, v253, 45
	s_waitcnt lgkmcnt(0)
	v_cmp_ne_u32_e32 vcc, 0, v3
	v_mov_b32_e32 v0, s1
	ds_read_b32 v2, v0
	s_cbranch_vccnz .LBB0_1299
	s_mov_b32 s1, 1
	s_branch .LBB0_1287

; __device__ __forceinline__ unsigned xb_add(unsigned* p, unsigned v) { return __hip_atomic_fetch_add(p, v, __ATOMIC_RELAXED, __HIP_MEMORY_SCOPE_AGENT); }
; __device__ __forceinline__ void xcd_barrier(const XcdBarrier& b) {
;     asm volatile("s_waitcnt vmcnt(0)" ::: "memory");
;     __syncthreads();
;     if (threadIdx.x == 0) {
;         unsigned* bar = b.bar;
;         __builtin_amdgcn_s_waitcnt(0);
;         unsigned nloc = b.st[0], nx = b.st[1];
;         if (nloc == 0u) { xcd_barrier_complete(bar, b.x, nloc, nx); b.st[0] = nloc; b.st[1] = nx; }
;         const unsigned old = xb_add(&bar[XB_XSUB(b.x)], 1u);
.LBB0_1517:
	s_or_b64 exec, exec, s[4:5]
	v_readlane_b32 s18, v254, 14
	v_readlane_b32 s19, v254, 15
	s_branch .Lmy_shLBB01518
	s_nop 0
	s_nop 0
.Lmy_shLBB01518:
.LBB0_1518:
	s_waitcnt vmcnt(0)
	s_waitcnt lgkmcnt(0)
	s_barrier
	s_and_saveexec_b64 s[4:5], s[96:97]
	s_xor_b64 s[4:5], exec, s[4:5]
	s_cbranch_execz .LBB0_1567
	v_readlane_b32 s1, v253, 44
	s_waitcnt vmcnt(0) expcnt(0) lgkmcnt(0)
	s_nop 0
	v_mov_b32_e32 v0, s1
	ds_read_b32 v3, v0
	v_readlane_b32 s1, v253, 45
	s_waitcnt lgkmcnt(0)
	v_cmp_ne_u32_e32 vcc, 0, v3
	v_mov_b32_e32 v0, s1
	ds_read_b32 v2, v0
	s_cbranch_vccnz .LBB0_1534
	s_mov_b32 s1, 1
	s_branch .LBB0_1522
